# K-loop: closing barrier signalled 4 MFMAs early, 4-MFMA tail at s_setprio 2
# baseline (speedup 1.0000x reference)
; #define PG8_STAGE_T(bufoff, gbase, voff, AUX) do { _Pragma("unroll") for (int _i = 0; _i < 2; ++_i) \
;         __builtin_amdgcn_global_load_lds((const unsigned*)((const char*)(gbase) + (voff)[_i]), (PG8_LAS unsigned*)(lds + (bufoff) + ldsw + _i * 8192), 16, 0, AUX); } while (0)
; #define PG8_LDA(dst, b, h) do { _Pragma("unroll") for (int m = 0; m < 4; ++m) _Pragma("unroll") for (int k = 0; k < 2; ++k) dst[m][k] = *(const PG8_LAS bf16x8*)(lds + PG8_SA(b, h) + aoff + m * 2048 + k * 1024); } while (0)
; #define PG8_LDB(dst, b, h) do { _Pragma("unroll") for (int n = 0; n < 2; ++n) _Pragma("unroll") for (int k = 0; k < 2; ++k) dst[n][k] = *(const PG8_LAS bf16x8*)(lds + PG8_SB(b, h) + boff + n * 2048 + k * 1024); } while (0)
; #define PG8_MMA(ai, bj, At, Bt) do { __builtin_amdgcn_s_setprio(1); _Pragma("unroll") for (int m = 0; m < 4; ++m) _Pragma("unroll") for (int n = 0; n < 2; ++n) _Pragma("unroll") for (int k = 0; k < 2; ++k) \
;         acc[ai][bj][m][n] = __builtin_amdgcn_mfma_f32_16x16x32_bf16(Bt[n][k], At[m][k], acc[ai][bj][m][n], 0, 0, 0); __builtin_amdgcn_s_setprio(0); } while (0)
; #define PG8_WAIT_V(n) asm volatile("s_waitcnt vmcnt(" #n ")" ::: "memory")
;     ...
;             const bool last = (t == nt - 2);
;             const char* a1 = cA + (ptrdiff_t)(t + 1) * ck;
;             const char* a2 = last ? nA : cA + (ptrdiff_t)(t + 2) * ck; const char* b2 = last ? nB : cB + (ptrdiff_t)(t + 2) * ck;
;             const ptrdiff_t k3 = last ? nk : ck;
;             const char* a3 = a2 + k3; const char* b3 = b2 + k3;
;             if (last && has_next) S.a_ready(nxt);
;             if constexpr (SP2) {
;             int pei = 0; if constexpr (PEEL) { pei = __builtin_amdgcn_readfirstlane((t == 0 && ui > 0) ? 1 : 0); asm volatile("" : "+s"(pei)); }
;             const bool pe = pei != 0;
;             PG8_LDB(B0, 0, 0); PG8_LDB(B1, 0, 1); PG8_SCHED; PG8_LDA(At, 0, 0); if (!pe) { PG8_STAGE_T(PG8_SA(1, 1), a1 + hstep, voffA, AUX_A); }
;             if (!pe) { PG8_WAIT_V(8); } PG8_WAIT_L(0); PG8_BAR; PG8_MMA(0, 0, At, B0); PG8_MMA(0, 1, At, B1); PG8_BAR; PG8_SCHED;
;             PG8_LDA(At, 0, 1); PG8_STAGE_T(PG8_SB(0, 0), b2, voffB, AUX_B); PG8_STAGE_T(PG8_SB(0, 1), b2 + hstep, voffB, AUX_B); PG8_STAGE_T(PG8_SA(0, 0), a2, voffA, AUX_A);
;             if (!pe) { PG8_WAIT_V(8); } PG8_WAIT_L(0); PG8_BAR; PG8_MMA(1, 0, At, B0); PG8_MMA(1, 1, At, B1); PG8_BAR; PG8_SCHED;
.LBB0_244:
	ds_read_b128 v[146:149], v166
	ds_read_b128 v[162:165], v166 offset:1024
	ds_read_b128 v[170:173], v166 offset:2048
	ds_read_b128 v[174:177], v166 offset:3072
	ds_read_b128 v[178:181], v167
	ds_read_b128 v[182:185], v167 offset:1024
	ds_read_b128 v[186:189], v167 offset:2048
	ds_read_b128 v[190:193], v167 offset:3072
	s_add_u32 s44, s40, 0xfffc0080
	s_addc_u32 s45, s41, -1
	s_cmp_eq_u32 s70, 12
	s_cselect_b32 s49, s21, s45
	s_cselect_b32 s48, s37, s44
	s_cselect_b32 s45, s23, s69
	s_cselect_b32 s44, s67, s68
	v_lshl_add_u64 v[150:151], s[40:41], 0, v[136:137]
	s_add_i32 m0, s51, 0xc000
	ds_read_b128 v[196:199], v168
	ds_read_b128 v[200:203], v168 offset:1024
	ds_read_b128 v[204:207], v168 offset:2048
	ds_read_b128 v[208:211], v168 offset:3072
	ds_read_b128 v[212:215], v168 offset:4096
	ds_read_b128 v[216:219], v168 offset:5120
	ds_read_b128 v[220:223], v168 offset:6144
	ds_read_b128 v[224:227], v168 offset:7168
	global_load_lds_dwordx4 v[150:151], off
	v_lshl_add_u64 v[150:151], s[40:41], 0, v[138:139]
	s_add_i32 m0, s51, 0xe000
	s_nop 0
	global_load_lds_dwordx4 v[150:151], off
	s_waitcnt vmcnt(8)
	s_waitcnt lgkmcnt(0)
	s_barrier
	s_waitcnt lgkmcnt(0)
	v_mfma_f32_16x16x32_bf16 v[124:127], v[146:149], v[196:199], v[124:127]
	v_mfma_f32_16x16x32_bf16 v[120:123], v[170:173], v[196:199], v[120:123]
	v_mfma_f32_16x16x32_bf16 v[108:111], v[146:149], v[204:207], v[108:111]
	v_mfma_f32_16x16x32_bf16 v[104:107], v[170:173], v[204:207], v[104:107]
	v_mfma_f32_16x16x32_bf16 v[92:95], v[146:149], v[212:215], v[92:95]
	v_mfma_f32_16x16x32_bf16 v[88:91], v[170:173], v[212:215], v[88:91]
	v_mfma_f32_16x16x32_bf16 v[76:79], v[146:149], v[220:223], v[76:79]
	v_mfma_f32_16x16x32_bf16 v[72:75], v[170:173], v[220:223], v[72:75]
	v_mfma_f32_16x16x32_bf16 v[124:127], v[162:165], v[200:203], v[124:127]
	v_mfma_f32_16x16x32_bf16 v[120:123], v[174:177], v[200:203], v[120:123]
	v_mfma_f32_16x16x32_bf16 v[108:111], v[162:165], v[208:211], v[108:111]
	v_mfma_f32_16x16x32_bf16 v[104:107], v[174:177], v[208:211], v[104:107]
	v_mfma_f32_16x16x32_bf16 v[92:95], v[162:165], v[216:219], v[92:95]
	v_mfma_f32_16x16x32_bf16 v[88:91], v[174:177], v[216:219], v[88:91]
	v_mfma_f32_16x16x32_bf16 v[76:79], v[162:165], v[224:227], v[76:79]
	v_mfma_f32_16x16x32_bf16 v[72:75], v[174:177], v[224:227], v[72:75]
	v_mfma_f32_16x16x32_bf16 v[116:119], v[178:181], v[196:199], v[116:119]
	v_mfma_f32_16x16x32_bf16 v[112:115], v[186:189], v[196:199], v[112:115]
	v_mfma_f32_16x16x32_bf16 v[100:103], v[178:181], v[204:207], v[100:103]
	v_mfma_f32_16x16x32_bf16 v[96:99], v[186:189], v[204:207], v[96:99]
	v_mfma_f32_16x16x32_bf16 v[84:87], v[178:181], v[212:215], v[84:87]
	v_mfma_f32_16x16x32_bf16 v[80:83], v[186:189], v[212:215], v[80:83]
	v_mfma_f32_16x16x32_bf16 v[68:71], v[178:181], v[220:223], v[68:71]
	v_mfma_f32_16x16x32_bf16 v[64:67], v[186:189], v[220:223], v[64:67]
	v_mfma_f32_16x16x32_bf16 v[116:119], v[182:185], v[200:203], v[116:119]
	v_mfma_f32_16x16x32_bf16 v[112:115], v[190:193], v[200:203], v[112:115]
	v_mfma_f32_16x16x32_bf16 v[100:103], v[182:185], v[208:211], v[100:103]
	v_mfma_f32_16x16x32_bf16 v[96:99], v[190:193], v[208:211], v[96:99]
	s_setprio 2
	s_barrier
	v_mfma_f32_16x16x32_bf16 v[84:87], v[182:185], v[216:219], v[84:87]
	v_mfma_f32_16x16x32_bf16 v[80:83], v[190:193], v[216:219], v[80:83]
	v_mfma_f32_16x16x32_bf16 v[68:71], v[182:185], v[224:227], v[68:71]
	v_mfma_f32_16x16x32_bf16 v[64:67], v[190:193], v[224:227], v[64:67]
	s_setprio 0
	s_add_i32 s71, s58, s9
	v_lshl_add_u64 v[150:151], s[44:45], 0, v[132:133]
	s_mov_b32 m0, s71
	ds_read_b128 v[196:199], v168 offset:16384
	ds_read_b128 v[200:203], v168 offset:17408
	ds_read_b128 v[204:207], v168 offset:18432
	ds_read_b128 v[208:211], v168 offset:19456
	ds_read_b128 v[212:215], v168 offset:20480
	ds_read_b128 v[216:219], v168 offset:21504
	ds_read_b128 v[220:223], v168 offset:22528
	ds_read_b128 v[224:227], v168 offset:23552
	global_load_lds_dwordx4 v[150:151], off
	s_add_i32 m0, s71, 0x2000
	s_add_u32 s76, s44, 0x40000
	v_lshl_add_u64 v[154:155], s[44:45], 0, v[128:129]
	s_addc_u32 s77, s45, 0
	s_add_i32 s71, s59, s9
	global_load_lds_dwordx4 v[154:155], off
	v_lshl_add_u64 v[158:159], s[76:77], 0, v[132:133]
	s_mov_b32 m0, s71
	v_lshl_add_u64 v[228:229], s[48:49], 0, v[130:131]
	global_load_lds_dwordx4 v[158:159], off
	v_lshl_add_u64 v[158:159], s[76:77], 0, v[128:129]
	s_add_i32 m0, s71, 0x2000
	s_nop 0
	global_load_lds_dwordx4 v[158:159], off
	v_lshl_add_u64 v[158:159], s[48:49], 0, v[134:135]
	s_mov_b32 m0, s51
	s_nop 0
	global_load_lds_dwordx4 v[158:159], off
	s_mov_b32 m0, s52
	s_nop 0
	global_load_lds_dwordx4 v[228:229], off
	s_waitcnt vmcnt(8)
	s_waitcnt lgkmcnt(0)
	s_barrier
; #define PG8_STAGE_T(bufoff, gbase, voff, AUX) do { _Pragma("unroll") for (int _i = 0; _i < 2; ++_i) \
;         __builtin_amdgcn_global_load_lds((const unsigned*)((const char*)(gbase) + (voff)[_i]), (PG8_LAS unsigned*)(lds + (bufoff) + ldsw + _i * 8192), 16, 0, AUX); } while (0)
; #define PG8_LDA(dst, b, h) do { _Pragma("unroll") for (int m = 0; m < 4; ++m) _Pragma("unroll") for (int k = 0; k < 2; ++k) dst[m][k] = *(const PG8_LAS bf16x8*)(lds + PG8_SA(b, h) + aoff + m * 2048 + k * 1024); } while (0)
; #define PG8_LDB(dst, b, h) do { _Pragma("unroll") for (int n = 0; n < 2; ++n) _Pragma("unroll") for (int k = 0; k < 2; ++k) dst[n][k] = *(const PG8_LAS bf16x8*)(lds + PG8_SB(b, h) + boff + n * 2048 + k * 1024); } while (0)
; #define PG8_MMA(ai, bj, At, Bt) do { __builtin_amdgcn_s_setprio(1); _Pragma("unroll") for (int m = 0; m < 4; ++m) _Pragma("unroll") for (int n = 0; n < 2; ++n) _Pragma("unroll") for (int k = 0; k < 2; ++k) \
;         acc[ai][bj][m][n] = __builtin_amdgcn_mfma_f32_16x16x32_bf16(Bt[n][k], At[m][k], acc[ai][bj][m][n], 0, 0, 0); __builtin_amdgcn_s_setprio(0); } while (0)
; #define PG8_WAIT_V(n) asm volatile("s_waitcnt vmcnt(" #n ")" ::: "memory")
; #define PG8_WAIT_L(n) asm volatile("s_waitcnt lgkmcnt(" #n ")" ::: "memory")
; #define PG8_BAR __builtin_amdgcn_s_barrier()
; #define PG8_SCHED __builtin_amdgcn_sched_barrier(0)
;     ...
;             if (!pe) { PG8_WAIT_V(8); } PG8_WAIT_L(0); PG8_BAR; PG8_MMA(1, 0, At, B0); PG8_MMA(1, 1, At, B1); PG8_BAR; PG8_SCHED;
;             PG8_LDB(B0, 1, 0); PG8_LDB(B1, 1, 1); PG8_SCHED; PG8_LDA(At, 1, 0); PG8_STAGE_T(PG8_SA(0, 1), a2 + hstep, voffA, AUX_A);
;             if (!pe) { PG8_WAIT_V(8); } PG8_WAIT_L(0); PG8_BAR; PG8_MMA(0, 0, At, B0); PG8_MMA(0, 1, At, B1); PG8_BAR; PG8_SCHED;
	s_waitcnt lgkmcnt(0)
	v_mfma_f32_16x16x32_bf16 v[60:63], v[146:149], v[196:199], v[60:63]
	v_mfma_f32_16x16x32_bf16 v[56:59], v[170:173], v[196:199], v[56:59]
	v_mfma_f32_16x16x32_bf16 v[44:47], v[146:149], v[204:207], v[44:47]
	v_mfma_f32_16x16x32_bf16 v[40:43], v[170:173], v[204:207], v[40:43]
	v_mfma_f32_16x16x32_bf16 v[28:31], v[146:149], v[212:215], v[28:31]
	v_mfma_f32_16x16x32_bf16 v[24:27], v[170:173], v[212:215], v[24:27]
	v_mfma_f32_16x16x32_bf16 v[12:15], v[146:149], v[220:223], v[12:15]
	v_mfma_f32_16x16x32_bf16 v[8:11], v[170:173], v[220:223], v[8:11]
	v_mfma_f32_16x16x32_bf16 v[60:63], v[162:165], v[200:203], v[60:63]
	v_mfma_f32_16x16x32_bf16 v[56:59], v[174:177], v[200:203], v[56:59]
	v_mfma_f32_16x16x32_bf16 v[44:47], v[162:165], v[208:211], v[44:47]
	v_mfma_f32_16x16x32_bf16 v[40:43], v[174:177], v[208:211], v[40:43]
	v_mfma_f32_16x16x32_bf16 v[28:31], v[162:165], v[216:219], v[28:31]
	v_mfma_f32_16x16x32_bf16 v[24:27], v[174:177], v[216:219], v[24:27]
	v_mfma_f32_16x16x32_bf16 v[12:15], v[162:165], v[224:227], v[12:15]
	v_mfma_f32_16x16x32_bf16 v[8:11], v[174:177], v[224:227], v[8:11]
	v_mfma_f32_16x16x32_bf16 v[52:55], v[178:181], v[196:199], v[52:55]
	v_mfma_f32_16x16x32_bf16 v[48:51], v[186:189], v[196:199], v[48:51]
	v_mfma_f32_16x16x32_bf16 v[36:39], v[178:181], v[204:207], v[36:39]
	v_mfma_f32_16x16x32_bf16 v[32:35], v[186:189], v[204:207], v[32:35]
	v_mfma_f32_16x16x32_bf16 v[20:23], v[178:181], v[212:215], v[20:23]
	v_mfma_f32_16x16x32_bf16 v[16:19], v[186:189], v[212:215], v[16:19]
	v_mfma_f32_16x16x32_bf16 v[4:7], v[178:181], v[220:223], v[4:7]
	v_mfma_f32_16x16x32_bf16 v[0:3], v[186:189], v[220:223], v[0:3]
	v_mfma_f32_16x16x32_bf16 v[52:55], v[182:185], v[200:203], v[52:55]
	v_mfma_f32_16x16x32_bf16 v[48:51], v[190:193], v[200:203], v[48:51]
	v_mfma_f32_16x16x32_bf16 v[36:39], v[182:185], v[208:211], v[36:39]
	v_mfma_f32_16x16x32_bf16 v[32:35], v[190:193], v[208:211], v[32:35]
	s_setprio 2
	s_barrier
	v_mfma_f32_16x16x32_bf16 v[20:23], v[182:185], v[216:219], v[20:23]
	v_mfma_f32_16x16x32_bf16 v[16:19], v[190:193], v[216:219], v[16:19]
	v_mfma_f32_16x16x32_bf16 v[4:7], v[182:185], v[224:227], v[4:7]
	v_mfma_f32_16x16x32_bf16 v[0:3], v[190:193], v[224:227], v[0:3]
	s_setprio 0
	s_add_i32 s71, 0, 0x18000
	v_add_u32_e32 v144, s71, v153
	s_add_i32 s76, 0, 0x1c000
	ds_read_b128 v[146:149], v144
	ds_read_b128 v[162:165], v144 offset:1024
	ds_read_b128 v[170:173], v144 offset:2048
	ds_read_b128 v[174:177], v144 offset:3072
	v_add_u32_e32 v144, s76, v153
	ds_read_b128 v[178:181], v144
	ds_read_b128 v[182:185], v144 offset:1024
	ds_read_b128 v[186:189], v144 offset:2048
	ds_read_b128 v[190:193], v144 offset:3072
	s_add_u32 s48, s48, 0x40000
	s_addc_u32 s49, s49, 0
	s_mov_b32 m0, s53
	v_lshl_add_u64 v[230:231], s[48:49], 0, v[134:135]
	ds_read_b128 v[196:199], v168 offset:32768
	ds_read_b128 v[200:203], v168 offset:33792
	ds_read_b128 v[204:207], v168 offset:34816
	ds_read_b128 v[208:211], v168 offset:35840
	ds_read_b128 v[212:215], v168 offset:36864
	ds_read_b128 v[216:219], v168 offset:37888
	ds_read_b128 v[220:223], v168 offset:38912
	ds_read_b128 v[224:227], v168 offset:39936
	global_load_lds_dwordx4 v[230:231], off
	v_lshl_add_u64 v[230:231], s[48:49], 0, v[130:131]
	s_mov_b32 m0, s54
	s_nop 0
	global_load_lds_dwordx4 v[230:231], off
	s_waitcnt vmcnt(8)
	s_waitcnt lgkmcnt(0)
	s_barrier
	s_waitcnt lgkmcnt(0)
	v_mfma_f32_16x16x32_bf16 v[124:127], v[146:149], v[196:199], v[124:127]
	v_mfma_f32_16x16x32_bf16 v[120:123], v[170:173], v[196:199], v[120:123]
	v_mfma_f32_16x16x32_bf16 v[108:111], v[146:149], v[204:207], v[108:111]
	v_mfma_f32_16x16x32_bf16 v[104:107], v[170:173], v[204:207], v[104:107]
	v_mfma_f32_16x16x32_bf16 v[92:95], v[146:149], v[212:215], v[92:95]
	v_mfma_f32_16x16x32_bf16 v[88:91], v[170:173], v[212:215], v[88:91]
	v_mfma_f32_16x16x32_bf16 v[76:79], v[146:149], v[220:223], v[76:79]
	v_mfma_f32_16x16x32_bf16 v[72:75], v[170:173], v[220:223], v[72:75]
	v_mfma_f32_16x16x32_bf16 v[124:127], v[162:165], v[200:203], v[124:127]
	v_mfma_f32_16x16x32_bf16 v[120:123], v[174:177], v[200:203], v[120:123]
	v_mfma_f32_16x16x32_bf16 v[108:111], v[162:165], v[208:211], v[108:111]
	v_mfma_f32_16x16x32_bf16 v[104:107], v[174:177], v[208:211], v[104:107]
	v_mfma_f32_16x16x32_bf16 v[92:95], v[162:165], v[216:219], v[92:95]
	v_mfma_f32_16x16x32_bf16 v[88:91], v[174:177], v[216:219], v[88:91]
	v_mfma_f32_16x16x32_bf16 v[76:79], v[162:165], v[224:227], v[76:79]
	v_mfma_f32_16x16x32_bf16 v[72:75], v[174:177], v[224:227], v[72:75]
	v_mfma_f32_16x16x32_bf16 v[116:119], v[178:181], v[196:199], v[116:119]
	v_mfma_f32_16x16x32_bf16 v[112:115], v[186:189], v[196:199], v[112:115]
	v_mfma_f32_16x16x32_bf16 v[100:103], v[178:181], v[204:207], v[100:103]
	v_mfma_f32_16x16x32_bf16 v[96:99], v[186:189], v[204:207], v[96:99]
	v_mfma_f32_16x16x32_bf16 v[84:87], v[178:181], v[212:215], v[84:87]
	v_mfma_f32_16x16x32_bf16 v[80:83], v[186:189], v[212:215], v[80:83]
	v_mfma_f32_16x16x32_bf16 v[68:71], v[178:181], v[220:223], v[68:71]
	v_mfma_f32_16x16x32_bf16 v[64:67], v[186:189], v[220:223], v[64:67]
	v_mfma_f32_16x16x32_bf16 v[116:119], v[182:185], v[200:203], v[116:119]
	v_mfma_f32_16x16x32_bf16 v[112:115], v[190:193], v[200:203], v[112:115]
	v_mfma_f32_16x16x32_bf16 v[100:103], v[182:185], v[208:211], v[100:103]
	v_mfma_f32_16x16x32_bf16 v[96:99], v[190:193], v[208:211], v[96:99]
	s_setprio 2
	s_barrier
; #define PG8_STAGE_T(bufoff, gbase, voff, AUX) do { _Pragma("unroll") for (int _i = 0; _i < 2; ++_i) \
;         __builtin_amdgcn_global_load_lds((const unsigned*)((const char*)(gbase) + (voff)[_i]), (PG8_LAS unsigned*)(lds + (bufoff) + ldsw + _i * 8192), 16, 0, AUX); } while (0)
; #define PG8_LDA(dst, b, h) do { _Pragma("unroll") for (int m = 0; m < 4; ++m) _Pragma("unroll") for (int k = 0; k < 2; ++k) dst[m][k] = *(const PG8_LAS bf16x8*)(lds + PG8_SA(b, h) + aoff + m * 2048 + k * 1024); } while (0)
; #define PG8_MMA(ai, bj, At, Bt) do { __builtin_amdgcn_s_setprio(1); _Pragma("unroll") for (int m = 0; m < 4; ++m) _Pragma("unroll") for (int n = 0; n < 2; ++n) _Pragma("unroll") for (int k = 0; k < 2; ++k) \
;         acc[ai][bj][m][n] = __builtin_amdgcn_mfma_f32_16x16x32_bf16(Bt[n][k], At[m][k], acc[ai][bj][m][n], 0, 0, 0); __builtin_amdgcn_s_setprio(0); } while (0)
; #define PG8_WAIT_V(n) asm volatile("s_waitcnt vmcnt(" #n ")" ::: "memory")
; #define PG8_WAIT_L(n) asm volatile("s_waitcnt lgkmcnt(" #n ")" ::: "memory")
; #define PG8_BAR __builtin_amdgcn_s_barrier()
; #define PG8_SCHED __builtin_amdgcn_sched_barrier(0)
;     ...
;             if (!pe) { PG8_WAIT_V(8); } PG8_WAIT_L(0); PG8_BAR; PG8_MMA(0, 0, At, B0); PG8_MMA(0, 1, At, B1); PG8_BAR; PG8_SCHED;
;             PG8_LDA(At, 1, 1); PG8_STAGE_T(PG8_SB(1, 0), b3, voffB, AUX_B); PG8_STAGE_T(PG8_SB(1, 1), b3 + hstep, voffB, AUX_B); PG8_STAGE_T(PG8_SA(1, 0), a3, voffA, AUX_A);
;             PG8_WAIT_V(8); PG8_WAIT_L(0); PG8_BAR; PG8_MMA(1, 0, At, B0); PG8_MMA(1, 1, At, B1); PG8_BAR; PG8_SCHED;
;     ...
;         if constexpr (ALIGN_EPI) { if (wr == 0) PG8_BAR; }
	v_mfma_f32_16x16x32_bf16 v[84:87], v[182:185], v[216:219], v[84:87]
	v_mfma_f32_16x16x32_bf16 v[80:83], v[190:193], v[216:219], v[80:83]
	v_mfma_f32_16x16x32_bf16 v[68:71], v[182:185], v[224:227], v[68:71]
	v_mfma_f32_16x16x32_bf16 v[64:67], v[190:193], v[224:227], v[64:67]
	s_setprio 0
	s_add_i32 s48, s71, s9
	v_lshl_add_u64 v[150:151], v[150:151], 0, s[14:15]
	s_mov_b32 m0, s48
	ds_read_b128 v[196:199], v168 offset:49152
	ds_read_b128 v[200:203], v168 offset:50176
	ds_read_b128 v[204:207], v168 offset:51200
	ds_read_b128 v[208:211], v168 offset:52224
	ds_read_b128 v[212:215], v168 offset:53248
	ds_read_b128 v[216:219], v168 offset:54272
	ds_read_b128 v[220:223], v168 offset:55296
	ds_read_b128 v[224:227], v168 offset:56320
	global_load_lds_dwordx4 v[150:151], off
	s_add_i32 m0, s48, 0x2000
	s_add_u32 s44, s44, 0x40080
	v_lshl_add_u64 v[150:151], v[154:155], 0, s[14:15]
	s_addc_u32 s45, s45, 0
	s_add_i32 s48, s76, s9
	global_load_lds_dwordx4 v[150:151], off
	v_lshl_add_u64 v[150:151], s[44:45], 0, v[132:133]
	s_mov_b32 m0, s48
	s_nop 0
	global_load_lds_dwordx4 v[150:151], off
	v_lshl_add_u64 v[150:151], s[44:45], 0, v[128:129]
	s_add_i32 m0, s48, 0x2000
	s_nop 0
	global_load_lds_dwordx4 v[150:151], off
	v_lshl_add_u64 v[150:151], v[158:159], 0, s[14:15]
	s_mov_b32 m0, s56
	s_nop 0
	global_load_lds_dwordx4 v[150:151], off
	v_lshl_add_u64 v[150:151], v[228:229], 0, s[14:15]
	s_mov_b32 m0, s57
	s_nop 0
	global_load_lds_dwordx4 v[150:151], off
	s_waitcnt vmcnt(8)
	s_waitcnt lgkmcnt(0)
	s_barrier
	s_waitcnt lgkmcnt(0)
	v_mfma_f32_16x16x32_bf16 v[60:63], v[146:149], v[196:199], v[60:63]
	v_mfma_f32_16x16x32_bf16 v[56:59], v[170:173], v[196:199], v[56:59]
	v_mfma_f32_16x16x32_bf16 v[44:47], v[146:149], v[204:207], v[44:47]
	v_mfma_f32_16x16x32_bf16 v[40:43], v[170:173], v[204:207], v[40:43]
	v_mfma_f32_16x16x32_bf16 v[28:31], v[146:149], v[212:215], v[28:31]
	v_mfma_f32_16x16x32_bf16 v[24:27], v[170:173], v[212:215], v[24:27]
	v_mfma_f32_16x16x32_bf16 v[12:15], v[146:149], v[220:223], v[12:15]
	v_mfma_f32_16x16x32_bf16 v[8:11], v[170:173], v[220:223], v[8:11]
	v_mfma_f32_16x16x32_bf16 v[60:63], v[162:165], v[200:203], v[60:63]
	v_mfma_f32_16x16x32_bf16 v[56:59], v[174:177], v[200:203], v[56:59]
	v_mfma_f32_16x16x32_bf16 v[44:47], v[162:165], v[208:211], v[44:47]
	v_mfma_f32_16x16x32_bf16 v[40:43], v[174:177], v[208:211], v[40:43]
	v_mfma_f32_16x16x32_bf16 v[28:31], v[162:165], v[216:219], v[28:31]
	v_mfma_f32_16x16x32_bf16 v[24:27], v[174:177], v[216:219], v[24:27]
	v_mfma_f32_16x16x32_bf16 v[12:15], v[162:165], v[224:227], v[12:15]
	v_mfma_f32_16x16x32_bf16 v[8:11], v[174:177], v[224:227], v[8:11]
	v_mfma_f32_16x16x32_bf16 v[52:55], v[178:181], v[196:199], v[52:55]
	v_mfma_f32_16x16x32_bf16 v[48:51], v[186:189], v[196:199], v[48:51]
	v_mfma_f32_16x16x32_bf16 v[36:39], v[178:181], v[204:207], v[36:39]
	v_mfma_f32_16x16x32_bf16 v[32:35], v[186:189], v[204:207], v[32:35]
	v_mfma_f32_16x16x32_bf16 v[20:23], v[178:181], v[212:215], v[20:23]
	v_mfma_f32_16x16x32_bf16 v[16:19], v[186:189], v[212:215], v[16:19]
	v_mfma_f32_16x16x32_bf16 v[4:7], v[178:181], v[220:223], v[4:7]
	v_mfma_f32_16x16x32_bf16 v[0:3], v[186:189], v[220:223], v[0:3]
	v_mfma_f32_16x16x32_bf16 v[52:55], v[182:185], v[200:203], v[52:55]
	v_mfma_f32_16x16x32_bf16 v[48:51], v[190:193], v[200:203], v[48:51]
	v_mfma_f32_16x16x32_bf16 v[36:39], v[182:185], v[208:211], v[36:39]
	v_mfma_f32_16x16x32_bf16 v[32:35], v[190:193], v[208:211], v[32:35]
	s_setprio 2
	s_barrier
	v_mfma_f32_16x16x32_bf16 v[20:23], v[182:185], v[216:219], v[20:23]
	v_mfma_f32_16x16x32_bf16 v[16:19], v[190:193], v[216:219], v[16:19]
	v_mfma_f32_16x16x32_bf16 v[4:7], v[182:185], v[224:227], v[4:7]
	v_mfma_f32_16x16x32_bf16 v[0:3], v[190:193], v[224:227], v[0:3]
	s_setprio 0
	s_add_i32 s70, s70, 2
	s_add_u32 s40, s40, 0x100
	s_addc_u32 s41, s41, 0
	s_add_u32 s68, s68, 0x100
	s_addc_u32 s69, s69, 0
	s_cmp_gt_u32 s70, 13
	s_cbranch_scc0 .LBB0_244
	s_and_b64 vcc, exec, s[18:19]
	s_cbranch_vccz .LBB0_247
	s_barrier

; #define PG8_STAGE_T(bufoff, gbase, voff, AUX) do { _Pragma("unroll") for (int _i = 0; _i < 2; ++_i) \
;         __builtin_amdgcn_global_load_lds((const unsigned*)((const char*)(gbase) + (voff)[_i]), (PG8_LAS unsigned*)(lds + (bufoff) + ldsw + _i * 8192), 16, 0, AUX); } while (0)
; #define PG8_LDA(dst, b, h) do { _Pragma("unroll") for (int m = 0; m < 4; ++m) _Pragma("unroll") for (int k = 0; k < 2; ++k) dst[m][k] = *(const PG8_LAS bf16x8*)(lds + PG8_SA(b, h) + aoff + m * 2048 + k * 1024); } while (0)
; #define PG8_LDB(dst, b, h) do { _Pragma("unroll") for (int n = 0; n < 2; ++n) _Pragma("unroll") for (int k = 0; k < 2; ++k) dst[n][k] = *(const PG8_LAS bf16x8*)(lds + PG8_SB(b, h) + boff + n * 2048 + k * 1024); } while (0)
; #define PG8_MMA(ai, bj, At, Bt) do { __builtin_amdgcn_s_setprio(1); _Pragma("unroll") for (int m = 0; m < 4; ++m) _Pragma("unroll") for (int n = 0; n < 2; ++n) _Pragma("unroll") for (int k = 0; k < 2; ++k) \
;         acc[ai][bj][m][n] = __builtin_amdgcn_mfma_f32_16x16x32_bf16(Bt[n][k], At[m][k], acc[ai][bj][m][n], 0, 0, 0); __builtin_amdgcn_s_setprio(0); } while (0)
; #define PG8_WAIT_V(n) asm volatile("s_waitcnt vmcnt(" #n ")" ::: "memory")
; #define PG8_WAIT_L(n) asm volatile("s_waitcnt lgkmcnt(" #n ")" ::: "memory")
; #define PG8_BAR __builtin_amdgcn_s_barrier()
;     ...
;             const bool last = (t == nt - 2);
;             const char* a1 = cA + (ptrdiff_t)(t + 1) * ck;
;             const char* a2 = last ? nA : cA + (ptrdiff_t)(t + 2) * ck; const char* b2 = last ? nB : cB + (ptrdiff_t)(t + 2) * ck;
;             const ptrdiff_t k3 = last ? nk : ck;
;             const char* a3 = a2 + k3; const char* b3 = b2 + k3;
;             if (last && has_next) S.a_ready(nxt);
;             if constexpr (SP2) {
;             int pei = 0; if constexpr (PEEL) { pei = __builtin_amdgcn_readfirstlane((t == 0 && ui > 0) ? 1 : 0); asm volatile("" : "+s"(pei)); }
;             const bool pe = pei != 0;
;             PG8_LDB(B0, 0, 0); PG8_LDB(B1, 0, 1); PG8_SCHED; PG8_LDA(At, 0, 0); if (!pe) { PG8_STAGE_T(PG8_SA(1, 1), a1 + hstep, voffA, AUX_A); }
;             if (!pe) { PG8_WAIT_V(8); } PG8_WAIT_L(0); PG8_BAR; PG8_MMA(0, 0, At, B0); PG8_MMA(0, 1, At, B1); PG8_BAR; PG8_SCHED;
;             PG8_LDA(At, 0, 1); PG8_STAGE_T(PG8_SB(0, 0), b2, voffB, AUX_B); PG8_STAGE_T(PG8_SB(0, 1), b2 + hstep, voffB, AUX_B); PG8_STAGE_T(PG8_SA(0, 0), a2, voffA, AUX_A);
.LBB0_329:
	ds_read_b128 v[154:157], v149
	ds_read_b128 v[158:161], v149 offset:1024
	ds_read_b128 v[162:165], v149 offset:2048
	ds_read_b128 v[166:169], v149 offset:3072
	ds_read_b128 v[170:173], v150
	ds_read_b128 v[174:177], v150 offset:1024
	ds_read_b128 v[178:181], v150 offset:2048
	ds_read_b128 v[182:185], v150 offset:3072
	s_add_u32 s44, s40, 0xfff50080
	s_addc_u32 s45, s41, -1
	s_cmp_eq_u32 s67, 40
	s_cselect_b32 s49, s5, s45
	s_cselect_b32 s48, s4, s44
	s_cselect_b32 s45, s37, s66
	s_cselect_b32 s44, s36, s63
	v_lshl_add_u64 v[144:145], s[40:41], 0, v[136:137]
	s_add_i32 m0, s9, 0xc000
	ds_read_b128 v[186:189], v151
	ds_read_b128 v[190:193], v151 offset:1024
	ds_read_b128 v[196:199], v151 offset:2048
	ds_read_b128 v[200:203], v151 offset:3072
	ds_read_b128 v[204:207], v151 offset:4096
	ds_read_b128 v[208:211], v151 offset:5120
	ds_read_b128 v[212:215], v151 offset:6144
	ds_read_b128 v[216:219], v151 offset:7168
	global_load_lds_dwordx4 v[144:145], off
	v_lshl_add_u64 v[144:145], s[40:41], 0, v[138:139]
	s_add_i32 m0, s9, 0xe000
	s_nop 0
	global_load_lds_dwordx4 v[144:145], off
	s_waitcnt vmcnt(8)
	s_waitcnt lgkmcnt(0)
	s_barrier
	s_waitcnt lgkmcnt(0)
	v_mfma_f32_16x16x32_bf16 v[124:127], v[154:157], v[186:189], v[124:127]
	v_mfma_f32_16x16x32_bf16 v[120:123], v[162:165], v[186:189], v[120:123]
	v_mfma_f32_16x16x32_bf16 v[108:111], v[154:157], v[196:199], v[108:111]
	v_mfma_f32_16x16x32_bf16 v[104:107], v[162:165], v[196:199], v[104:107]
	v_mfma_f32_16x16x32_bf16 v[92:95], v[154:157], v[204:207], v[92:95]
	v_mfma_f32_16x16x32_bf16 v[88:91], v[162:165], v[204:207], v[88:91]
	v_mfma_f32_16x16x32_bf16 v[76:79], v[154:157], v[212:215], v[76:79]
	v_mfma_f32_16x16x32_bf16 v[72:75], v[162:165], v[212:215], v[72:75]
	v_mfma_f32_16x16x32_bf16 v[124:127], v[158:161], v[190:193], v[124:127]
	v_mfma_f32_16x16x32_bf16 v[120:123], v[166:169], v[190:193], v[120:123]
	v_mfma_f32_16x16x32_bf16 v[108:111], v[158:161], v[200:203], v[108:111]
	v_mfma_f32_16x16x32_bf16 v[104:107], v[166:169], v[200:203], v[104:107]
	v_mfma_f32_16x16x32_bf16 v[92:95], v[158:161], v[208:211], v[92:95]
	v_mfma_f32_16x16x32_bf16 v[88:91], v[166:169], v[208:211], v[88:91]
	v_mfma_f32_16x16x32_bf16 v[76:79], v[158:161], v[216:219], v[76:79]
	v_mfma_f32_16x16x32_bf16 v[72:75], v[166:169], v[216:219], v[72:75]
	v_mfma_f32_16x16x32_bf16 v[116:119], v[170:173], v[186:189], v[116:119]
	v_mfma_f32_16x16x32_bf16 v[112:115], v[178:181], v[186:189], v[112:115]
	v_mfma_f32_16x16x32_bf16 v[100:103], v[170:173], v[196:199], v[100:103]
	v_mfma_f32_16x16x32_bf16 v[96:99], v[178:181], v[196:199], v[96:99]
	v_mfma_f32_16x16x32_bf16 v[84:87], v[170:173], v[204:207], v[84:87]
	v_mfma_f32_16x16x32_bf16 v[80:83], v[178:181], v[204:207], v[80:83]
	v_mfma_f32_16x16x32_bf16 v[68:71], v[170:173], v[212:215], v[68:71]
	v_mfma_f32_16x16x32_bf16 v[64:67], v[178:181], v[212:215], v[64:67]
	v_mfma_f32_16x16x32_bf16 v[116:119], v[174:177], v[190:193], v[116:119]
	v_mfma_f32_16x16x32_bf16 v[112:115], v[182:185], v[190:193], v[112:115]
	v_mfma_f32_16x16x32_bf16 v[100:103], v[174:177], v[200:203], v[100:103]
	v_mfma_f32_16x16x32_bf16 v[96:99], v[182:185], v[200:203], v[96:99]
	s_setprio 2
	s_barrier
	v_mfma_f32_16x16x32_bf16 v[84:87], v[174:177], v[208:211], v[84:87]
	v_mfma_f32_16x16x32_bf16 v[80:83], v[182:185], v[208:211], v[80:83]
	v_mfma_f32_16x16x32_bf16 v[68:71], v[174:177], v[216:219], v[68:71]
	v_mfma_f32_16x16x32_bf16 v[64:67], v[182:185], v[216:219], v[64:67]
	s_setprio 0
	s_add_i32 s68, s56, s8
	v_lshl_add_u64 v[144:145], s[44:45], 0, v[130:131]
	s_mov_b32 m0, s68
	ds_read_b128 v[186:189], v151 offset:16384
	ds_read_b128 v[190:193], v151 offset:17408
	ds_read_b128 v[196:199], v151 offset:18432
	ds_read_b128 v[200:203], v151 offset:19456
	ds_read_b128 v[204:207], v151 offset:20480
	ds_read_b128 v[208:211], v151 offset:21504
	ds_read_b128 v[212:215], v151 offset:22528
	ds_read_b128 v[216:219], v151 offset:23552
	global_load_lds_dwordx4 v[144:145], off
	s_add_i32 m0, s68, 0x2000
	s_add_u32 s68, s44, 0xb0000
	v_lshl_add_u64 v[220:221], s[44:45], 0, v[134:135]
	s_addc_u32 s69, s45, 0
	s_add_i32 s70, s57, s8
	global_load_lds_dwordx4 v[220:221], off
	v_lshl_add_u64 v[222:223], s[68:69], 0, v[130:131]
	s_mov_b32 m0, s70
	v_lshl_add_u64 v[224:225], s[48:49], 0, v[132:133]
	global_load_lds_dwordx4 v[222:223], off
	v_lshl_add_u64 v[222:223], s[68:69], 0, v[134:135]
	s_add_i32 m0, s70, 0x2000
	s_nop 0
	global_load_lds_dwordx4 v[222:223], off
	v_lshl_add_u64 v[222:223], s[48:49], 0, v[128:129]
	s_mov_b32 m0, s9
	s_nop 0
	global_load_lds_dwordx4 v[222:223], off
	s_mov_b32 m0, s50
	s_nop 0
	global_load_lds_dwordx4 v[224:225], off
	s_waitcnt vmcnt(8)
	s_waitcnt lgkmcnt(0)
	s_barrier
; #define PG8_STAGE_T(bufoff, gbase, voff, AUX) do { _Pragma("unroll") for (int _i = 0; _i < 2; ++_i) \
;         __builtin_amdgcn_global_load_lds((const unsigned*)((const char*)(gbase) + (voff)[_i]), (PG8_LAS unsigned*)(lds + (bufoff) + ldsw + _i * 8192), 16, 0, AUX); } while (0)
; #define PG8_LDA(dst, b, h) do { _Pragma("unroll") for (int m = 0; m < 4; ++m) _Pragma("unroll") for (int k = 0; k < 2; ++k) dst[m][k] = *(const PG8_LAS bf16x8*)(lds + PG8_SA(b, h) + aoff + m * 2048 + k * 1024); } while (0)
; #define PG8_LDB(dst, b, h) do { _Pragma("unroll") for (int n = 0; n < 2; ++n) _Pragma("unroll") for (int k = 0; k < 2; ++k) dst[n][k] = *(const PG8_LAS bf16x8*)(lds + PG8_SB(b, h) + boff + n * 2048 + k * 1024); } while (0)
; #define PG8_MMA(ai, bj, At, Bt) do { __builtin_amdgcn_s_setprio(1); _Pragma("unroll") for (int m = 0; m < 4; ++m) _Pragma("unroll") for (int n = 0; n < 2; ++n) _Pragma("unroll") for (int k = 0; k < 2; ++k) \
;         acc[ai][bj][m][n] = __builtin_amdgcn_mfma_f32_16x16x32_bf16(Bt[n][k], At[m][k], acc[ai][bj][m][n], 0, 0, 0); __builtin_amdgcn_s_setprio(0); } while (0)
; #define PG8_WAIT_V(n) asm volatile("s_waitcnt vmcnt(" #n ")" ::: "memory")
; #define PG8_WAIT_L(n) asm volatile("s_waitcnt lgkmcnt(" #n ")" ::: "memory")
; #define PG8_BAR __builtin_amdgcn_s_barrier()
; #define PG8_SCHED __builtin_amdgcn_sched_barrier(0)
;     ...
;             if (!pe) { PG8_WAIT_V(8); } PG8_WAIT_L(0); PG8_BAR; PG8_MMA(1, 0, At, B0); PG8_MMA(1, 1, At, B1); PG8_BAR; PG8_SCHED;
;             PG8_LDB(B0, 1, 0); PG8_LDB(B1, 1, 1); PG8_SCHED; PG8_LDA(At, 1, 0); PG8_STAGE_T(PG8_SA(0, 1), a2 + hstep, voffA, AUX_A);
;             if (!pe) { PG8_WAIT_V(8); } PG8_WAIT_L(0); PG8_BAR; PG8_MMA(0, 0, At, B0); PG8_MMA(0, 1, At, B1); PG8_BAR; PG8_SCHED;
	s_waitcnt lgkmcnt(0)
	v_mfma_f32_16x16x32_bf16 v[60:63], v[154:157], v[186:189], v[60:63]
	v_mfma_f32_16x16x32_bf16 v[56:59], v[162:165], v[186:189], v[56:59]
	v_mfma_f32_16x16x32_bf16 v[44:47], v[154:157], v[196:199], v[44:47]
	v_mfma_f32_16x16x32_bf16 v[40:43], v[162:165], v[196:199], v[40:43]
	v_mfma_f32_16x16x32_bf16 v[28:31], v[154:157], v[204:207], v[28:31]
	v_mfma_f32_16x16x32_bf16 v[24:27], v[162:165], v[204:207], v[24:27]
	v_mfma_f32_16x16x32_bf16 v[12:15], v[154:157], v[212:215], v[12:15]
	v_mfma_f32_16x16x32_bf16 v[8:11], v[162:165], v[212:215], v[8:11]
	v_mfma_f32_16x16x32_bf16 v[60:63], v[158:161], v[190:193], v[60:63]
	v_mfma_f32_16x16x32_bf16 v[56:59], v[166:169], v[190:193], v[56:59]
	v_mfma_f32_16x16x32_bf16 v[44:47], v[158:161], v[200:203], v[44:47]
	v_mfma_f32_16x16x32_bf16 v[40:43], v[166:169], v[200:203], v[40:43]
	v_mfma_f32_16x16x32_bf16 v[28:31], v[158:161], v[208:211], v[28:31]
	v_mfma_f32_16x16x32_bf16 v[24:27], v[166:169], v[208:211], v[24:27]
	v_mfma_f32_16x16x32_bf16 v[12:15], v[158:161], v[216:219], v[12:15]
	v_mfma_f32_16x16x32_bf16 v[8:11], v[166:169], v[216:219], v[8:11]
	v_mfma_f32_16x16x32_bf16 v[52:55], v[170:173], v[186:189], v[52:55]
	v_mfma_f32_16x16x32_bf16 v[48:51], v[178:181], v[186:189], v[48:51]
	v_mfma_f32_16x16x32_bf16 v[36:39], v[170:173], v[196:199], v[36:39]
	v_mfma_f32_16x16x32_bf16 v[32:35], v[178:181], v[196:199], v[32:35]
	v_mfma_f32_16x16x32_bf16 v[20:23], v[170:173], v[204:207], v[20:23]
	v_mfma_f32_16x16x32_bf16 v[16:19], v[178:181], v[204:207], v[16:19]
	v_mfma_f32_16x16x32_bf16 v[4:7], v[170:173], v[212:215], v[4:7]
	v_mfma_f32_16x16x32_bf16 v[0:3], v[178:181], v[212:215], v[0:3]
	v_mfma_f32_16x16x32_bf16 v[52:55], v[174:177], v[190:193], v[52:55]
	v_mfma_f32_16x16x32_bf16 v[48:51], v[182:185], v[190:193], v[48:51]
	v_mfma_f32_16x16x32_bf16 v[36:39], v[174:177], v[200:203], v[36:39]
	v_mfma_f32_16x16x32_bf16 v[32:35], v[182:185], v[200:203], v[32:35]
	s_setprio 2
	s_barrier
	v_mfma_f32_16x16x32_bf16 v[20:23], v[174:177], v[208:211], v[20:23]
	v_mfma_f32_16x16x32_bf16 v[16:19], v[182:185], v[208:211], v[16:19]
	v_mfma_f32_16x16x32_bf16 v[4:7], v[174:177], v[216:219], v[4:7]
	v_mfma_f32_16x16x32_bf16 v[0:3], v[182:185], v[216:219], v[0:3]
	s_setprio 0
	s_add_i32 s68, 0, 0x18000
	v_add_u32_e32 v153, s68, v147
	s_add_i32 s69, 0, 0x1c000
	ds_read_b128 v[154:157], v153
	ds_read_b128 v[158:161], v153 offset:1024
	ds_read_b128 v[162:165], v153 offset:2048
	ds_read_b128 v[166:169], v153 offset:3072
	v_add_u32_e32 v153, s69, v147
	ds_read_b128 v[170:173], v153
	ds_read_b128 v[174:177], v153 offset:1024
	ds_read_b128 v[178:181], v153 offset:2048
	ds_read_b128 v[182:185], v153 offset:3072
	s_add_u32 s48, s48, 0xb0000
	s_addc_u32 s49, s49, 0
	s_mov_b32 m0, s51
	v_lshl_add_u64 v[226:227], s[48:49], 0, v[128:129]
	ds_read_b128 v[186:189], v151 offset:32768
	ds_read_b128 v[190:193], v151 offset:33792
	ds_read_b128 v[196:199], v151 offset:34816
	ds_read_b128 v[200:203], v151 offset:35840
	ds_read_b128 v[204:207], v151 offset:36864
	ds_read_b128 v[208:211], v151 offset:37888
	ds_read_b128 v[212:215], v151 offset:38912
	ds_read_b128 v[216:219], v151 offset:39936
	global_load_lds_dwordx4 v[226:227], off
	v_lshl_add_u64 v[226:227], s[48:49], 0, v[132:133]
	s_mov_b32 m0, s52
	s_nop 0
	global_load_lds_dwordx4 v[226:227], off
	s_waitcnt vmcnt(8)
	s_waitcnt lgkmcnt(0)
	s_barrier
	s_waitcnt lgkmcnt(0)
	v_mfma_f32_16x16x32_bf16 v[124:127], v[154:157], v[186:189], v[124:127]
	v_mfma_f32_16x16x32_bf16 v[120:123], v[162:165], v[186:189], v[120:123]
	v_mfma_f32_16x16x32_bf16 v[108:111], v[154:157], v[196:199], v[108:111]
	v_mfma_f32_16x16x32_bf16 v[104:107], v[162:165], v[196:199], v[104:107]
	v_mfma_f32_16x16x32_bf16 v[92:95], v[154:157], v[204:207], v[92:95]
	v_mfma_f32_16x16x32_bf16 v[88:91], v[162:165], v[204:207], v[88:91]
	v_mfma_f32_16x16x32_bf16 v[76:79], v[154:157], v[212:215], v[76:79]
	v_mfma_f32_16x16x32_bf16 v[72:75], v[162:165], v[212:215], v[72:75]
	v_mfma_f32_16x16x32_bf16 v[124:127], v[158:161], v[190:193], v[124:127]
	v_mfma_f32_16x16x32_bf16 v[120:123], v[166:169], v[190:193], v[120:123]
	v_mfma_f32_16x16x32_bf16 v[108:111], v[158:161], v[200:203], v[108:111]
	v_mfma_f32_16x16x32_bf16 v[104:107], v[166:169], v[200:203], v[104:107]
	v_mfma_f32_16x16x32_bf16 v[92:95], v[158:161], v[208:211], v[92:95]
	v_mfma_f32_16x16x32_bf16 v[88:91], v[166:169], v[208:211], v[88:91]
	v_mfma_f32_16x16x32_bf16 v[76:79], v[158:161], v[216:219], v[76:79]
	v_mfma_f32_16x16x32_bf16 v[72:75], v[166:169], v[216:219], v[72:75]
	v_mfma_f32_16x16x32_bf16 v[116:119], v[170:173], v[186:189], v[116:119]
	v_mfma_f32_16x16x32_bf16 v[112:115], v[178:181], v[186:189], v[112:115]
	v_mfma_f32_16x16x32_bf16 v[100:103], v[170:173], v[196:199], v[100:103]
	v_mfma_f32_16x16x32_bf16 v[96:99], v[178:181], v[196:199], v[96:99]
	v_mfma_f32_16x16x32_bf16 v[84:87], v[170:173], v[204:207], v[84:87]
	v_mfma_f32_16x16x32_bf16 v[80:83], v[178:181], v[204:207], v[80:83]
	v_mfma_f32_16x16x32_bf16 v[68:71], v[170:173], v[212:215], v[68:71]
	v_mfma_f32_16x16x32_bf16 v[64:67], v[178:181], v[212:215], v[64:67]
	v_mfma_f32_16x16x32_bf16 v[116:119], v[174:177], v[190:193], v[116:119]
	v_mfma_f32_16x16x32_bf16 v[112:115], v[182:185], v[190:193], v[112:115]
	v_mfma_f32_16x16x32_bf16 v[100:103], v[174:177], v[200:203], v[100:103]
	v_mfma_f32_16x16x32_bf16 v[96:99], v[182:185], v[200:203], v[96:99]
	s_setprio 2
	s_barrier
; #define PG8_STAGE_T(bufoff, gbase, voff, AUX) do { _Pragma("unroll") for (int _i = 0; _i < 2; ++_i) \
;         __builtin_amdgcn_global_load_lds((const unsigned*)((const char*)(gbase) + (voff)[_i]), (PG8_LAS unsigned*)(lds + (bufoff) + ldsw + _i * 8192), 16, 0, AUX); } while (0)
; #define PG8_LDA(dst, b, h) do { _Pragma("unroll") for (int m = 0; m < 4; ++m) _Pragma("unroll") for (int k = 0; k < 2; ++k) dst[m][k] = *(const PG8_LAS bf16x8*)(lds + PG8_SA(b, h) + aoff + m * 2048 + k * 1024); } while (0)
; #define PG8_MMA(ai, bj, At, Bt) do { __builtin_amdgcn_s_setprio(1); _Pragma("unroll") for (int m = 0; m < 4; ++m) _Pragma("unroll") for (int n = 0; n < 2; ++n) _Pragma("unroll") for (int k = 0; k < 2; ++k) \
;         acc[ai][bj][m][n] = __builtin_amdgcn_mfma_f32_16x16x32_bf16(Bt[n][k], At[m][k], acc[ai][bj][m][n], 0, 0, 0); __builtin_amdgcn_s_setprio(0); } while (0)
; #define PG8_WAIT_V(n) asm volatile("s_waitcnt vmcnt(" #n ")" ::: "memory")
; #define PG8_WAIT_L(n) asm volatile("s_waitcnt lgkmcnt(" #n ")" ::: "memory")
; #define PG8_BAR __builtin_amdgcn_s_barrier()
; #define PG8_SCHED __builtin_amdgcn_sched_barrier(0)
;     ...
;             if (!pe) { PG8_WAIT_V(8); } PG8_WAIT_L(0); PG8_BAR; PG8_MMA(0, 0, At, B0); PG8_MMA(0, 1, At, B1); PG8_BAR; PG8_SCHED;
;             PG8_LDA(At, 1, 1); PG8_STAGE_T(PG8_SB(1, 0), b3, voffB, AUX_B); PG8_STAGE_T(PG8_SB(1, 1), b3 + hstep, voffB, AUX_B); PG8_STAGE_T(PG8_SA(1, 0), a3, voffA, AUX_A);
;             PG8_WAIT_V(8); PG8_WAIT_L(0); PG8_BAR; PG8_MMA(1, 0, At, B0); PG8_MMA(1, 1, At, B1); PG8_BAR; PG8_SCHED;
;     ...
;         if constexpr (ALIGN_EPI) { if (wr == 0) PG8_BAR; }
	v_mfma_f32_16x16x32_bf16 v[84:87], v[174:177], v[208:211], v[84:87]
	v_mfma_f32_16x16x32_bf16 v[80:83], v[182:185], v[208:211], v[80:83]
	v_mfma_f32_16x16x32_bf16 v[68:71], v[174:177], v[216:219], v[68:71]
	v_mfma_f32_16x16x32_bf16 v[64:67], v[182:185], v[216:219], v[64:67]
	s_setprio 0
	s_add_i32 s48, s68, s8
	v_lshl_add_u64 v[144:145], v[144:145], 0, s[24:25]
	s_mov_b32 m0, s48
	ds_read_b128 v[186:189], v151 offset:49152
	ds_read_b128 v[190:193], v151 offset:50176
	ds_read_b128 v[196:199], v151 offset:51200
	ds_read_b128 v[200:203], v151 offset:52224
	ds_read_b128 v[204:207], v151 offset:53248
	ds_read_b128 v[208:211], v151 offset:54272
	ds_read_b128 v[212:215], v151 offset:55296
	ds_read_b128 v[216:219], v151 offset:56320
	global_load_lds_dwordx4 v[144:145], off
	s_add_i32 m0, s48, 0x2000
	s_add_u32 s44, s44, 0xb0080
	v_lshl_add_u64 v[144:145], v[220:221], 0, s[24:25]
	s_addc_u32 s45, s45, 0
	s_add_i32 s48, s69, s8
	global_load_lds_dwordx4 v[144:145], off
	v_lshl_add_u64 v[144:145], s[44:45], 0, v[130:131]
	s_mov_b32 m0, s48
	s_nop 0
	global_load_lds_dwordx4 v[144:145], off
	v_lshl_add_u64 v[144:145], s[44:45], 0, v[134:135]
	s_add_i32 m0, s48, 0x2000
	s_nop 0
	global_load_lds_dwordx4 v[144:145], off
	v_lshl_add_u64 v[144:145], v[222:223], 0, s[24:25]
	s_mov_b32 m0, s53
	s_nop 0
	global_load_lds_dwordx4 v[144:145], off
	v_lshl_add_u64 v[144:145], v[224:225], 0, s[24:25]
	s_mov_b32 m0, s54
	s_nop 0
	global_load_lds_dwordx4 v[144:145], off
	s_waitcnt vmcnt(8)
	s_waitcnt lgkmcnt(0)
	s_barrier
	s_waitcnt lgkmcnt(0)
	v_mfma_f32_16x16x32_bf16 v[60:63], v[154:157], v[186:189], v[60:63]
	v_mfma_f32_16x16x32_bf16 v[56:59], v[162:165], v[186:189], v[56:59]
	v_mfma_f32_16x16x32_bf16 v[44:47], v[154:157], v[196:199], v[44:47]
	v_mfma_f32_16x16x32_bf16 v[40:43], v[162:165], v[196:199], v[40:43]
	v_mfma_f32_16x16x32_bf16 v[28:31], v[154:157], v[204:207], v[28:31]
	v_mfma_f32_16x16x32_bf16 v[24:27], v[162:165], v[204:207], v[24:27]
	v_mfma_f32_16x16x32_bf16 v[12:15], v[154:157], v[212:215], v[12:15]
	v_mfma_f32_16x16x32_bf16 v[8:11], v[162:165], v[212:215], v[8:11]
	v_mfma_f32_16x16x32_bf16 v[60:63], v[158:161], v[190:193], v[60:63]
	v_mfma_f32_16x16x32_bf16 v[56:59], v[166:169], v[190:193], v[56:59]
	v_mfma_f32_16x16x32_bf16 v[44:47], v[158:161], v[200:203], v[44:47]
	v_mfma_f32_16x16x32_bf16 v[40:43], v[166:169], v[200:203], v[40:43]
	v_mfma_f32_16x16x32_bf16 v[28:31], v[158:161], v[208:211], v[28:31]
	v_mfma_f32_16x16x32_bf16 v[24:27], v[166:169], v[208:211], v[24:27]
	v_mfma_f32_16x16x32_bf16 v[12:15], v[158:161], v[216:219], v[12:15]
	v_mfma_f32_16x16x32_bf16 v[8:11], v[166:169], v[216:219], v[8:11]
	v_mfma_f32_16x16x32_bf16 v[52:55], v[170:173], v[186:189], v[52:55]
	v_mfma_f32_16x16x32_bf16 v[48:51], v[178:181], v[186:189], v[48:51]
	v_mfma_f32_16x16x32_bf16 v[36:39], v[170:173], v[196:199], v[36:39]
	v_mfma_f32_16x16x32_bf16 v[32:35], v[178:181], v[196:199], v[32:35]
	v_mfma_f32_16x16x32_bf16 v[20:23], v[170:173], v[204:207], v[20:23]
	v_mfma_f32_16x16x32_bf16 v[16:19], v[178:181], v[204:207], v[16:19]
	v_mfma_f32_16x16x32_bf16 v[4:7], v[170:173], v[212:215], v[4:7]
	v_mfma_f32_16x16x32_bf16 v[0:3], v[178:181], v[212:215], v[0:3]
	v_mfma_f32_16x16x32_bf16 v[52:55], v[174:177], v[190:193], v[52:55]
	v_mfma_f32_16x16x32_bf16 v[48:51], v[182:185], v[190:193], v[48:51]
	v_mfma_f32_16x16x32_bf16 v[36:39], v[174:177], v[200:203], v[36:39]
	v_mfma_f32_16x16x32_bf16 v[32:35], v[182:185], v[200:203], v[32:35]
	s_setprio 2
	s_barrier
	v_mfma_f32_16x16x32_bf16 v[20:23], v[174:177], v[208:211], v[20:23]
	v_mfma_f32_16x16x32_bf16 v[16:19], v[182:185], v[208:211], v[16:19]
	v_mfma_f32_16x16x32_bf16 v[4:7], v[174:177], v[216:219], v[4:7]
	v_mfma_f32_16x16x32_bf16 v[0:3], v[182:185], v[216:219], v[0:3]
	s_setprio 0
	s_add_i32 s67, s67, 2
	s_add_u32 s40, s40, 0x100
	s_addc_u32 s41, s41, 0
	s_add_u32 s63, s63, 0x100
	s_addc_u32 s66, s66, 0
	s_cmp_gt_u32 s67, 41
	s_cbranch_scc0 .LBB0_329
	s_and_b64 vcc, exec, s[26:27]
	s_cbranch_vccz .LBB0_332
	s_barrier

; #define PG8_STAGE_T(bufoff, gbase, voff, AUX) do { _Pragma("unroll") for (int _i = 0; _i < 2; ++_i) \
;         __builtin_amdgcn_global_load_lds((const unsigned*)((const char*)(gbase) + (voff)[_i]), (PG8_LAS unsigned*)(lds + (bufoff) + ldsw + _i * 8192), 16, 0, AUX); } while (0)
; #define PG8_LDA(dst, b, h) do { _Pragma("unroll") for (int m = 0; m < 4; ++m) _Pragma("unroll") for (int k = 0; k < 2; ++k) dst[m][k] = *(const PG8_LAS bf16x8*)(lds + PG8_SA(b, h) + aoff + m * 2048 + k * 1024); } while (0)
; #define PG8_LDB(dst, b, h) do { _Pragma("unroll") for (int n = 0; n < 2; ++n) _Pragma("unroll") for (int k = 0; k < 2; ++k) dst[n][k] = *(const PG8_LAS bf16x8*)(lds + PG8_SB(b, h) + boff + n * 2048 + k * 1024); } while (0)
; #define PG8_MMA(ai, bj, At, Bt) do { __builtin_amdgcn_s_setprio(1); _Pragma("unroll") for (int m = 0; m < 4; ++m) _Pragma("unroll") for (int n = 0; n < 2; ++n) _Pragma("unroll") for (int k = 0; k < 2; ++k) \
;         acc[ai][bj][m][n] = __builtin_amdgcn_mfma_f32_16x16x32_bf16(Bt[n][k], At[m][k], acc[ai][bj][m][n], 0, 0, 0); __builtin_amdgcn_s_setprio(0); } while (0)
; #define PG8_WAIT_V(n) asm volatile("s_waitcnt vmcnt(" #n ")" ::: "memory")
; #define PG8_WAIT_L(n) asm volatile("s_waitcnt lgkmcnt(" #n ")" ::: "memory")
; #define PG8_BAR __builtin_amdgcn_s_barrier()
;     ...
;             const bool last = (t == nt - 2);
;             const char* a1 = cA + (ptrdiff_t)(t + 1) * ck;
;             const char* a2 = last ? nA : cA + (ptrdiff_t)(t + 2) * ck; const char* b2 = last ? nB : cB + (ptrdiff_t)(t + 2) * ck;
;             const ptrdiff_t k3 = last ? nk : ck;
;             const char* a3 = a2 + k3; const char* b3 = b2 + k3;
;             if (last && has_next) S.a_ready(nxt);
;             if constexpr (SP2) {
;             int pei = 0; if constexpr (PEEL) { pei = __builtin_amdgcn_readfirstlane((t == 0 && ui > 0) ? 1 : 0); asm volatile("" : "+s"(pei)); }
;             const bool pe = pei != 0;
;             PG8_LDB(B0, 0, 0); PG8_LDB(B1, 0, 1); PG8_SCHED; PG8_LDA(At, 0, 0); if (!pe) { PG8_STAGE_T(PG8_SA(1, 1), a1 + hstep, voffA, AUX_A); }
;             if (!pe) { PG8_WAIT_V(8); } PG8_WAIT_L(0); PG8_BAR; PG8_MMA(0, 0, At, B0); PG8_MMA(0, 1, At, B1); PG8_BAR; PG8_SCHED;
;             PG8_LDA(At, 0, 1); PG8_STAGE_T(PG8_SB(0, 0), b2, voffB, AUX_B); PG8_STAGE_T(PG8_SB(0, 1), b2 + hstep, voffB, AUX_B); PG8_STAGE_T(PG8_SA(0, 0), a2, voffA, AUX_A);
.LBB0_516:
	ds_read_b128 v[146:149], v178
	ds_read_b128 v[150:153], v178 offset:1024
	ds_read_b128 v[154:157], v178 offset:2048
	ds_read_b128 v[158:161], v178 offset:3072
	ds_read_b128 v[162:165], v179
	ds_read_b128 v[166:169], v179 offset:1024
	ds_read_b128 v[170:173], v179 offset:2048
	ds_read_b128 v[182:185], v179 offset:3072
	s_add_u32 s50, s48, 0xfffc0080
	s_addc_u32 s51, s49, -1
	s_cmp_eq_u32 s68, 12
	s_cselect_b32 s53, s5, s51
	s_cselect_b32 s52, s7, s50
	s_cselect_b32 s51, s27, s67
	s_cselect_b32 s50, s37, s66
	v_lshl_add_u64 v[220:221], s[48:49], 0, v[138:139]
	s_add_i32 m0, s9, 0xc000
	ds_read_b128 v[186:189], v180
	ds_read_b128 v[190:193], v180 offset:1024
	ds_read_b128 v[196:199], v180 offset:2048
	ds_read_b128 v[200:203], v180 offset:3072
	ds_read_b128 v[204:207], v180 offset:4096
	ds_read_b128 v[208:211], v180 offset:5120
	ds_read_b128 v[212:215], v180 offset:6144
	ds_read_b128 v[216:219], v180 offset:7168
	global_load_lds_dwordx4 v[220:221], off
	v_lshl_add_u64 v[220:221], s[48:49], 0, v[140:141]
	s_add_i32 m0, s9, 0xe000
	s_nop 0
	global_load_lds_dwordx4 v[220:221], off
	s_waitcnt vmcnt(8)
	s_waitcnt lgkmcnt(0)
	s_barrier
	s_waitcnt lgkmcnt(0)
	v_mfma_f32_16x16x32_bf16 v[124:127], v[146:149], v[186:189], v[124:127]
	v_mfma_f32_16x16x32_bf16 v[120:123], v[154:157], v[186:189], v[120:123]
	v_mfma_f32_16x16x32_bf16 v[108:111], v[146:149], v[196:199], v[108:111]
	v_mfma_f32_16x16x32_bf16 v[104:107], v[154:157], v[196:199], v[104:107]
	v_mfma_f32_16x16x32_bf16 v[92:95], v[146:149], v[204:207], v[92:95]
	v_mfma_f32_16x16x32_bf16 v[88:91], v[154:157], v[204:207], v[88:91]
	v_mfma_f32_16x16x32_bf16 v[76:79], v[146:149], v[212:215], v[76:79]
	v_mfma_f32_16x16x32_bf16 v[72:75], v[154:157], v[212:215], v[72:75]
	v_mfma_f32_16x16x32_bf16 v[124:127], v[150:153], v[190:193], v[124:127]
	v_mfma_f32_16x16x32_bf16 v[120:123], v[158:161], v[190:193], v[120:123]
	v_mfma_f32_16x16x32_bf16 v[108:111], v[150:153], v[200:203], v[108:111]
	v_mfma_f32_16x16x32_bf16 v[104:107], v[158:161], v[200:203], v[104:107]
	v_mfma_f32_16x16x32_bf16 v[92:95], v[150:153], v[208:211], v[92:95]
	v_mfma_f32_16x16x32_bf16 v[88:91], v[158:161], v[208:211], v[88:91]
	v_mfma_f32_16x16x32_bf16 v[76:79], v[150:153], v[216:219], v[76:79]
	v_mfma_f32_16x16x32_bf16 v[72:75], v[158:161], v[216:219], v[72:75]
	v_mfma_f32_16x16x32_bf16 v[116:119], v[162:165], v[186:189], v[116:119]
	v_mfma_f32_16x16x32_bf16 v[112:115], v[170:173], v[186:189], v[112:115]
	v_mfma_f32_16x16x32_bf16 v[100:103], v[162:165], v[196:199], v[100:103]
	v_mfma_f32_16x16x32_bf16 v[96:99], v[170:173], v[196:199], v[96:99]
	v_mfma_f32_16x16x32_bf16 v[84:87], v[162:165], v[204:207], v[84:87]
	v_mfma_f32_16x16x32_bf16 v[80:83], v[170:173], v[204:207], v[80:83]
	v_mfma_f32_16x16x32_bf16 v[68:71], v[162:165], v[212:215], v[68:71]
	v_mfma_f32_16x16x32_bf16 v[64:67], v[170:173], v[212:215], v[64:67]
	v_mfma_f32_16x16x32_bf16 v[116:119], v[166:169], v[190:193], v[116:119]
	v_mfma_f32_16x16x32_bf16 v[112:115], v[182:185], v[190:193], v[112:115]
	v_mfma_f32_16x16x32_bf16 v[100:103], v[166:169], v[200:203], v[100:103]
	v_mfma_f32_16x16x32_bf16 v[96:99], v[182:185], v[200:203], v[96:99]
	s_setprio 2
	s_barrier
	v_mfma_f32_16x16x32_bf16 v[84:87], v[166:169], v[208:211], v[84:87]
	v_mfma_f32_16x16x32_bf16 v[80:83], v[182:185], v[208:211], v[80:83]
	v_mfma_f32_16x16x32_bf16 v[68:71], v[166:169], v[216:219], v[68:71]
	v_mfma_f32_16x16x32_bf16 v[64:67], v[182:185], v[216:219], v[64:67]
	s_setprio 0
	s_add_i32 s69, s61, s8
	v_lshl_add_u64 v[220:221], s[50:51], 0, v[130:131]
	s_mov_b32 m0, s69
	ds_read_b128 v[186:189], v180 offset:16384
	ds_read_b128 v[190:193], v180 offset:17408
	ds_read_b128 v[196:199], v180 offset:18432
	ds_read_b128 v[200:203], v180 offset:19456
	ds_read_b128 v[204:207], v180 offset:20480
	ds_read_b128 v[208:211], v180 offset:21504
	ds_read_b128 v[212:215], v180 offset:22528
	ds_read_b128 v[216:219], v180 offset:23552
	global_load_lds_dwordx4 v[220:221], off
	s_add_i32 m0, s69, 0x2000
	s_add_u32 s70, s50, 0x40000
	v_lshl_add_u64 v[222:223], s[50:51], 0, v[134:135]
	s_addc_u32 s71, s51, 0
	s_add_i32 s69, s62, s8
	global_load_lds_dwordx4 v[222:223], off
	v_lshl_add_u64 v[224:225], s[70:71], 0, v[130:131]
	s_mov_b32 m0, s69
	v_lshl_add_u64 v[226:227], s[52:53], 0, v[132:133]
	global_load_lds_dwordx4 v[224:225], off
	v_lshl_add_u64 v[224:225], s[70:71], 0, v[134:135]
	s_add_i32 m0, s69, 0x2000
	s_nop 0
	global_load_lds_dwordx4 v[224:225], off
	v_lshl_add_u64 v[224:225], s[52:53], 0, v[128:129]
	s_mov_b32 m0, s9
	s_nop 0
	global_load_lds_dwordx4 v[224:225], off
	s_mov_b32 m0, s55
	s_nop 0
	global_load_lds_dwordx4 v[226:227], off
	s_waitcnt vmcnt(8)
	s_waitcnt lgkmcnt(0)
	s_barrier
; #define PG8_STAGE_T(bufoff, gbase, voff, AUX) do { _Pragma("unroll") for (int _i = 0; _i < 2; ++_i) \
;         __builtin_amdgcn_global_load_lds((const unsigned*)((const char*)(gbase) + (voff)[_i]), (PG8_LAS unsigned*)(lds + (bufoff) + ldsw + _i * 8192), 16, 0, AUX); } while (0)
; #define PG8_LDA(dst, b, h) do { _Pragma("unroll") for (int m = 0; m < 4; ++m) _Pragma("unroll") for (int k = 0; k < 2; ++k) dst[m][k] = *(const PG8_LAS bf16x8*)(lds + PG8_SA(b, h) + aoff + m * 2048 + k * 1024); } while (0)
; #define PG8_LDB(dst, b, h) do { _Pragma("unroll") for (int n = 0; n < 2; ++n) _Pragma("unroll") for (int k = 0; k < 2; ++k) dst[n][k] = *(const PG8_LAS bf16x8*)(lds + PG8_SB(b, h) + boff + n * 2048 + k * 1024); } while (0)
; #define PG8_MMA(ai, bj, At, Bt) do { __builtin_amdgcn_s_setprio(1); _Pragma("unroll") for (int m = 0; m < 4; ++m) _Pragma("unroll") for (int n = 0; n < 2; ++n) _Pragma("unroll") for (int k = 0; k < 2; ++k) \
;         acc[ai][bj][m][n] = __builtin_amdgcn_mfma_f32_16x16x32_bf16(Bt[n][k], At[m][k], acc[ai][bj][m][n], 0, 0, 0); __builtin_amdgcn_s_setprio(0); } while (0)
; #define PG8_WAIT_V(n) asm volatile("s_waitcnt vmcnt(" #n ")" ::: "memory")
; #define PG8_WAIT_L(n) asm volatile("s_waitcnt lgkmcnt(" #n ")" ::: "memory")
; #define PG8_BAR __builtin_amdgcn_s_barrier()
; #define PG8_SCHED __builtin_amdgcn_sched_barrier(0)
;     ...
;             if (!pe) { PG8_WAIT_V(8); } PG8_WAIT_L(0); PG8_BAR; PG8_MMA(1, 0, At, B0); PG8_MMA(1, 1, At, B1); PG8_BAR; PG8_SCHED;
;             PG8_LDB(B0, 1, 0); PG8_LDB(B1, 1, 1); PG8_SCHED; PG8_LDA(At, 1, 0); PG8_STAGE_T(PG8_SA(0, 1), a2 + hstep, voffA, AUX_A);
;             if (!pe) { PG8_WAIT_V(8); } PG8_WAIT_L(0); PG8_BAR; PG8_MMA(0, 0, At, B0); PG8_MMA(0, 1, At, B1); PG8_BAR; PG8_SCHED;
	s_waitcnt lgkmcnt(0)
	v_mfma_f32_16x16x32_bf16 v[60:63], v[146:149], v[186:189], v[60:63]
	v_mfma_f32_16x16x32_bf16 v[56:59], v[154:157], v[186:189], v[56:59]
	v_mfma_f32_16x16x32_bf16 v[44:47], v[146:149], v[196:199], v[44:47]
	v_mfma_f32_16x16x32_bf16 v[40:43], v[154:157], v[196:199], v[40:43]
	v_mfma_f32_16x16x32_bf16 v[28:31], v[146:149], v[204:207], v[28:31]
	v_mfma_f32_16x16x32_bf16 v[24:27], v[154:157], v[204:207], v[24:27]
	v_mfma_f32_16x16x32_bf16 v[12:15], v[146:149], v[212:215], v[12:15]
	v_mfma_f32_16x16x32_bf16 v[8:11], v[154:157], v[212:215], v[8:11]
	v_mfma_f32_16x16x32_bf16 v[60:63], v[150:153], v[190:193], v[60:63]
	v_mfma_f32_16x16x32_bf16 v[56:59], v[158:161], v[190:193], v[56:59]
	v_mfma_f32_16x16x32_bf16 v[44:47], v[150:153], v[200:203], v[44:47]
	v_mfma_f32_16x16x32_bf16 v[40:43], v[158:161], v[200:203], v[40:43]
	v_mfma_f32_16x16x32_bf16 v[28:31], v[150:153], v[208:211], v[28:31]
	v_mfma_f32_16x16x32_bf16 v[24:27], v[158:161], v[208:211], v[24:27]
	v_mfma_f32_16x16x32_bf16 v[12:15], v[150:153], v[216:219], v[12:15]
	v_mfma_f32_16x16x32_bf16 v[8:11], v[158:161], v[216:219], v[8:11]
	v_mfma_f32_16x16x32_bf16 v[52:55], v[162:165], v[186:189], v[52:55]
	v_mfma_f32_16x16x32_bf16 v[48:51], v[170:173], v[186:189], v[48:51]
	v_mfma_f32_16x16x32_bf16 v[36:39], v[162:165], v[196:199], v[36:39]
	v_mfma_f32_16x16x32_bf16 v[32:35], v[170:173], v[196:199], v[32:35]
	v_mfma_f32_16x16x32_bf16 v[20:23], v[162:165], v[204:207], v[20:23]
	v_mfma_f32_16x16x32_bf16 v[16:19], v[170:173], v[204:207], v[16:19]
	v_mfma_f32_16x16x32_bf16 v[4:7], v[162:165], v[212:215], v[4:7]
	v_mfma_f32_16x16x32_bf16 v[0:3], v[170:173], v[212:215], v[0:3]
	v_mfma_f32_16x16x32_bf16 v[52:55], v[166:169], v[190:193], v[52:55]
	v_mfma_f32_16x16x32_bf16 v[48:51], v[182:185], v[190:193], v[48:51]
	v_mfma_f32_16x16x32_bf16 v[36:39], v[166:169], v[200:203], v[36:39]
	v_mfma_f32_16x16x32_bf16 v[32:35], v[182:185], v[200:203], v[32:35]
	s_setprio 2
	s_barrier
	v_mfma_f32_16x16x32_bf16 v[20:23], v[166:169], v[208:211], v[20:23]
	v_mfma_f32_16x16x32_bf16 v[16:19], v[182:185], v[208:211], v[16:19]
	v_mfma_f32_16x16x32_bf16 v[4:7], v[166:169], v[216:219], v[4:7]
	v_mfma_f32_16x16x32_bf16 v[0:3], v[182:185], v[216:219], v[0:3]
	s_setprio 0
	s_add_i32 s69, 0, 0x18000
	v_add_u32_e32 v136, s69, v175
	s_add_i32 s70, 0, 0x1c000
	ds_read_b128 v[146:149], v136
	ds_read_b128 v[150:153], v136 offset:1024
	ds_read_b128 v[154:157], v136 offset:2048
	ds_read_b128 v[158:161], v136 offset:3072
	v_add_u32_e32 v136, s70, v175
	ds_read_b128 v[162:165], v136
	ds_read_b128 v[166:169], v136 offset:1024
	ds_read_b128 v[170:173], v136 offset:2048
	ds_read_b128 v[182:185], v136 offset:3072
	s_add_u32 s52, s52, 0x40000
	s_addc_u32 s53, s53, 0
	s_mov_b32 m0, s56
	v_lshl_add_u64 v[228:229], s[52:53], 0, v[128:129]
	ds_read_b128 v[186:189], v180 offset:32768
	ds_read_b128 v[190:193], v180 offset:33792
	ds_read_b128 v[196:199], v180 offset:34816
	ds_read_b128 v[200:203], v180 offset:35840
	ds_read_b128 v[204:207], v180 offset:36864
	ds_read_b128 v[208:211], v180 offset:37888
	ds_read_b128 v[212:215], v180 offset:38912
	ds_read_b128 v[216:219], v180 offset:39936
	global_load_lds_dwordx4 v[228:229], off
	v_lshl_add_u64 v[228:229], s[52:53], 0, v[132:133]
	s_mov_b32 m0, s57
	s_nop 0
	global_load_lds_dwordx4 v[228:229], off
	s_waitcnt vmcnt(8)
	s_waitcnt lgkmcnt(0)
	s_barrier
	s_waitcnt lgkmcnt(0)
	v_mfma_f32_16x16x32_bf16 v[124:127], v[146:149], v[186:189], v[124:127]
	v_mfma_f32_16x16x32_bf16 v[120:123], v[154:157], v[186:189], v[120:123]
	v_mfma_f32_16x16x32_bf16 v[108:111], v[146:149], v[196:199], v[108:111]
	v_mfma_f32_16x16x32_bf16 v[104:107], v[154:157], v[196:199], v[104:107]
	v_mfma_f32_16x16x32_bf16 v[92:95], v[146:149], v[204:207], v[92:95]
	v_mfma_f32_16x16x32_bf16 v[88:91], v[154:157], v[204:207], v[88:91]
	v_mfma_f32_16x16x32_bf16 v[76:79], v[146:149], v[212:215], v[76:79]
	v_mfma_f32_16x16x32_bf16 v[72:75], v[154:157], v[212:215], v[72:75]
	v_mfma_f32_16x16x32_bf16 v[124:127], v[150:153], v[190:193], v[124:127]
	v_mfma_f32_16x16x32_bf16 v[120:123], v[158:161], v[190:193], v[120:123]
	v_mfma_f32_16x16x32_bf16 v[108:111], v[150:153], v[200:203], v[108:111]
	v_mfma_f32_16x16x32_bf16 v[104:107], v[158:161], v[200:203], v[104:107]
	v_mfma_f32_16x16x32_bf16 v[92:95], v[150:153], v[208:211], v[92:95]
	v_mfma_f32_16x16x32_bf16 v[88:91], v[158:161], v[208:211], v[88:91]
	v_mfma_f32_16x16x32_bf16 v[76:79], v[150:153], v[216:219], v[76:79]
	v_mfma_f32_16x16x32_bf16 v[72:75], v[158:161], v[216:219], v[72:75]
	v_mfma_f32_16x16x32_bf16 v[116:119], v[162:165], v[186:189], v[116:119]
	v_mfma_f32_16x16x32_bf16 v[112:115], v[170:173], v[186:189], v[112:115]
	v_mfma_f32_16x16x32_bf16 v[100:103], v[162:165], v[196:199], v[100:103]
	v_mfma_f32_16x16x32_bf16 v[96:99], v[170:173], v[196:199], v[96:99]
	v_mfma_f32_16x16x32_bf16 v[84:87], v[162:165], v[204:207], v[84:87]
	v_mfma_f32_16x16x32_bf16 v[80:83], v[170:173], v[204:207], v[80:83]
	v_mfma_f32_16x16x32_bf16 v[68:71], v[162:165], v[212:215], v[68:71]
	v_mfma_f32_16x16x32_bf16 v[64:67], v[170:173], v[212:215], v[64:67]
	v_mfma_f32_16x16x32_bf16 v[116:119], v[166:169], v[190:193], v[116:119]
	v_mfma_f32_16x16x32_bf16 v[112:115], v[182:185], v[190:193], v[112:115]
	v_mfma_f32_16x16x32_bf16 v[100:103], v[166:169], v[200:203], v[100:103]
	v_mfma_f32_16x16x32_bf16 v[96:99], v[182:185], v[200:203], v[96:99]
	s_setprio 2
	s_barrier
; #define PG8_STAGE_T(bufoff, gbase, voff, AUX) do { _Pragma("unroll") for (int _i = 0; _i < 2; ++_i) \
;         __builtin_amdgcn_global_load_lds((const unsigned*)((const char*)(gbase) + (voff)[_i]), (PG8_LAS unsigned*)(lds + (bufoff) + ldsw + _i * 8192), 16, 0, AUX); } while (0)
; #define PG8_LDA(dst, b, h) do { _Pragma("unroll") for (int m = 0; m < 4; ++m) _Pragma("unroll") for (int k = 0; k < 2; ++k) dst[m][k] = *(const PG8_LAS bf16x8*)(lds + PG8_SA(b, h) + aoff + m * 2048 + k * 1024); } while (0)
; #define PG8_MMA(ai, bj, At, Bt) do { __builtin_amdgcn_s_setprio(1); _Pragma("unroll") for (int m = 0; m < 4; ++m) _Pragma("unroll") for (int n = 0; n < 2; ++n) _Pragma("unroll") for (int k = 0; k < 2; ++k) \
;         acc[ai][bj][m][n] = __builtin_amdgcn_mfma_f32_16x16x32_bf16(Bt[n][k], At[m][k], acc[ai][bj][m][n], 0, 0, 0); __builtin_amdgcn_s_setprio(0); } while (0)
; #define PG8_WAIT_V(n) asm volatile("s_waitcnt vmcnt(" #n ")" ::: "memory")
; #define PG8_WAIT_L(n) asm volatile("s_waitcnt lgkmcnt(" #n ")" ::: "memory")
; #define PG8_BAR __builtin_amdgcn_s_barrier()
; #define PG8_SCHED __builtin_amdgcn_sched_barrier(0)
;     ...
;             if (!pe) { PG8_WAIT_V(8); } PG8_WAIT_L(0); PG8_BAR; PG8_MMA(0, 0, At, B0); PG8_MMA(0, 1, At, B1); PG8_BAR; PG8_SCHED;
;             PG8_LDA(At, 1, 1); PG8_STAGE_T(PG8_SB(1, 0), b3, voffB, AUX_B); PG8_STAGE_T(PG8_SB(1, 1), b3 + hstep, voffB, AUX_B); PG8_STAGE_T(PG8_SA(1, 0), a3, voffA, AUX_A);
;             PG8_WAIT_V(8); PG8_WAIT_L(0); PG8_BAR; PG8_MMA(1, 0, At, B0); PG8_MMA(1, 1, At, B1); PG8_BAR; PG8_SCHED;
;     ...
;         if constexpr (ALIGN_EPI) { if (wr == 0) PG8_BAR; }
	v_mfma_f32_16x16x32_bf16 v[84:87], v[166:169], v[208:211], v[84:87]
	v_mfma_f32_16x16x32_bf16 v[80:83], v[182:185], v[208:211], v[80:83]
	v_mfma_f32_16x16x32_bf16 v[68:71], v[166:169], v[216:219], v[68:71]
	v_mfma_f32_16x16x32_bf16 v[64:67], v[182:185], v[216:219], v[64:67]
	s_setprio 0
	s_add_i32 s52, s69, s8
	v_lshl_add_u64 v[220:221], v[220:221], 0, s[22:23]
	s_mov_b32 m0, s52
	ds_read_b128 v[186:189], v180 offset:49152
	ds_read_b128 v[190:193], v180 offset:50176
	ds_read_b128 v[196:199], v180 offset:51200
	ds_read_b128 v[200:203], v180 offset:52224
	ds_read_b128 v[204:207], v180 offset:53248
	ds_read_b128 v[208:211], v180 offset:54272
	ds_read_b128 v[212:215], v180 offset:55296
	ds_read_b128 v[216:219], v180 offset:56320
	global_load_lds_dwordx4 v[220:221], off
	s_add_i32 m0, s52, 0x2000
	s_add_u32 s50, s50, 0x40080
	v_lshl_add_u64 v[220:221], v[222:223], 0, s[22:23]
	s_addc_u32 s51, s51, 0
	s_add_i32 s52, s70, s8
	global_load_lds_dwordx4 v[220:221], off
	v_lshl_add_u64 v[220:221], s[50:51], 0, v[130:131]
	s_mov_b32 m0, s52
	s_nop 0
	global_load_lds_dwordx4 v[220:221], off
	v_lshl_add_u64 v[220:221], s[50:51], 0, v[134:135]
	s_add_i32 m0, s52, 0x2000
	s_nop 0
	global_load_lds_dwordx4 v[220:221], off
	v_lshl_add_u64 v[220:221], v[224:225], 0, s[22:23]
	s_mov_b32 m0, s59
	s_nop 0
	global_load_lds_dwordx4 v[220:221], off
	v_lshl_add_u64 v[220:221], v[226:227], 0, s[22:23]
	s_mov_b32 m0, s60
	s_nop 0
	global_load_lds_dwordx4 v[220:221], off
	s_waitcnt vmcnt(8)
	s_waitcnt lgkmcnt(0)
	s_barrier
	s_waitcnt lgkmcnt(0)
	v_mfma_f32_16x16x32_bf16 v[60:63], v[146:149], v[186:189], v[60:63]
	v_mfma_f32_16x16x32_bf16 v[56:59], v[154:157], v[186:189], v[56:59]
	v_mfma_f32_16x16x32_bf16 v[44:47], v[146:149], v[196:199], v[44:47]
	v_mfma_f32_16x16x32_bf16 v[40:43], v[154:157], v[196:199], v[40:43]
	v_mfma_f32_16x16x32_bf16 v[28:31], v[146:149], v[204:207], v[28:31]
	v_mfma_f32_16x16x32_bf16 v[24:27], v[154:157], v[204:207], v[24:27]
	v_mfma_f32_16x16x32_bf16 v[12:15], v[146:149], v[212:215], v[12:15]
	v_mfma_f32_16x16x32_bf16 v[8:11], v[154:157], v[212:215], v[8:11]
	v_mfma_f32_16x16x32_bf16 v[60:63], v[150:153], v[190:193], v[60:63]
	v_mfma_f32_16x16x32_bf16 v[56:59], v[158:161], v[190:193], v[56:59]
	v_mfma_f32_16x16x32_bf16 v[44:47], v[150:153], v[200:203], v[44:47]
	v_mfma_f32_16x16x32_bf16 v[40:43], v[158:161], v[200:203], v[40:43]
	v_mfma_f32_16x16x32_bf16 v[28:31], v[150:153], v[208:211], v[28:31]
	v_mfma_f32_16x16x32_bf16 v[24:27], v[158:161], v[208:211], v[24:27]
	v_mfma_f32_16x16x32_bf16 v[12:15], v[150:153], v[216:219], v[12:15]
	v_mfma_f32_16x16x32_bf16 v[8:11], v[158:161], v[216:219], v[8:11]
	v_mfma_f32_16x16x32_bf16 v[52:55], v[162:165], v[186:189], v[52:55]
	v_mfma_f32_16x16x32_bf16 v[48:51], v[170:173], v[186:189], v[48:51]
	v_mfma_f32_16x16x32_bf16 v[36:39], v[162:165], v[196:199], v[36:39]
	v_mfma_f32_16x16x32_bf16 v[32:35], v[170:173], v[196:199], v[32:35]
	v_mfma_f32_16x16x32_bf16 v[20:23], v[162:165], v[204:207], v[20:23]
	v_mfma_f32_16x16x32_bf16 v[16:19], v[170:173], v[204:207], v[16:19]
	v_mfma_f32_16x16x32_bf16 v[4:7], v[162:165], v[212:215], v[4:7]
	v_mfma_f32_16x16x32_bf16 v[0:3], v[170:173], v[212:215], v[0:3]
	v_mfma_f32_16x16x32_bf16 v[52:55], v[166:169], v[190:193], v[52:55]
	v_mfma_f32_16x16x32_bf16 v[48:51], v[182:185], v[190:193], v[48:51]
	v_mfma_f32_16x16x32_bf16 v[36:39], v[166:169], v[200:203], v[36:39]
	v_mfma_f32_16x16x32_bf16 v[32:35], v[182:185], v[200:203], v[32:35]
	s_setprio 2
	s_barrier
	v_mfma_f32_16x16x32_bf16 v[20:23], v[166:169], v[208:211], v[20:23]
	v_mfma_f32_16x16x32_bf16 v[16:19], v[182:185], v[208:211], v[16:19]
	v_mfma_f32_16x16x32_bf16 v[4:7], v[166:169], v[216:219], v[4:7]
	v_mfma_f32_16x16x32_bf16 v[0:3], v[182:185], v[216:219], v[0:3]
	s_setprio 0
	s_add_i32 s68, s68, 2
	s_add_u32 s48, s48, 0x100
	s_addc_u32 s49, s49, 0
	s_add_u32 s66, s66, 0x100
	s_addc_u32 s67, s67, 0
	s_cmp_gt_u32 s68, 13
	s_cbranch_scc0 .LBB0_516
	s_and_b64 vcc, exec, s[24:25]
	s_cbranch_vccz .LBB0_519
	s_barrier

; #define PG8_STAGE_T(bufoff, gbase, voff, AUX) do { _Pragma("unroll") for (int _i = 0; _i < 2; ++_i) \
;         __builtin_amdgcn_global_load_lds((const unsigned*)((const char*)(gbase) + (voff)[_i]), (PG8_LAS unsigned*)(lds + (bufoff) + ldsw + _i * 8192), 16, 0, AUX); } while (0)
; #define PG8_LDA(dst, b, h) do { _Pragma("unroll") for (int m = 0; m < 4; ++m) _Pragma("unroll") for (int k = 0; k < 2; ++k) dst[m][k] = *(const PG8_LAS bf16x8*)(lds + PG8_SA(b, h) + aoff + m * 2048 + k * 1024); } while (0)
; #define PG8_LDB(dst, b, h) do { _Pragma("unroll") for (int n = 0; n < 2; ++n) _Pragma("unroll") for (int k = 0; k < 2; ++k) dst[n][k] = *(const PG8_LAS bf16x8*)(lds + PG8_SB(b, h) + boff + n * 2048 + k * 1024); } while (0)
; #define PG8_MMA(ai, bj, At, Bt) do { __builtin_amdgcn_s_setprio(1); _Pragma("unroll") for (int m = 0; m < 4; ++m) _Pragma("unroll") for (int n = 0; n < 2; ++n) _Pragma("unroll") for (int k = 0; k < 2; ++k) \
;         acc[ai][bj][m][n] = __builtin_amdgcn_mfma_f32_16x16x32_bf16(Bt[n][k], At[m][k], acc[ai][bj][m][n], 0, 0, 0); __builtin_amdgcn_s_setprio(0); } while (0)
; #define PG8_WAIT_V(n) asm volatile("s_waitcnt vmcnt(" #n ")" ::: "memory")
; #define PG8_WAIT_L(n) asm volatile("s_waitcnt lgkmcnt(" #n ")" ::: "memory")
; #define PG8_BAR __builtin_amdgcn_s_barrier()
;     ...
;             const bool last = (t == nt - 2);
;             const char* a1 = cA + (ptrdiff_t)(t + 1) * ck;
;             const char* a2 = last ? nA : cA + (ptrdiff_t)(t + 2) * ck; const char* b2 = last ? nB : cB + (ptrdiff_t)(t + 2) * ck;
;             const ptrdiff_t k3 = last ? nk : ck;
;             const char* a3 = a2 + k3; const char* b3 = b2 + k3;
;             if (last && has_next) S.a_ready(nxt);
;             if constexpr (SP2) {
;             int pei = 0; if constexpr (PEEL) { pei = __builtin_amdgcn_readfirstlane((t == 0 && ui > 0) ? 1 : 0); asm volatile("" : "+s"(pei)); }
;             const bool pe = pei != 0;
;             PG8_LDB(B0, 0, 0); PG8_LDB(B1, 0, 1); PG8_SCHED; PG8_LDA(At, 0, 0); if (!pe) { PG8_STAGE_T(PG8_SA(1, 1), a1 + hstep, voffA, AUX_A); }
;             if (!pe) { PG8_WAIT_V(8); } PG8_WAIT_L(0); PG8_BAR; PG8_MMA(0, 0, At, B0); PG8_MMA(0, 1, At, B1); PG8_BAR; PG8_SCHED;
;             PG8_LDA(At, 0, 1); PG8_STAGE_T(PG8_SB(0, 0), b2, voffB, AUX_B); PG8_STAGE_T(PG8_SB(0, 1), b2 + hstep, voffB, AUX_B); PG8_STAGE_T(PG8_SA(0, 0), a2, voffA, AUX_A);
.LBB0_787:
	ds_read_b128 v[136:139], v163
	ds_read_b128 v[140:143], v163 offset:1024
	ds_read_b128 v[166:169], v163 offset:2048
	ds_read_b128 v[170:173], v163 offset:3072
	ds_read_b128 v[174:177], v164
	ds_read_b128 v[178:181], v164 offset:1024
	ds_read_b128 v[182:185], v164 offset:2048
	ds_read_b128 v[186:189], v164 offset:3072
	s_add_u32 s46, s44, 0xfffc0080
	s_addc_u32 s47, s45, -1
	s_cmp_eq_u32 s65, 12
	s_cselect_b32 s49, s25, s47
	s_cselect_b32 s48, s61, s46
	s_cselect_b32 s47, s37, s64
	s_cselect_b32 s46, s62, s63
	v_lshl_add_u64 v[224:225], s[44:45], 0, v[128:129]
	s_add_i32 m0, s43, 0xc000
	ds_read_b128 v[190:193], v165
	ds_read_b128 v[196:199], v165 offset:1024
	ds_read_b128 v[200:203], v165 offset:2048
	ds_read_b128 v[204:207], v165 offset:3072
	ds_read_b128 v[208:211], v165 offset:4096
	ds_read_b128 v[212:215], v165 offset:5120
	ds_read_b128 v[216:219], v165 offset:6144
	ds_read_b128 v[220:223], v165 offset:7168
	global_load_lds_dwordx4 v[224:225], off
	v_lshl_add_u64 v[224:225], s[44:45], 0, v[130:131]
	s_add_i32 m0, s43, 0xe000
	s_nop 0
	global_load_lds_dwordx4 v[224:225], off
	s_waitcnt vmcnt(8)
	s_waitcnt lgkmcnt(0)
	s_barrier
	s_waitcnt lgkmcnt(0)
	v_mfma_f32_16x16x32_bf16 v[124:127], v[136:139], v[190:193], v[124:127]
	v_mfma_f32_16x16x32_bf16 v[120:123], v[166:169], v[190:193], v[120:123]
	v_mfma_f32_16x16x32_bf16 v[116:119], v[136:139], v[200:203], v[116:119]
	v_mfma_f32_16x16x32_bf16 v[112:115], v[166:169], v[200:203], v[112:115]
	v_mfma_f32_16x16x32_bf16 v[96:99], v[136:139], v[208:211], v[96:99]
	v_mfma_f32_16x16x32_bf16 v[88:91], v[166:169], v[208:211], v[88:91]
	v_mfma_f32_16x16x32_bf16 v[80:83], v[136:139], v[216:219], v[80:83]
	v_mfma_f32_16x16x32_bf16 v[72:75], v[166:169], v[216:219], v[72:75]
	v_mfma_f32_16x16x32_bf16 v[124:127], v[140:143], v[196:199], v[124:127]
	v_mfma_f32_16x16x32_bf16 v[120:123], v[170:173], v[196:199], v[120:123]
	v_mfma_f32_16x16x32_bf16 v[116:119], v[140:143], v[204:207], v[116:119]
	v_mfma_f32_16x16x32_bf16 v[112:115], v[170:173], v[204:207], v[112:115]
	v_mfma_f32_16x16x32_bf16 v[96:99], v[140:143], v[212:215], v[96:99]
	v_mfma_f32_16x16x32_bf16 v[88:91], v[170:173], v[212:215], v[88:91]
	v_mfma_f32_16x16x32_bf16 v[80:83], v[140:143], v[220:223], v[80:83]
	v_mfma_f32_16x16x32_bf16 v[72:75], v[170:173], v[220:223], v[72:75]
	v_mfma_f32_16x16x32_bf16 v[108:111], v[174:177], v[190:193], v[108:111]
	v_mfma_f32_16x16x32_bf16 v[104:107], v[182:185], v[190:193], v[104:107]
	v_mfma_f32_16x16x32_bf16 v[100:103], v[174:177], v[200:203], v[100:103]
	v_mfma_f32_16x16x32_bf16 v[92:95], v[182:185], v[200:203], v[92:95]
	v_mfma_f32_16x16x32_bf16 v[84:87], v[174:177], v[208:211], v[84:87]
	v_mfma_f32_16x16x32_bf16 v[76:79], v[182:185], v[208:211], v[76:79]
	v_mfma_f32_16x16x32_bf16 v[68:71], v[174:177], v[216:219], v[68:71]
	v_mfma_f32_16x16x32_bf16 v[64:67], v[182:185], v[216:219], v[64:67]
	v_mfma_f32_16x16x32_bf16 v[108:111], v[178:181], v[196:199], v[108:111]
	v_mfma_f32_16x16x32_bf16 v[104:107], v[186:189], v[196:199], v[104:107]
	v_mfma_f32_16x16x32_bf16 v[100:103], v[178:181], v[204:207], v[100:103]
	v_mfma_f32_16x16x32_bf16 v[92:95], v[186:189], v[204:207], v[92:95]
	s_setprio 2
	s_barrier
	v_mfma_f32_16x16x32_bf16 v[84:87], v[178:181], v[212:215], v[84:87]
	v_mfma_f32_16x16x32_bf16 v[76:79], v[186:189], v[212:215], v[76:79]
	v_mfma_f32_16x16x32_bf16 v[68:71], v[178:181], v[220:223], v[68:71]
	v_mfma_f32_16x16x32_bf16 v[64:67], v[186:189], v[220:223], v[64:67]
	s_setprio 0
	s_add_i32 s66, s58, s50
	v_lshl_add_u64 v[224:225], s[46:47], 0, v[154:155]
	s_mov_b32 m0, s66
	ds_read_b128 v[190:193], v165 offset:16384
	ds_read_b128 v[196:199], v165 offset:17408
	ds_read_b128 v[200:203], v165 offset:18432
	ds_read_b128 v[204:207], v165 offset:19456
	ds_read_b128 v[208:211], v165 offset:20480
	ds_read_b128 v[212:215], v165 offset:21504
	ds_read_b128 v[216:219], v165 offset:22528
	ds_read_b128 v[220:223], v165 offset:23552
	global_load_lds_dwordx4 v[224:225], off
	s_add_i32 m0, s66, 0x2000
	s_add_u32 s66, s46, 0x40000
	v_lshl_add_u64 v[226:227], s[46:47], 0, v[158:159]
	s_addc_u32 s67, s47, 0
	s_add_i32 s68, s59, s50
	global_load_lds_dwordx4 v[226:227], off
	v_lshl_add_u64 v[228:229], s[66:67], 0, v[154:155]
	s_mov_b32 m0, s68
	v_lshl_add_u64 v[230:231], s[48:49], 0, v[156:157]
	global_load_lds_dwordx4 v[228:229], off
	v_lshl_add_u64 v[228:229], s[66:67], 0, v[158:159]
	s_add_i32 m0, s68, 0x2000
	s_nop 0
	global_load_lds_dwordx4 v[228:229], off
	v_lshl_add_u64 v[228:229], s[48:49], 0, v[152:153]
	s_mov_b32 m0, s43
	s_nop 0
	global_load_lds_dwordx4 v[228:229], off
	s_mov_b32 m0, s51
	s_nop 0
	global_load_lds_dwordx4 v[230:231], off
	s_waitcnt vmcnt(8)
	s_waitcnt lgkmcnt(0)
	s_barrier
; #define PG8_STAGE_T(bufoff, gbase, voff, AUX) do { _Pragma("unroll") for (int _i = 0; _i < 2; ++_i) \
;         __builtin_amdgcn_global_load_lds((const unsigned*)((const char*)(gbase) + (voff)[_i]), (PG8_LAS unsigned*)(lds + (bufoff) + ldsw + _i * 8192), 16, 0, AUX); } while (0)
; #define PG8_LDA(dst, b, h) do { _Pragma("unroll") for (int m = 0; m < 4; ++m) _Pragma("unroll") for (int k = 0; k < 2; ++k) dst[m][k] = *(const PG8_LAS bf16x8*)(lds + PG8_SA(b, h) + aoff + m * 2048 + k * 1024); } while (0)
; #define PG8_LDB(dst, b, h) do { _Pragma("unroll") for (int n = 0; n < 2; ++n) _Pragma("unroll") for (int k = 0; k < 2; ++k) dst[n][k] = *(const PG8_LAS bf16x8*)(lds + PG8_SB(b, h) + boff + n * 2048 + k * 1024); } while (0)
; #define PG8_MMA(ai, bj, At, Bt) do { __builtin_amdgcn_s_setprio(1); _Pragma("unroll") for (int m = 0; m < 4; ++m) _Pragma("unroll") for (int n = 0; n < 2; ++n) _Pragma("unroll") for (int k = 0; k < 2; ++k) \
;         acc[ai][bj][m][n] = __builtin_amdgcn_mfma_f32_16x16x32_bf16(Bt[n][k], At[m][k], acc[ai][bj][m][n], 0, 0, 0); __builtin_amdgcn_s_setprio(0); } while (0)
; #define PG8_WAIT_V(n) asm volatile("s_waitcnt vmcnt(" #n ")" ::: "memory")
; #define PG8_WAIT_L(n) asm volatile("s_waitcnt lgkmcnt(" #n ")" ::: "memory")
; #define PG8_BAR __builtin_amdgcn_s_barrier()
; #define PG8_SCHED __builtin_amdgcn_sched_barrier(0)
;     ...
;             if (!pe) { PG8_WAIT_V(8); } PG8_WAIT_L(0); PG8_BAR; PG8_MMA(1, 0, At, B0); PG8_MMA(1, 1, At, B1); PG8_BAR; PG8_SCHED;
;             PG8_LDB(B0, 1, 0); PG8_LDB(B1, 1, 1); PG8_SCHED; PG8_LDA(At, 1, 0); PG8_STAGE_T(PG8_SA(0, 1), a2 + hstep, voffA, AUX_A);
;             if (!pe) { PG8_WAIT_V(8); } PG8_WAIT_L(0); PG8_BAR; PG8_MMA(0, 0, At, B0); PG8_MMA(0, 1, At, B1); PG8_BAR; PG8_SCHED;
	s_waitcnt lgkmcnt(0)
	v_mfma_f32_16x16x32_bf16 v[60:63], v[136:139], v[190:193], v[60:63]
	v_mfma_f32_16x16x32_bf16 v[56:59], v[166:169], v[190:193], v[56:59]
	v_mfma_f32_16x16x32_bf16 v[48:51], v[136:139], v[200:203], v[48:51]
	v_mfma_f32_16x16x32_bf16 v[40:43], v[166:169], v[200:203], v[40:43]
	v_mfma_f32_16x16x32_bf16 v[32:35], v[136:139], v[208:211], v[32:35]
	v_mfma_f32_16x16x32_bf16 v[24:27], v[166:169], v[208:211], v[24:27]
	v_mfma_f32_16x16x32_bf16 v[16:19], v[136:139], v[216:219], v[16:19]
	v_mfma_f32_16x16x32_bf16 v[8:11], v[166:169], v[216:219], v[8:11]
	v_mfma_f32_16x16x32_bf16 v[60:63], v[140:143], v[196:199], v[60:63]
	v_mfma_f32_16x16x32_bf16 v[56:59], v[170:173], v[196:199], v[56:59]
	v_mfma_f32_16x16x32_bf16 v[48:51], v[140:143], v[204:207], v[48:51]
	v_mfma_f32_16x16x32_bf16 v[40:43], v[170:173], v[204:207], v[40:43]
	v_mfma_f32_16x16x32_bf16 v[32:35], v[140:143], v[212:215], v[32:35]
	v_mfma_f32_16x16x32_bf16 v[24:27], v[170:173], v[212:215], v[24:27]
	v_mfma_f32_16x16x32_bf16 v[16:19], v[140:143], v[220:223], v[16:19]
	v_mfma_f32_16x16x32_bf16 v[8:11], v[170:173], v[220:223], v[8:11]
	v_mfma_f32_16x16x32_bf16 v[52:55], v[174:177], v[190:193], v[52:55]
	v_mfma_f32_16x16x32_bf16 v[44:47], v[182:185], v[190:193], v[44:47]
	v_mfma_f32_16x16x32_bf16 v[36:39], v[174:177], v[200:203], v[36:39]
	v_mfma_f32_16x16x32_bf16 v[28:31], v[182:185], v[200:203], v[28:31]
	v_mfma_f32_16x16x32_bf16 v[20:23], v[174:177], v[208:211], v[20:23]
	v_mfma_f32_16x16x32_bf16 v[12:15], v[182:185], v[208:211], v[12:15]
	v_mfma_f32_16x16x32_bf16 v[4:7], v[174:177], v[216:219], v[4:7]
	v_mfma_f32_16x16x32_bf16 v[0:3], v[182:185], v[216:219], v[0:3]
	v_mfma_f32_16x16x32_bf16 v[52:55], v[178:181], v[196:199], v[52:55]
	v_mfma_f32_16x16x32_bf16 v[44:47], v[186:189], v[196:199], v[44:47]
	v_mfma_f32_16x16x32_bf16 v[36:39], v[178:181], v[204:207], v[36:39]
	v_mfma_f32_16x16x32_bf16 v[28:31], v[186:189], v[204:207], v[28:31]
	s_setprio 2
	s_barrier
	v_mfma_f32_16x16x32_bf16 v[20:23], v[178:181], v[212:215], v[20:23]
	v_mfma_f32_16x16x32_bf16 v[12:15], v[186:189], v[212:215], v[12:15]
	v_mfma_f32_16x16x32_bf16 v[4:7], v[178:181], v[220:223], v[4:7]
	v_mfma_f32_16x16x32_bf16 v[0:3], v[186:189], v[220:223], v[0:3]
	s_setprio 0
	s_add_i32 s66, 0, 0x18000
	s_add_i32 s67, 0, 0x1c000
	v_add_u32_e32 v170, s66, v161
	v_add_u32_e32 v186, s67, v161
	ds_read_b128 v[136:139], v170
	ds_read_b128 v[140:143], v170 offset:1024
	ds_read_b128 v[166:169], v170 offset:2048
	ds_read_b128 v[170:173], v170 offset:3072
	ds_read_b128 v[174:177], v186
	ds_read_b128 v[178:181], v186 offset:1024
	ds_read_b128 v[182:185], v186 offset:2048
	ds_read_b128 v[186:189], v186 offset:3072
	s_add_u32 s48, s48, 0x40000
	s_addc_u32 s49, s49, 0
	s_mov_b32 m0, s52
	v_lshl_add_u64 v[232:233], s[48:49], 0, v[152:153]
	ds_read_b128 v[190:193], v165 offset:32768
	ds_read_b128 v[196:199], v165 offset:33792
	ds_read_b128 v[200:203], v165 offset:34816
	ds_read_b128 v[204:207], v165 offset:35840
	ds_read_b128 v[208:211], v165 offset:36864
	ds_read_b128 v[212:215], v165 offset:37888
	ds_read_b128 v[216:219], v165 offset:38912
	ds_read_b128 v[220:223], v165 offset:39936
	global_load_lds_dwordx4 v[232:233], off
	v_lshl_add_u64 v[232:233], s[48:49], 0, v[156:157]
	s_mov_b32 m0, s53
	s_nop 0
	global_load_lds_dwordx4 v[232:233], off
	s_waitcnt vmcnt(8)
	s_waitcnt lgkmcnt(0)
	s_barrier
	s_waitcnt lgkmcnt(0)
	v_mfma_f32_16x16x32_bf16 v[124:127], v[136:139], v[190:193], v[124:127]
	v_mfma_f32_16x16x32_bf16 v[120:123], v[166:169], v[190:193], v[120:123]
	v_mfma_f32_16x16x32_bf16 v[116:119], v[136:139], v[200:203], v[116:119]
	v_mfma_f32_16x16x32_bf16 v[112:115], v[166:169], v[200:203], v[112:115]
	v_mfma_f32_16x16x32_bf16 v[96:99], v[136:139], v[208:211], v[96:99]
	v_mfma_f32_16x16x32_bf16 v[88:91], v[166:169], v[208:211], v[88:91]
	v_mfma_f32_16x16x32_bf16 v[80:83], v[136:139], v[216:219], v[80:83]
	v_mfma_f32_16x16x32_bf16 v[72:75], v[166:169], v[216:219], v[72:75]
	v_mfma_f32_16x16x32_bf16 v[124:127], v[140:143], v[196:199], v[124:127]
	v_mfma_f32_16x16x32_bf16 v[120:123], v[170:173], v[196:199], v[120:123]
	v_mfma_f32_16x16x32_bf16 v[116:119], v[140:143], v[204:207], v[116:119]
	v_mfma_f32_16x16x32_bf16 v[112:115], v[170:173], v[204:207], v[112:115]
	v_mfma_f32_16x16x32_bf16 v[96:99], v[140:143], v[212:215], v[96:99]
	v_mfma_f32_16x16x32_bf16 v[88:91], v[170:173], v[212:215], v[88:91]
	v_mfma_f32_16x16x32_bf16 v[80:83], v[140:143], v[220:223], v[80:83]
	v_mfma_f32_16x16x32_bf16 v[72:75], v[170:173], v[220:223], v[72:75]
	v_mfma_f32_16x16x32_bf16 v[108:111], v[174:177], v[190:193], v[108:111]
	v_mfma_f32_16x16x32_bf16 v[104:107], v[182:185], v[190:193], v[104:107]
	v_mfma_f32_16x16x32_bf16 v[100:103], v[174:177], v[200:203], v[100:103]
	v_mfma_f32_16x16x32_bf16 v[92:95], v[182:185], v[200:203], v[92:95]
	v_mfma_f32_16x16x32_bf16 v[84:87], v[174:177], v[208:211], v[84:87]
	v_mfma_f32_16x16x32_bf16 v[76:79], v[182:185], v[208:211], v[76:79]
	v_mfma_f32_16x16x32_bf16 v[68:71], v[174:177], v[216:219], v[68:71]
	v_mfma_f32_16x16x32_bf16 v[64:67], v[182:185], v[216:219], v[64:67]
	v_mfma_f32_16x16x32_bf16 v[108:111], v[178:181], v[196:199], v[108:111]
	v_mfma_f32_16x16x32_bf16 v[104:107], v[186:189], v[196:199], v[104:107]
	v_mfma_f32_16x16x32_bf16 v[100:103], v[178:181], v[204:207], v[100:103]
	v_mfma_f32_16x16x32_bf16 v[92:95], v[186:189], v[204:207], v[92:95]
	s_setprio 2
	s_barrier
; #define PG8_STAGE_T(bufoff, gbase, voff, AUX) do { _Pragma("unroll") for (int _i = 0; _i < 2; ++_i) \
;         __builtin_amdgcn_global_load_lds((const unsigned*)((const char*)(gbase) + (voff)[_i]), (PG8_LAS unsigned*)(lds + (bufoff) + ldsw + _i * 8192), 16, 0, AUX); } while (0)
; #define PG8_LDA(dst, b, h) do { _Pragma("unroll") for (int m = 0; m < 4; ++m) _Pragma("unroll") for (int k = 0; k < 2; ++k) dst[m][k] = *(const PG8_LAS bf16x8*)(lds + PG8_SA(b, h) + aoff + m * 2048 + k * 1024); } while (0)
; #define PG8_MMA(ai, bj, At, Bt) do { __builtin_amdgcn_s_setprio(1); _Pragma("unroll") for (int m = 0; m < 4; ++m) _Pragma("unroll") for (int n = 0; n < 2; ++n) _Pragma("unroll") for (int k = 0; k < 2; ++k) \
;         acc[ai][bj][m][n] = __builtin_amdgcn_mfma_f32_16x16x32_bf16(Bt[n][k], At[m][k], acc[ai][bj][m][n], 0, 0, 0); __builtin_amdgcn_s_setprio(0); } while (0)
; #define PG8_WAIT_V(n) asm volatile("s_waitcnt vmcnt(" #n ")" ::: "memory")
; #define PG8_WAIT_L(n) asm volatile("s_waitcnt lgkmcnt(" #n ")" ::: "memory")
; #define PG8_BAR __builtin_amdgcn_s_barrier()
; #define PG8_SCHED __builtin_amdgcn_sched_barrier(0)
;     ...
;             if (!pe) { PG8_WAIT_V(8); } PG8_WAIT_L(0); PG8_BAR; PG8_MMA(0, 0, At, B0); PG8_MMA(0, 1, At, B1); PG8_BAR; PG8_SCHED;
;             PG8_LDA(At, 1, 1); PG8_STAGE_T(PG8_SB(1, 0), b3, voffB, AUX_B); PG8_STAGE_T(PG8_SB(1, 1), b3 + hstep, voffB, AUX_B); PG8_STAGE_T(PG8_SA(1, 0), a3, voffA, AUX_A);
;             PG8_WAIT_V(8); PG8_WAIT_L(0); PG8_BAR; PG8_MMA(1, 0, At, B0); PG8_MMA(1, 1, At, B1); PG8_BAR; PG8_SCHED;
;     ...
;         if constexpr (ALIGN_EPI) { if (wr == 0) PG8_BAR; }
	v_mfma_f32_16x16x32_bf16 v[84:87], v[178:181], v[212:215], v[84:87]
	v_mfma_f32_16x16x32_bf16 v[76:79], v[186:189], v[212:215], v[76:79]
	v_mfma_f32_16x16x32_bf16 v[68:71], v[178:181], v[220:223], v[68:71]
	v_mfma_f32_16x16x32_bf16 v[64:67], v[186:189], v[220:223], v[64:67]
	s_setprio 0
	s_add_i32 s48, s66, s50
	v_lshl_add_u64 v[224:225], v[224:225], 0, s[10:11]
	s_mov_b32 m0, s48
	ds_read_b128 v[190:193], v165 offset:49152
	ds_read_b128 v[196:199], v165 offset:50176
	ds_read_b128 v[200:203], v165 offset:51200
	ds_read_b128 v[204:207], v165 offset:52224
	ds_read_b128 v[208:211], v165 offset:53248
	ds_read_b128 v[212:215], v165 offset:54272
	ds_read_b128 v[216:219], v165 offset:55296
	ds_read_b128 v[220:223], v165 offset:56320
	global_load_lds_dwordx4 v[224:225], off
	s_add_i32 m0, s48, 0x2000
	s_add_u32 s46, s46, 0x40080
	v_lshl_add_u64 v[224:225], v[226:227], 0, s[10:11]
	s_addc_u32 s47, s47, 0
	s_add_i32 s48, s67, s50
	global_load_lds_dwordx4 v[224:225], off
	v_lshl_add_u64 v[224:225], s[46:47], 0, v[154:155]
	s_mov_b32 m0, s48
	s_nop 0
	global_load_lds_dwordx4 v[224:225], off
	v_lshl_add_u64 v[224:225], s[46:47], 0, v[158:159]
	s_add_i32 m0, s48, 0x2000
	s_nop 0
	global_load_lds_dwordx4 v[224:225], off
	v_lshl_add_u64 v[224:225], v[228:229], 0, s[10:11]
	s_mov_b32 m0, s55
	s_nop 0
	global_load_lds_dwordx4 v[224:225], off
	v_lshl_add_u64 v[224:225], v[230:231], 0, s[10:11]
	s_mov_b32 m0, s56
	s_nop 0
	global_load_lds_dwordx4 v[224:225], off
	s_waitcnt vmcnt(8)
	s_waitcnt lgkmcnt(0)
	s_barrier
	s_waitcnt lgkmcnt(0)
	v_mfma_f32_16x16x32_bf16 v[60:63], v[136:139], v[190:193], v[60:63]
	v_mfma_f32_16x16x32_bf16 v[56:59], v[166:169], v[190:193], v[56:59]
	v_mfma_f32_16x16x32_bf16 v[48:51], v[136:139], v[200:203], v[48:51]
	v_mfma_f32_16x16x32_bf16 v[40:43], v[166:169], v[200:203], v[40:43]
	v_mfma_f32_16x16x32_bf16 v[32:35], v[136:139], v[208:211], v[32:35]
	v_mfma_f32_16x16x32_bf16 v[24:27], v[166:169], v[208:211], v[24:27]
	v_mfma_f32_16x16x32_bf16 v[16:19], v[136:139], v[216:219], v[16:19]
	v_mfma_f32_16x16x32_bf16 v[8:11], v[166:169], v[216:219], v[8:11]
	v_mfma_f32_16x16x32_bf16 v[60:63], v[140:143], v[196:199], v[60:63]
	v_mfma_f32_16x16x32_bf16 v[56:59], v[170:173], v[196:199], v[56:59]
	v_mfma_f32_16x16x32_bf16 v[48:51], v[140:143], v[204:207], v[48:51]
	v_mfma_f32_16x16x32_bf16 v[40:43], v[170:173], v[204:207], v[40:43]
	v_mfma_f32_16x16x32_bf16 v[32:35], v[140:143], v[212:215], v[32:35]
	v_mfma_f32_16x16x32_bf16 v[24:27], v[170:173], v[212:215], v[24:27]
	v_mfma_f32_16x16x32_bf16 v[16:19], v[140:143], v[220:223], v[16:19]
	v_mfma_f32_16x16x32_bf16 v[8:11], v[170:173], v[220:223], v[8:11]
	v_mfma_f32_16x16x32_bf16 v[52:55], v[174:177], v[190:193], v[52:55]
	v_mfma_f32_16x16x32_bf16 v[44:47], v[182:185], v[190:193], v[44:47]
	v_mfma_f32_16x16x32_bf16 v[36:39], v[174:177], v[200:203], v[36:39]
	v_mfma_f32_16x16x32_bf16 v[28:31], v[182:185], v[200:203], v[28:31]
	v_mfma_f32_16x16x32_bf16 v[20:23], v[174:177], v[208:211], v[20:23]
	v_mfma_f32_16x16x32_bf16 v[12:15], v[182:185], v[208:211], v[12:15]
	v_mfma_f32_16x16x32_bf16 v[4:7], v[174:177], v[216:219], v[4:7]
	v_mfma_f32_16x16x32_bf16 v[0:3], v[182:185], v[216:219], v[0:3]
	v_mfma_f32_16x16x32_bf16 v[52:55], v[178:181], v[196:199], v[52:55]
	v_mfma_f32_16x16x32_bf16 v[44:47], v[186:189], v[196:199], v[44:47]
	v_mfma_f32_16x16x32_bf16 v[36:39], v[178:181], v[204:207], v[36:39]
	v_mfma_f32_16x16x32_bf16 v[28:31], v[186:189], v[204:207], v[28:31]
	s_setprio 2
	s_barrier
	v_mfma_f32_16x16x32_bf16 v[20:23], v[178:181], v[212:215], v[20:23]
	v_mfma_f32_16x16x32_bf16 v[12:15], v[186:189], v[212:215], v[12:15]
	v_mfma_f32_16x16x32_bf16 v[4:7], v[178:181], v[220:223], v[4:7]
	v_mfma_f32_16x16x32_bf16 v[0:3], v[186:189], v[220:223], v[0:3]
	s_setprio 0
	s_add_i32 s65, s65, 2
	s_add_u32 s44, s44, 0x100
	s_addc_u32 s45, s45, 0
	s_add_u32 s63, s63, 0x100
	s_addc_u32 s64, s64, 0
	s_cmp_gt_u32 s65, 13
	s_cbranch_scc0 .LBB0_787
	s_and_b64 vcc, exec, s[12:13]
	s_cbranch_vccz .LBB0_790
	s_barrier

; #define PG8_STAGE_T(bufoff, gbase, voff, AUX) do { _Pragma("unroll") for (int _i = 0; _i < 2; ++_i) \
;         __builtin_amdgcn_global_load_lds((const unsigned*)((const char*)(gbase) + (voff)[_i]), (PG8_LAS unsigned*)(lds + (bufoff) + ldsw + _i * 8192), 16, 0, AUX); } while (0)
; #define PG8_LDA(dst, b, h) do { _Pragma("unroll") for (int m = 0; m < 4; ++m) _Pragma("unroll") for (int k = 0; k < 2; ++k) dst[m][k] = *(const PG8_LAS bf16x8*)(lds + PG8_SA(b, h) + aoff + m * 2048 + k * 1024); } while (0)
; #define PG8_LDB(dst, b, h) do { _Pragma("unroll") for (int n = 0; n < 2; ++n) _Pragma("unroll") for (int k = 0; k < 2; ++k) dst[n][k] = *(const PG8_LAS bf16x8*)(lds + PG8_SB(b, h) + boff + n * 2048 + k * 1024); } while (0)
; #define PG8_MMA(ai, bj, At, Bt) do { __builtin_amdgcn_s_setprio(1); _Pragma("unroll") for (int m = 0; m < 4; ++m) _Pragma("unroll") for (int n = 0; n < 2; ++n) _Pragma("unroll") for (int k = 0; k < 2; ++k) \
;         acc[ai][bj][m][n] = __builtin_amdgcn_mfma_f32_16x16x32_bf16(Bt[n][k], At[m][k], acc[ai][bj][m][n], 0, 0, 0); __builtin_amdgcn_s_setprio(0); } while (0)
; #define PG8_WAIT_V(n) asm volatile("s_waitcnt vmcnt(" #n ")" ::: "memory")
; #define PG8_WAIT_L(n) asm volatile("s_waitcnt lgkmcnt(" #n ")" ::: "memory")
; #define PG8_BAR __builtin_amdgcn_s_barrier()
;     ...
;             const bool last = (t == nt - 2);
;             const char* a1 = cA + (ptrdiff_t)(t + 1) * ck;
;             const char* a2 = last ? nA : cA + (ptrdiff_t)(t + 2) * ck; const char* b2 = last ? nB : cB + (ptrdiff_t)(t + 2) * ck;
;             const ptrdiff_t k3 = last ? nk : ck;
;             const char* a3 = a2 + k3; const char* b3 = b2 + k3;
;             if (last && has_next) S.a_ready(nxt);
;             if constexpr (SP2) {
;             int pei = 0; if constexpr (PEEL) { pei = __builtin_amdgcn_readfirstlane((t == 0 && ui > 0) ? 1 : 0); asm volatile("" : "+s"(pei)); }
;             const bool pe = pei != 0;
;             PG8_LDB(B0, 0, 0); PG8_LDB(B1, 0, 1); PG8_SCHED; PG8_LDA(At, 0, 0); if (!pe) { PG8_STAGE_T(PG8_SA(1, 1), a1 + hstep, voffA, AUX_A); }
;             if (!pe) { PG8_WAIT_V(8); } PG8_WAIT_L(0); PG8_BAR; PG8_MMA(0, 0, At, B0); PG8_MMA(0, 1, At, B1); PG8_BAR; PG8_SCHED;
;             PG8_LDA(At, 0, 1); PG8_STAGE_T(PG8_SB(0, 0), b2, voffB, AUX_B); PG8_STAGE_T(PG8_SB(0, 1), b2 + hstep, voffB, AUX_B); PG8_STAGE_T(PG8_SA(0, 0), a2, voffA, AUX_A);
.LBB0_811:
	ds_read_b128 v[128:131], v183
	ds_read_b128 v[132:135], v183 offset:1024
	ds_read_b128 v[136:139], v183 offset:2048
	ds_read_b128 v[140:143], v183 offset:3072
	ds_read_b128 v[144:147], v184
	ds_read_b128 v[148:151], v184 offset:1024
	ds_read_b128 v[168:171], v184 offset:2048
	ds_read_b128 v[172:175], v184 offset:3072
	s_add_u32 s48, s46, 0xfffc0080
	s_addc_u32 s49, s47, -1
	s_cmp_eq_u32 s67, 12
	s_cselect_b32 s51, s37, s49
	s_cselect_b32 s50, s63, s48
	s_cselect_b32 s49, s39, s66
	s_cselect_b32 s48, s64, s65
	v_lshl_add_u64 v[216:217], s[46:47], 0, v[160:161]
	s_add_i32 m0, s45, 0xc000
	ds_read_b128 v[176:179], v185
	ds_read_b128 v[186:189], v185 offset:1024
	ds_read_b128 v[190:193], v185 offset:2048
	ds_read_b128 v[196:199], v185 offset:3072
	ds_read_b128 v[200:203], v185 offset:4096
	ds_read_b128 v[204:207], v185 offset:5120
	ds_read_b128 v[208:211], v185 offset:6144
	ds_read_b128 v[212:215], v185 offset:7168
	global_load_lds_dwordx4 v[216:217], off
	v_lshl_add_u64 v[216:217], s[46:47], 0, v[162:163]
	s_add_i32 m0, s45, 0xe000
	s_nop 0
	global_load_lds_dwordx4 v[216:217], off
	s_waitcnt vmcnt(8)
	s_waitcnt lgkmcnt(0)
	s_barrier
	s_waitcnt lgkmcnt(0)
	v_mfma_f32_16x16x32_bf16 v[124:127], v[128:131], v[176:179], v[124:127]
	v_mfma_f32_16x16x32_bf16 v[120:123], v[136:139], v[176:179], v[120:123]
	v_mfma_f32_16x16x32_bf16 v[108:111], v[128:131], v[190:193], v[108:111]
	v_mfma_f32_16x16x32_bf16 v[104:107], v[136:139], v[190:193], v[104:107]
	v_mfma_f32_16x16x32_bf16 v[92:95], v[128:131], v[200:203], v[92:95]
	v_mfma_f32_16x16x32_bf16 v[88:91], v[136:139], v[200:203], v[88:91]
	v_mfma_f32_16x16x32_bf16 v[76:79], v[128:131], v[208:211], v[76:79]
	v_mfma_f32_16x16x32_bf16 v[72:75], v[136:139], v[208:211], v[72:75]
	v_mfma_f32_16x16x32_bf16 v[124:127], v[132:135], v[186:189], v[124:127]
	v_mfma_f32_16x16x32_bf16 v[120:123], v[140:143], v[186:189], v[120:123]
	v_mfma_f32_16x16x32_bf16 v[108:111], v[132:135], v[196:199], v[108:111]
	v_mfma_f32_16x16x32_bf16 v[104:107], v[140:143], v[196:199], v[104:107]
	v_mfma_f32_16x16x32_bf16 v[92:95], v[132:135], v[204:207], v[92:95]
	v_mfma_f32_16x16x32_bf16 v[88:91], v[140:143], v[204:207], v[88:91]
	v_mfma_f32_16x16x32_bf16 v[76:79], v[132:135], v[212:215], v[76:79]
	v_mfma_f32_16x16x32_bf16 v[72:75], v[140:143], v[212:215], v[72:75]
	v_mfma_f32_16x16x32_bf16 v[116:119], v[144:147], v[176:179], v[116:119]
	v_mfma_f32_16x16x32_bf16 v[112:115], v[168:171], v[176:179], v[112:115]
	v_mfma_f32_16x16x32_bf16 v[100:103], v[144:147], v[190:193], v[100:103]
	v_mfma_f32_16x16x32_bf16 v[96:99], v[168:171], v[190:193], v[96:99]
	v_mfma_f32_16x16x32_bf16 v[84:87], v[144:147], v[200:203], v[84:87]
	v_mfma_f32_16x16x32_bf16 v[80:83], v[168:171], v[200:203], v[80:83]
	v_mfma_f32_16x16x32_bf16 v[68:71], v[144:147], v[208:211], v[68:71]
	v_mfma_f32_16x16x32_bf16 v[64:67], v[168:171], v[208:211], v[64:67]
	v_mfma_f32_16x16x32_bf16 v[116:119], v[148:151], v[186:189], v[116:119]
	v_mfma_f32_16x16x32_bf16 v[112:115], v[172:175], v[186:189], v[112:115]
	v_mfma_f32_16x16x32_bf16 v[100:103], v[148:151], v[196:199], v[100:103]
	v_mfma_f32_16x16x32_bf16 v[96:99], v[172:175], v[196:199], v[96:99]
	s_setprio 2
	s_barrier
	v_mfma_f32_16x16x32_bf16 v[84:87], v[148:151], v[204:207], v[84:87]
	v_mfma_f32_16x16x32_bf16 v[80:83], v[172:175], v[204:207], v[80:83]
	v_mfma_f32_16x16x32_bf16 v[68:71], v[148:151], v[212:215], v[68:71]
	v_mfma_f32_16x16x32_bf16 v[64:67], v[172:175], v[212:215], v[64:67]
	s_setprio 0
	s_add_i32 s68, s60, s52
	v_lshl_add_u64 v[216:217], s[48:49], 0, v[154:155]
	s_mov_b32 m0, s68
	ds_read_b128 v[176:179], v185 offset:16384
	ds_read_b128 v[186:189], v185 offset:17408
	ds_read_b128 v[190:193], v185 offset:18432
	ds_read_b128 v[196:199], v185 offset:19456
	ds_read_b128 v[200:203], v185 offset:20480
	ds_read_b128 v[204:207], v185 offset:21504
	ds_read_b128 v[208:211], v185 offset:22528
	ds_read_b128 v[212:215], v185 offset:23552
	global_load_lds_dwordx4 v[216:217], off
	s_add_i32 m0, s68, 0x2000
	s_add_u32 s68, s48, 0x40000
	v_lshl_add_u64 v[218:219], s[48:49], 0, v[158:159]
	s_addc_u32 s69, s49, 0
	s_add_i32 s70, s61, s52
	global_load_lds_dwordx4 v[218:219], off
	v_lshl_add_u64 v[220:221], s[68:69], 0, v[154:155]
	s_mov_b32 m0, s70
	v_lshl_add_u64 v[222:223], s[50:51], 0, v[156:157]
	global_load_lds_dwordx4 v[220:221], off
	v_lshl_add_u64 v[220:221], s[68:69], 0, v[158:159]
	s_add_i32 m0, s70, 0x2000
	s_nop 0
	global_load_lds_dwordx4 v[220:221], off
	v_lshl_add_u64 v[220:221], s[50:51], 0, v[152:153]
	s_mov_b32 m0, s45
	s_nop 0
	global_load_lds_dwordx4 v[220:221], off
	s_mov_b32 m0, s53
	s_nop 0
	global_load_lds_dwordx4 v[222:223], off
	s_waitcnt vmcnt(8)
	s_waitcnt lgkmcnt(0)
	s_barrier
; #define PG8_STAGE_T(bufoff, gbase, voff, AUX) do { _Pragma("unroll") for (int _i = 0; _i < 2; ++_i) \
;         __builtin_amdgcn_global_load_lds((const unsigned*)((const char*)(gbase) + (voff)[_i]), (PG8_LAS unsigned*)(lds + (bufoff) + ldsw + _i * 8192), 16, 0, AUX); } while (0)
; #define PG8_LDA(dst, b, h) do { _Pragma("unroll") for (int m = 0; m < 4; ++m) _Pragma("unroll") for (int k = 0; k < 2; ++k) dst[m][k] = *(const PG8_LAS bf16x8*)(lds + PG8_SA(b, h) + aoff + m * 2048 + k * 1024); } while (0)
; #define PG8_LDB(dst, b, h) do { _Pragma("unroll") for (int n = 0; n < 2; ++n) _Pragma("unroll") for (int k = 0; k < 2; ++k) dst[n][k] = *(const PG8_LAS bf16x8*)(lds + PG8_SB(b, h) + boff + n * 2048 + k * 1024); } while (0)
; #define PG8_MMA(ai, bj, At, Bt) do { __builtin_amdgcn_s_setprio(1); _Pragma("unroll") for (int m = 0; m < 4; ++m) _Pragma("unroll") for (int n = 0; n < 2; ++n) _Pragma("unroll") for (int k = 0; k < 2; ++k) \
;         acc[ai][bj][m][n] = __builtin_amdgcn_mfma_f32_16x16x32_bf16(Bt[n][k], At[m][k], acc[ai][bj][m][n], 0, 0, 0); __builtin_amdgcn_s_setprio(0); } while (0)
; #define PG8_WAIT_V(n) asm volatile("s_waitcnt vmcnt(" #n ")" ::: "memory")
; #define PG8_WAIT_L(n) asm volatile("s_waitcnt lgkmcnt(" #n ")" ::: "memory")
; #define PG8_BAR __builtin_amdgcn_s_barrier()
; #define PG8_SCHED __builtin_amdgcn_sched_barrier(0)
;     ...
;             if (!pe) { PG8_WAIT_V(8); } PG8_WAIT_L(0); PG8_BAR; PG8_MMA(1, 0, At, B0); PG8_MMA(1, 1, At, B1); PG8_BAR; PG8_SCHED;
;             PG8_LDB(B0, 1, 0); PG8_LDB(B1, 1, 1); PG8_SCHED; PG8_LDA(At, 1, 0); PG8_STAGE_T(PG8_SA(0, 1), a2 + hstep, voffA, AUX_A);
;             if (!pe) { PG8_WAIT_V(8); } PG8_WAIT_L(0); PG8_BAR; PG8_MMA(0, 0, At, B0); PG8_MMA(0, 1, At, B1); PG8_BAR; PG8_SCHED;
	s_waitcnt lgkmcnt(0)
	v_mfma_f32_16x16x32_bf16 v[60:63], v[128:131], v[176:179], v[60:63]
	v_mfma_f32_16x16x32_bf16 v[56:59], v[136:139], v[176:179], v[56:59]
	v_mfma_f32_16x16x32_bf16 v[44:47], v[128:131], v[190:193], v[44:47]
	v_mfma_f32_16x16x32_bf16 v[40:43], v[136:139], v[190:193], v[40:43]
	v_mfma_f32_16x16x32_bf16 v[28:31], v[128:131], v[200:203], v[28:31]
	v_mfma_f32_16x16x32_bf16 v[24:27], v[136:139], v[200:203], v[24:27]
	v_mfma_f32_16x16x32_bf16 v[12:15], v[128:131], v[208:211], v[12:15]
	v_mfma_f32_16x16x32_bf16 v[8:11], v[136:139], v[208:211], v[8:11]
	v_mfma_f32_16x16x32_bf16 v[60:63], v[132:135], v[186:189], v[60:63]
	v_mfma_f32_16x16x32_bf16 v[56:59], v[140:143], v[186:189], v[56:59]
	v_mfma_f32_16x16x32_bf16 v[44:47], v[132:135], v[196:199], v[44:47]
	v_mfma_f32_16x16x32_bf16 v[40:43], v[140:143], v[196:199], v[40:43]
	v_mfma_f32_16x16x32_bf16 v[28:31], v[132:135], v[204:207], v[28:31]
	v_mfma_f32_16x16x32_bf16 v[24:27], v[140:143], v[204:207], v[24:27]
	v_mfma_f32_16x16x32_bf16 v[12:15], v[132:135], v[212:215], v[12:15]
	v_mfma_f32_16x16x32_bf16 v[8:11], v[140:143], v[212:215], v[8:11]
	v_mfma_f32_16x16x32_bf16 v[52:55], v[144:147], v[176:179], v[52:55]
	v_mfma_f32_16x16x32_bf16 v[48:51], v[168:171], v[176:179], v[48:51]
	v_mfma_f32_16x16x32_bf16 v[36:39], v[144:147], v[190:193], v[36:39]
	v_mfma_f32_16x16x32_bf16 v[32:35], v[168:171], v[190:193], v[32:35]
	v_mfma_f32_16x16x32_bf16 v[20:23], v[144:147], v[200:203], v[20:23]
	v_mfma_f32_16x16x32_bf16 v[16:19], v[168:171], v[200:203], v[16:19]
	v_mfma_f32_16x16x32_bf16 v[4:7], v[144:147], v[208:211], v[4:7]
	v_mfma_f32_16x16x32_bf16 v[0:3], v[168:171], v[208:211], v[0:3]
	v_mfma_f32_16x16x32_bf16 v[52:55], v[148:151], v[186:189], v[52:55]
	v_mfma_f32_16x16x32_bf16 v[48:51], v[172:175], v[186:189], v[48:51]
	v_mfma_f32_16x16x32_bf16 v[36:39], v[148:151], v[196:199], v[36:39]
	v_mfma_f32_16x16x32_bf16 v[32:35], v[172:175], v[196:199], v[32:35]
	s_setprio 2
	s_barrier
	v_mfma_f32_16x16x32_bf16 v[20:23], v[148:151], v[204:207], v[20:23]
	v_mfma_f32_16x16x32_bf16 v[16:19], v[172:175], v[204:207], v[16:19]
	v_mfma_f32_16x16x32_bf16 v[4:7], v[148:151], v[212:215], v[4:7]
	v_mfma_f32_16x16x32_bf16 v[0:3], v[172:175], v[212:215], v[0:3]
	s_setprio 0
	s_add_i32 s68, 0, 0x18000
	s_add_i32 s69, 0, 0x1c000
	v_add_u32_e32 v140, s68, v181
	v_add_u32_e32 v172, s69, v181
	ds_read_b128 v[128:131], v140
	ds_read_b128 v[132:135], v140 offset:1024
	ds_read_b128 v[136:139], v140 offset:2048
	ds_read_b128 v[140:143], v140 offset:3072
	ds_read_b128 v[144:147], v172
	ds_read_b128 v[148:151], v172 offset:1024
	ds_read_b128 v[168:171], v172 offset:2048
	ds_read_b128 v[172:175], v172 offset:3072
	s_add_u32 s50, s50, 0x40000
	s_addc_u32 s51, s51, 0
	s_mov_b32 m0, s54
	v_lshl_add_u64 v[224:225], s[50:51], 0, v[152:153]
	ds_read_b128 v[176:179], v185 offset:32768
	ds_read_b128 v[186:189], v185 offset:33792
	ds_read_b128 v[190:193], v185 offset:34816
	ds_read_b128 v[196:199], v185 offset:35840
	ds_read_b128 v[200:203], v185 offset:36864
	ds_read_b128 v[204:207], v185 offset:37888
	ds_read_b128 v[208:211], v185 offset:38912
	ds_read_b128 v[212:215], v185 offset:39936
	global_load_lds_dwordx4 v[224:225], off
	v_lshl_add_u64 v[224:225], s[50:51], 0, v[156:157]
	s_mov_b32 m0, s55
	s_nop 0
	global_load_lds_dwordx4 v[224:225], off
	s_waitcnt vmcnt(8)
	s_waitcnt lgkmcnt(0)
	s_barrier
	s_waitcnt lgkmcnt(0)
	v_mfma_f32_16x16x32_bf16 v[124:127], v[128:131], v[176:179], v[124:127]
	v_mfma_f32_16x16x32_bf16 v[120:123], v[136:139], v[176:179], v[120:123]
	v_mfma_f32_16x16x32_bf16 v[108:111], v[128:131], v[190:193], v[108:111]
	v_mfma_f32_16x16x32_bf16 v[104:107], v[136:139], v[190:193], v[104:107]
	v_mfma_f32_16x16x32_bf16 v[92:95], v[128:131], v[200:203], v[92:95]
	v_mfma_f32_16x16x32_bf16 v[88:91], v[136:139], v[200:203], v[88:91]
	v_mfma_f32_16x16x32_bf16 v[76:79], v[128:131], v[208:211], v[76:79]
	v_mfma_f32_16x16x32_bf16 v[72:75], v[136:139], v[208:211], v[72:75]
	v_mfma_f32_16x16x32_bf16 v[124:127], v[132:135], v[186:189], v[124:127]
	v_mfma_f32_16x16x32_bf16 v[120:123], v[140:143], v[186:189], v[120:123]
	v_mfma_f32_16x16x32_bf16 v[108:111], v[132:135], v[196:199], v[108:111]
	v_mfma_f32_16x16x32_bf16 v[104:107], v[140:143], v[196:199], v[104:107]
	v_mfma_f32_16x16x32_bf16 v[92:95], v[132:135], v[204:207], v[92:95]
	v_mfma_f32_16x16x32_bf16 v[88:91], v[140:143], v[204:207], v[88:91]
	v_mfma_f32_16x16x32_bf16 v[76:79], v[132:135], v[212:215], v[76:79]
	v_mfma_f32_16x16x32_bf16 v[72:75], v[140:143], v[212:215], v[72:75]
	v_mfma_f32_16x16x32_bf16 v[116:119], v[144:147], v[176:179], v[116:119]
	v_mfma_f32_16x16x32_bf16 v[112:115], v[168:171], v[176:179], v[112:115]
	v_mfma_f32_16x16x32_bf16 v[100:103], v[144:147], v[190:193], v[100:103]
	v_mfma_f32_16x16x32_bf16 v[96:99], v[168:171], v[190:193], v[96:99]
	v_mfma_f32_16x16x32_bf16 v[84:87], v[144:147], v[200:203], v[84:87]
	v_mfma_f32_16x16x32_bf16 v[80:83], v[168:171], v[200:203], v[80:83]
	v_mfma_f32_16x16x32_bf16 v[68:71], v[144:147], v[208:211], v[68:71]
	v_mfma_f32_16x16x32_bf16 v[64:67], v[168:171], v[208:211], v[64:67]
	v_mfma_f32_16x16x32_bf16 v[116:119], v[148:151], v[186:189], v[116:119]
	v_mfma_f32_16x16x32_bf16 v[112:115], v[172:175], v[186:189], v[112:115]
	v_mfma_f32_16x16x32_bf16 v[100:103], v[148:151], v[196:199], v[100:103]
	v_mfma_f32_16x16x32_bf16 v[96:99], v[172:175], v[196:199], v[96:99]
	s_setprio 2
	s_barrier
; #define PG8_STAGE_T(bufoff, gbase, voff, AUX) do { _Pragma("unroll") for (int _i = 0; _i < 2; ++_i) \
;         __builtin_amdgcn_global_load_lds((const unsigned*)((const char*)(gbase) + (voff)[_i]), (PG8_LAS unsigned*)(lds + (bufoff) + ldsw + _i * 8192), 16, 0, AUX); } while (0)
; #define PG8_LDA(dst, b, h) do { _Pragma("unroll") for (int m = 0; m < 4; ++m) _Pragma("unroll") for (int k = 0; k < 2; ++k) dst[m][k] = *(const PG8_LAS bf16x8*)(lds + PG8_SA(b, h) + aoff + m * 2048 + k * 1024); } while (0)
; #define PG8_MMA(ai, bj, At, Bt) do { __builtin_amdgcn_s_setprio(1); _Pragma("unroll") for (int m = 0; m < 4; ++m) _Pragma("unroll") for (int n = 0; n < 2; ++n) _Pragma("unroll") for (int k = 0; k < 2; ++k) \
;         acc[ai][bj][m][n] = __builtin_amdgcn_mfma_f32_16x16x32_bf16(Bt[n][k], At[m][k], acc[ai][bj][m][n], 0, 0, 0); __builtin_amdgcn_s_setprio(0); } while (0)
; #define PG8_WAIT_V(n) asm volatile("s_waitcnt vmcnt(" #n ")" ::: "memory")
; #define PG8_WAIT_L(n) asm volatile("s_waitcnt lgkmcnt(" #n ")" ::: "memory")
; #define PG8_BAR __builtin_amdgcn_s_barrier()
; #define PG8_SCHED __builtin_amdgcn_sched_barrier(0)
;     ...
;             if (!pe) { PG8_WAIT_V(8); } PG8_WAIT_L(0); PG8_BAR; PG8_MMA(0, 0, At, B0); PG8_MMA(0, 1, At, B1); PG8_BAR; PG8_SCHED;
;             PG8_LDA(At, 1, 1); PG8_STAGE_T(PG8_SB(1, 0), b3, voffB, AUX_B); PG8_STAGE_T(PG8_SB(1, 1), b3 + hstep, voffB, AUX_B); PG8_STAGE_T(PG8_SA(1, 0), a3, voffA, AUX_A);
;             PG8_WAIT_V(8); PG8_WAIT_L(0); PG8_BAR; PG8_MMA(1, 0, At, B0); PG8_MMA(1, 1, At, B1); PG8_BAR; PG8_SCHED;
;     ...
;         if constexpr (ALIGN_EPI) { if (wr == 0) PG8_BAR; }
	v_mfma_f32_16x16x32_bf16 v[84:87], v[148:151], v[204:207], v[84:87]
	v_mfma_f32_16x16x32_bf16 v[80:83], v[172:175], v[204:207], v[80:83]
	v_mfma_f32_16x16x32_bf16 v[68:71], v[148:151], v[212:215], v[68:71]
	v_mfma_f32_16x16x32_bf16 v[64:67], v[172:175], v[212:215], v[64:67]
	s_setprio 0
	s_add_i32 s50, s68, s52
	v_lshl_add_u64 v[216:217], v[216:217], 0, s[10:11]
	s_mov_b32 m0, s50
	ds_read_b128 v[176:179], v185 offset:49152
	ds_read_b128 v[186:189], v185 offset:50176
	ds_read_b128 v[190:193], v185 offset:51200
	ds_read_b128 v[196:199], v185 offset:52224
	ds_read_b128 v[200:203], v185 offset:53248
	ds_read_b128 v[204:207], v185 offset:54272
	ds_read_b128 v[208:211], v185 offset:55296
	ds_read_b128 v[212:215], v185 offset:56320
	global_load_lds_dwordx4 v[216:217], off
	s_add_i32 m0, s50, 0x2000
	s_add_u32 s48, s48, 0x40080
	v_lshl_add_u64 v[216:217], v[218:219], 0, s[10:11]
	s_addc_u32 s49, s49, 0
	s_add_i32 s50, s69, s52
	global_load_lds_dwordx4 v[216:217], off
	v_lshl_add_u64 v[216:217], s[48:49], 0, v[154:155]
	s_mov_b32 m0, s50
	s_nop 0
	global_load_lds_dwordx4 v[216:217], off
	v_lshl_add_u64 v[216:217], s[48:49], 0, v[158:159]
	s_add_i32 m0, s50, 0x2000
	s_nop 0
	global_load_lds_dwordx4 v[216:217], off
	v_lshl_add_u64 v[216:217], v[220:221], 0, s[10:11]
	s_mov_b32 m0, s57
	s_nop 0
	global_load_lds_dwordx4 v[216:217], off
	v_lshl_add_u64 v[216:217], v[222:223], 0, s[10:11]
	s_mov_b32 m0, s58
	s_nop 0
	global_load_lds_dwordx4 v[216:217], off
	s_waitcnt vmcnt(8)
	s_waitcnt lgkmcnt(0)
	s_barrier
	s_waitcnt lgkmcnt(0)
	v_mfma_f32_16x16x32_bf16 v[60:63], v[128:131], v[176:179], v[60:63]
	v_mfma_f32_16x16x32_bf16 v[56:59], v[136:139], v[176:179], v[56:59]
	v_mfma_f32_16x16x32_bf16 v[44:47], v[128:131], v[190:193], v[44:47]
	v_mfma_f32_16x16x32_bf16 v[40:43], v[136:139], v[190:193], v[40:43]
	v_mfma_f32_16x16x32_bf16 v[28:31], v[128:131], v[200:203], v[28:31]
	v_mfma_f32_16x16x32_bf16 v[24:27], v[136:139], v[200:203], v[24:27]
	v_mfma_f32_16x16x32_bf16 v[12:15], v[128:131], v[208:211], v[12:15]
	v_mfma_f32_16x16x32_bf16 v[8:11], v[136:139], v[208:211], v[8:11]
	v_mfma_f32_16x16x32_bf16 v[60:63], v[132:135], v[186:189], v[60:63]
	v_mfma_f32_16x16x32_bf16 v[56:59], v[140:143], v[186:189], v[56:59]
	v_mfma_f32_16x16x32_bf16 v[44:47], v[132:135], v[196:199], v[44:47]
	v_mfma_f32_16x16x32_bf16 v[40:43], v[140:143], v[196:199], v[40:43]
	v_mfma_f32_16x16x32_bf16 v[28:31], v[132:135], v[204:207], v[28:31]
	v_mfma_f32_16x16x32_bf16 v[24:27], v[140:143], v[204:207], v[24:27]
	v_mfma_f32_16x16x32_bf16 v[12:15], v[132:135], v[212:215], v[12:15]
	v_mfma_f32_16x16x32_bf16 v[8:11], v[140:143], v[212:215], v[8:11]
	v_mfma_f32_16x16x32_bf16 v[52:55], v[144:147], v[176:179], v[52:55]
	v_mfma_f32_16x16x32_bf16 v[48:51], v[168:171], v[176:179], v[48:51]
	v_mfma_f32_16x16x32_bf16 v[36:39], v[144:147], v[190:193], v[36:39]
	v_mfma_f32_16x16x32_bf16 v[32:35], v[168:171], v[190:193], v[32:35]
	v_mfma_f32_16x16x32_bf16 v[20:23], v[144:147], v[200:203], v[20:23]
	v_mfma_f32_16x16x32_bf16 v[16:19], v[168:171], v[200:203], v[16:19]
	v_mfma_f32_16x16x32_bf16 v[4:7], v[144:147], v[208:211], v[4:7]
	v_mfma_f32_16x16x32_bf16 v[0:3], v[168:171], v[208:211], v[0:3]
	v_mfma_f32_16x16x32_bf16 v[52:55], v[148:151], v[186:189], v[52:55]
	v_mfma_f32_16x16x32_bf16 v[48:51], v[172:175], v[186:189], v[48:51]
	v_mfma_f32_16x16x32_bf16 v[36:39], v[148:151], v[196:199], v[36:39]
	v_mfma_f32_16x16x32_bf16 v[32:35], v[172:175], v[196:199], v[32:35]
	s_setprio 2
	s_barrier
	v_mfma_f32_16x16x32_bf16 v[20:23], v[148:151], v[204:207], v[20:23]
	v_mfma_f32_16x16x32_bf16 v[16:19], v[172:175], v[204:207], v[16:19]
	v_mfma_f32_16x16x32_bf16 v[4:7], v[148:151], v[212:215], v[4:7]
	v_mfma_f32_16x16x32_bf16 v[0:3], v[172:175], v[212:215], v[0:3]
	s_setprio 0
	s_add_i32 s67, s67, 2
	s_add_u32 s46, s46, 0x100
	s_addc_u32 s47, s47, 0
	s_add_u32 s65, s65, 0x100
	s_addc_u32 s66, s66, 0
	s_cmp_gt_u32 s67, 13
	s_cbranch_scc0 .LBB0_811
	s_and_b64 vcc, exec, s[12:13]
	s_cbranch_vccz .LBB0_814
	s_barrier

; #define PG8_STAGE_T(bufoff, gbase, voff, AUX) do { _Pragma("unroll") for (int _i = 0; _i < 2; ++_i) \
;         __builtin_amdgcn_global_load_lds((const unsigned*)((const char*)(gbase) + (voff)[_i]), (PG8_LAS unsigned*)(lds + (bufoff) + ldsw + _i * 8192), 16, 0, AUX); } while (0)
; #define PG8_LDA(dst, b, h) do { _Pragma("unroll") for (int m = 0; m < 4; ++m) _Pragma("unroll") for (int k = 0; k < 2; ++k) dst[m][k] = *(const PG8_LAS bf16x8*)(lds + PG8_SA(b, h) + aoff + m * 2048 + k * 1024); } while (0)
; #define PG8_LDB(dst, b, h) do { _Pragma("unroll") for (int n = 0; n < 2; ++n) _Pragma("unroll") for (int k = 0; k < 2; ++k) dst[n][k] = *(const PG8_LAS bf16x8*)(lds + PG8_SB(b, h) + boff + n * 2048 + k * 1024); } while (0)
; #define PG8_MMA(ai, bj, At, Bt) do { __builtin_amdgcn_s_setprio(1); _Pragma("unroll") for (int m = 0; m < 4; ++m) _Pragma("unroll") for (int n = 0; n < 2; ++n) _Pragma("unroll") for (int k = 0; k < 2; ++k) \
;         acc[ai][bj][m][n] = __builtin_amdgcn_mfma_f32_16x16x32_bf16(Bt[n][k], At[m][k], acc[ai][bj][m][n], 0, 0, 0); __builtin_amdgcn_s_setprio(0); } while (0)
; #define PG8_WAIT_V(n) asm volatile("s_waitcnt vmcnt(" #n ")" ::: "memory")
; #define PG8_WAIT_L(n) asm volatile("s_waitcnt lgkmcnt(" #n ")" ::: "memory")
; #define PG8_BAR __builtin_amdgcn_s_barrier()
;     ...
;             const bool last = (t == nt - 2);
;             const char* a1 = cA + (ptrdiff_t)(t + 1) * ck;
;             const char* a2 = last ? nA : cA + (ptrdiff_t)(t + 2) * ck; const char* b2 = last ? nB : cB + (ptrdiff_t)(t + 2) * ck;
;             const ptrdiff_t k3 = last ? nk : ck;
;             const char* a3 = a2 + k3; const char* b3 = b2 + k3;
;             if (last && has_next) S.a_ready(nxt);
;             if constexpr (SP2) {
;             int pei = 0; if constexpr (PEEL) { pei = __builtin_amdgcn_readfirstlane((t == 0 && ui > 0) ? 1 : 0); asm volatile("" : "+s"(pei)); }
;             const bool pe = pei != 0;
;             PG8_LDB(B0, 0, 0); PG8_LDB(B1, 0, 1); PG8_SCHED; PG8_LDA(At, 0, 0); if (!pe) { PG8_STAGE_T(PG8_SA(1, 1), a1 + hstep, voffA, AUX_A); }
;             if (!pe) { PG8_WAIT_V(8); } PG8_WAIT_L(0); PG8_BAR; PG8_MMA(0, 0, At, B0); PG8_MMA(0, 1, At, B1); PG8_BAR; PG8_SCHED;
;             PG8_LDA(At, 0, 1); PG8_STAGE_T(PG8_SB(0, 0), b2, voffB, AUX_B); PG8_STAGE_T(PG8_SB(0, 1), b2 + hstep, voffB, AUX_B); PG8_STAGE_T(PG8_SA(0, 0), a2, voffA, AUX_A);
.LBB0_886:
	ds_read_b128 v[154:157], v149
	s_waitcnt lgkmcnt(0)
	ds_read_b128 v[158:161], v149 offset:1024
	ds_read_b128 v[162:165], v149 offset:2048
	ds_read_b128 v[166:169], v149 offset:3072
	ds_read_b128 v[170:173], v150
	ds_read_b128 v[174:177], v150 offset:1024
	ds_read_b128 v[178:181], v150 offset:2048
	ds_read_b128 v[182:185], v150 offset:3072
	s_add_u32 s44, s42, 0xfffc0080
	s_addc_u32 s45, s43, -1
	s_cmp_eq_u32 s63, 12
	s_cselect_b32 s47, s15, s45
	s_cselect_b32 s46, s59, s44
	s_cselect_b32 s45, s25, s62
	s_cselect_b32 s44, s60, s61
	v_lshl_add_u64 v[144:145], s[42:43], 0, v[136:137]
	s_add_i32 m0, s49, 0xc000
	ds_read_b128 v[186:189], v151
	ds_read_b128 v[190:193], v151 offset:1024
	ds_read_b128 v[196:199], v151 offset:2048
	ds_read_b128 v[200:203], v151 offset:3072
	ds_read_b128 v[204:207], v151 offset:4096
	ds_read_b128 v[208:211], v151 offset:5120
	ds_read_b128 v[212:215], v151 offset:6144
	ds_read_b128 v[216:219], v151 offset:7168
	global_load_lds_dwordx4 v[144:145], off
	v_lshl_add_u64 v[144:145], s[42:43], 0, v[138:139]
	s_add_i32 m0, s49, 0xe000
	s_nop 0
	global_load_lds_dwordx4 v[144:145], off
	s_waitcnt vmcnt(8)
	s_waitcnt lgkmcnt(0)
	s_barrier
	s_waitcnt lgkmcnt(0)
	v_mfma_f32_16x16x32_bf16 v[124:127], v[154:157], v[186:189], v[124:127]
	v_mfma_f32_16x16x32_bf16 v[120:123], v[162:165], v[186:189], v[120:123]
	v_mfma_f32_16x16x32_bf16 v[108:111], v[154:157], v[196:199], v[108:111]
	v_mfma_f32_16x16x32_bf16 v[104:107], v[162:165], v[196:199], v[104:107]
	v_mfma_f32_16x16x32_bf16 v[92:95], v[154:157], v[204:207], v[92:95]
	v_mfma_f32_16x16x32_bf16 v[88:91], v[162:165], v[204:207], v[88:91]
	v_mfma_f32_16x16x32_bf16 v[76:79], v[154:157], v[212:215], v[76:79]
	v_mfma_f32_16x16x32_bf16 v[72:75], v[162:165], v[212:215], v[72:75]
	v_mfma_f32_16x16x32_bf16 v[124:127], v[158:161], v[190:193], v[124:127]
	v_mfma_f32_16x16x32_bf16 v[120:123], v[166:169], v[190:193], v[120:123]
	v_mfma_f32_16x16x32_bf16 v[108:111], v[158:161], v[200:203], v[108:111]
	v_mfma_f32_16x16x32_bf16 v[104:107], v[166:169], v[200:203], v[104:107]
	v_mfma_f32_16x16x32_bf16 v[92:95], v[158:161], v[208:211], v[92:95]
	v_mfma_f32_16x16x32_bf16 v[88:91], v[166:169], v[208:211], v[88:91]
	v_mfma_f32_16x16x32_bf16 v[76:79], v[158:161], v[216:219], v[76:79]
	v_mfma_f32_16x16x32_bf16 v[72:75], v[166:169], v[216:219], v[72:75]
	v_mfma_f32_16x16x32_bf16 v[116:119], v[170:173], v[186:189], v[116:119]
	v_mfma_f32_16x16x32_bf16 v[112:115], v[178:181], v[186:189], v[112:115]
	v_mfma_f32_16x16x32_bf16 v[100:103], v[170:173], v[196:199], v[100:103]
	v_mfma_f32_16x16x32_bf16 v[96:99], v[178:181], v[196:199], v[96:99]
	v_mfma_f32_16x16x32_bf16 v[84:87], v[170:173], v[204:207], v[84:87]
	v_mfma_f32_16x16x32_bf16 v[80:83], v[178:181], v[204:207], v[80:83]
	v_mfma_f32_16x16x32_bf16 v[68:71], v[170:173], v[212:215], v[68:71]
	v_mfma_f32_16x16x32_bf16 v[64:67], v[178:181], v[212:215], v[64:67]
	v_mfma_f32_16x16x32_bf16 v[116:119], v[174:177], v[190:193], v[116:119]
	v_mfma_f32_16x16x32_bf16 v[112:115], v[182:185], v[190:193], v[112:115]
	v_mfma_f32_16x16x32_bf16 v[100:103], v[174:177], v[200:203], v[100:103]
	v_mfma_f32_16x16x32_bf16 v[96:99], v[182:185], v[200:203], v[96:99]
	s_setprio 2
	s_barrier
	v_mfma_f32_16x16x32_bf16 v[84:87], v[174:177], v[208:211], v[84:87]
	v_mfma_f32_16x16x32_bf16 v[80:83], v[182:185], v[208:211], v[80:83]
	v_mfma_f32_16x16x32_bf16 v[68:71], v[174:177], v[216:219], v[68:71]
	v_mfma_f32_16x16x32_bf16 v[64:67], v[182:185], v[216:219], v[64:67]
	s_setprio 0
	s_add_i32 s64, s56, s48
	v_lshl_add_u64 v[144:145], s[44:45], 0, v[130:131]
	s_mov_b32 m0, s64
	ds_read_b128 v[186:189], v151 offset:16384
	ds_read_b128 v[190:193], v151 offset:17408
	ds_read_b128 v[196:199], v151 offset:18432
	ds_read_b128 v[200:203], v151 offset:19456
	ds_read_b128 v[204:207], v151 offset:20480
	ds_read_b128 v[208:211], v151 offset:21504
	ds_read_b128 v[212:215], v151 offset:22528
	ds_read_b128 v[216:219], v151 offset:23552
	global_load_lds_dwordx4 v[144:145], off
	s_add_i32 m0, s64, 0x2000
	s_add_u32 s64, s44, 0x40000
	v_lshl_add_u64 v[220:221], s[44:45], 0, v[134:135]
	s_addc_u32 s65, s45, 0
	s_add_i32 s66, s57, s48
	global_load_lds_dwordx4 v[220:221], off
	v_lshl_add_u64 v[222:223], s[64:65], 0, v[130:131]
	s_mov_b32 m0, s66
	v_lshl_add_u64 v[224:225], s[46:47], 0, v[132:133]
	global_load_lds_dwordx4 v[222:223], off
	v_lshl_add_u64 v[222:223], s[64:65], 0, v[134:135]
	s_add_i32 m0, s66, 0x2000
	s_nop 0
	global_load_lds_dwordx4 v[222:223], off
	v_lshl_add_u64 v[222:223], s[46:47], 0, v[128:129]
	s_mov_b32 m0, s49
	s_nop 0
	global_load_lds_dwordx4 v[222:223], off
	s_mov_b32 m0, s50
	s_nop 0
	global_load_lds_dwordx4 v[224:225], off
	s_waitcnt vmcnt(8)
	s_waitcnt lgkmcnt(0)
	s_barrier
; #define PG8_STAGE_T(bufoff, gbase, voff, AUX) do { _Pragma("unroll") for (int _i = 0; _i < 2; ++_i) \
;         __builtin_amdgcn_global_load_lds((const unsigned*)((const char*)(gbase) + (voff)[_i]), (PG8_LAS unsigned*)(lds + (bufoff) + ldsw + _i * 8192), 16, 0, AUX); } while (0)
; #define PG8_LDA(dst, b, h) do { _Pragma("unroll") for (int m = 0; m < 4; ++m) _Pragma("unroll") for (int k = 0; k < 2; ++k) dst[m][k] = *(const PG8_LAS bf16x8*)(lds + PG8_SA(b, h) + aoff + m * 2048 + k * 1024); } while (0)
; #define PG8_LDB(dst, b, h) do { _Pragma("unroll") for (int n = 0; n < 2; ++n) _Pragma("unroll") for (int k = 0; k < 2; ++k) dst[n][k] = *(const PG8_LAS bf16x8*)(lds + PG8_SB(b, h) + boff + n * 2048 + k * 1024); } while (0)
; #define PG8_MMA(ai, bj, At, Bt) do { __builtin_amdgcn_s_setprio(1); _Pragma("unroll") for (int m = 0; m < 4; ++m) _Pragma("unroll") for (int n = 0; n < 2; ++n) _Pragma("unroll") for (int k = 0; k < 2; ++k) \
;         acc[ai][bj][m][n] = __builtin_amdgcn_mfma_f32_16x16x32_bf16(Bt[n][k], At[m][k], acc[ai][bj][m][n], 0, 0, 0); __builtin_amdgcn_s_setprio(0); } while (0)
; #define PG8_WAIT_V(n) asm volatile("s_waitcnt vmcnt(" #n ")" ::: "memory")
; #define PG8_WAIT_L(n) asm volatile("s_waitcnt lgkmcnt(" #n ")" ::: "memory")
; #define PG8_BAR __builtin_amdgcn_s_barrier()
; #define PG8_SCHED __builtin_amdgcn_sched_barrier(0)
;     ...
;             if (!pe) { PG8_WAIT_V(8); } PG8_WAIT_L(0); PG8_BAR; PG8_MMA(1, 0, At, B0); PG8_MMA(1, 1, At, B1); PG8_BAR; PG8_SCHED;
;             PG8_LDB(B0, 1, 0); PG8_LDB(B1, 1, 1); PG8_SCHED; PG8_LDA(At, 1, 0); PG8_STAGE_T(PG8_SA(0, 1), a2 + hstep, voffA, AUX_A);
;             if (!pe) { PG8_WAIT_V(8); } PG8_WAIT_L(0); PG8_BAR; PG8_MMA(0, 0, At, B0); PG8_MMA(0, 1, At, B1); PG8_BAR; PG8_SCHED;
	s_waitcnt lgkmcnt(0)
	v_mfma_f32_16x16x32_bf16 v[60:63], v[154:157], v[186:189], v[60:63]
	v_mfma_f32_16x16x32_bf16 v[56:59], v[162:165], v[186:189], v[56:59]
	v_mfma_f32_16x16x32_bf16 v[44:47], v[154:157], v[196:199], v[44:47]
	v_mfma_f32_16x16x32_bf16 v[40:43], v[162:165], v[196:199], v[40:43]
	v_mfma_f32_16x16x32_bf16 v[28:31], v[154:157], v[204:207], v[28:31]
	v_mfma_f32_16x16x32_bf16 v[24:27], v[162:165], v[204:207], v[24:27]
	v_mfma_f32_16x16x32_bf16 v[12:15], v[154:157], v[212:215], v[12:15]
	v_mfma_f32_16x16x32_bf16 v[8:11], v[162:165], v[212:215], v[8:11]
	v_mfma_f32_16x16x32_bf16 v[60:63], v[158:161], v[190:193], v[60:63]
	v_mfma_f32_16x16x32_bf16 v[56:59], v[166:169], v[190:193], v[56:59]
	v_mfma_f32_16x16x32_bf16 v[44:47], v[158:161], v[200:203], v[44:47]
	v_mfma_f32_16x16x32_bf16 v[40:43], v[166:169], v[200:203], v[40:43]
	v_mfma_f32_16x16x32_bf16 v[28:31], v[158:161], v[208:211], v[28:31]
	v_mfma_f32_16x16x32_bf16 v[24:27], v[166:169], v[208:211], v[24:27]
	v_mfma_f32_16x16x32_bf16 v[12:15], v[158:161], v[216:219], v[12:15]
	v_mfma_f32_16x16x32_bf16 v[8:11], v[166:169], v[216:219], v[8:11]
	v_mfma_f32_16x16x32_bf16 v[52:55], v[170:173], v[186:189], v[52:55]
	v_mfma_f32_16x16x32_bf16 v[48:51], v[178:181], v[186:189], v[48:51]
	v_mfma_f32_16x16x32_bf16 v[36:39], v[170:173], v[196:199], v[36:39]
	v_mfma_f32_16x16x32_bf16 v[32:35], v[178:181], v[196:199], v[32:35]
	v_mfma_f32_16x16x32_bf16 v[20:23], v[170:173], v[204:207], v[20:23]
	v_mfma_f32_16x16x32_bf16 v[16:19], v[178:181], v[204:207], v[16:19]
	v_mfma_f32_16x16x32_bf16 v[4:7], v[170:173], v[212:215], v[4:7]
	v_mfma_f32_16x16x32_bf16 v[0:3], v[178:181], v[212:215], v[0:3]
	v_mfma_f32_16x16x32_bf16 v[52:55], v[174:177], v[190:193], v[52:55]
	v_mfma_f32_16x16x32_bf16 v[48:51], v[182:185], v[190:193], v[48:51]
	v_mfma_f32_16x16x32_bf16 v[36:39], v[174:177], v[200:203], v[36:39]
	v_mfma_f32_16x16x32_bf16 v[32:35], v[182:185], v[200:203], v[32:35]
	s_setprio 2
	s_barrier
	v_mfma_f32_16x16x32_bf16 v[20:23], v[174:177], v[208:211], v[20:23]
	v_mfma_f32_16x16x32_bf16 v[16:19], v[182:185], v[208:211], v[16:19]
	v_mfma_f32_16x16x32_bf16 v[4:7], v[174:177], v[216:219], v[4:7]
	v_mfma_f32_16x16x32_bf16 v[0:3], v[182:185], v[216:219], v[0:3]
	s_setprio 0
	s_add_i32 s64, 0, 0x18000
	v_add_u32_e32 v153, s64, v147
	s_add_i32 s65, 0, 0x1c000
	ds_read_b128 v[154:157], v153
	ds_read_b128 v[158:161], v153 offset:1024
	ds_read_b128 v[162:165], v153 offset:2048
	ds_read_b128 v[166:169], v153 offset:3072
	v_add_u32_e32 v153, s65, v147
	ds_read_b128 v[170:173], v153
	ds_read_b128 v[174:177], v153 offset:1024
	ds_read_b128 v[178:181], v153 offset:2048
	ds_read_b128 v[182:185], v153 offset:3072
	s_add_u32 s46, s46, 0x40000
	s_addc_u32 s47, s47, 0
	s_mov_b32 m0, s51
	v_lshl_add_u64 v[226:227], s[46:47], 0, v[128:129]
	ds_read_b128 v[186:189], v151 offset:32768
	ds_read_b128 v[190:193], v151 offset:33792
	ds_read_b128 v[196:199], v151 offset:34816
	ds_read_b128 v[200:203], v151 offset:35840
	ds_read_b128 v[204:207], v151 offset:36864
	ds_read_b128 v[208:211], v151 offset:37888
	ds_read_b128 v[212:215], v151 offset:38912
	ds_read_b128 v[216:219], v151 offset:39936
	global_load_lds_dwordx4 v[226:227], off
	v_lshl_add_u64 v[226:227], s[46:47], 0, v[132:133]
	s_mov_b32 m0, s52
	s_nop 0
	global_load_lds_dwordx4 v[226:227], off
	s_waitcnt vmcnt(8)
	s_waitcnt lgkmcnt(0)
	s_barrier
	s_waitcnt lgkmcnt(0)
	v_mfma_f32_16x16x32_bf16 v[124:127], v[154:157], v[186:189], v[124:127]
	v_mfma_f32_16x16x32_bf16 v[120:123], v[162:165], v[186:189], v[120:123]
	v_mfma_f32_16x16x32_bf16 v[108:111], v[154:157], v[196:199], v[108:111]
	v_mfma_f32_16x16x32_bf16 v[104:107], v[162:165], v[196:199], v[104:107]
	v_mfma_f32_16x16x32_bf16 v[92:95], v[154:157], v[204:207], v[92:95]
	v_mfma_f32_16x16x32_bf16 v[88:91], v[162:165], v[204:207], v[88:91]
	v_mfma_f32_16x16x32_bf16 v[76:79], v[154:157], v[212:215], v[76:79]
	v_mfma_f32_16x16x32_bf16 v[72:75], v[162:165], v[212:215], v[72:75]
	v_mfma_f32_16x16x32_bf16 v[124:127], v[158:161], v[190:193], v[124:127]
	v_mfma_f32_16x16x32_bf16 v[120:123], v[166:169], v[190:193], v[120:123]
	v_mfma_f32_16x16x32_bf16 v[108:111], v[158:161], v[200:203], v[108:111]
	v_mfma_f32_16x16x32_bf16 v[104:107], v[166:169], v[200:203], v[104:107]
	v_mfma_f32_16x16x32_bf16 v[92:95], v[158:161], v[208:211], v[92:95]
	v_mfma_f32_16x16x32_bf16 v[88:91], v[166:169], v[208:211], v[88:91]
	v_mfma_f32_16x16x32_bf16 v[76:79], v[158:161], v[216:219], v[76:79]
	v_mfma_f32_16x16x32_bf16 v[72:75], v[166:169], v[216:219], v[72:75]
	v_mfma_f32_16x16x32_bf16 v[116:119], v[170:173], v[186:189], v[116:119]
	v_mfma_f32_16x16x32_bf16 v[112:115], v[178:181], v[186:189], v[112:115]
	v_mfma_f32_16x16x32_bf16 v[100:103], v[170:173], v[196:199], v[100:103]
	v_mfma_f32_16x16x32_bf16 v[96:99], v[178:181], v[196:199], v[96:99]
	v_mfma_f32_16x16x32_bf16 v[84:87], v[170:173], v[204:207], v[84:87]
	v_mfma_f32_16x16x32_bf16 v[80:83], v[178:181], v[204:207], v[80:83]
	v_mfma_f32_16x16x32_bf16 v[68:71], v[170:173], v[212:215], v[68:71]
	v_mfma_f32_16x16x32_bf16 v[64:67], v[178:181], v[212:215], v[64:67]
	v_mfma_f32_16x16x32_bf16 v[116:119], v[174:177], v[190:193], v[116:119]
	v_mfma_f32_16x16x32_bf16 v[112:115], v[182:185], v[190:193], v[112:115]
	v_mfma_f32_16x16x32_bf16 v[100:103], v[174:177], v[200:203], v[100:103]
	v_mfma_f32_16x16x32_bf16 v[96:99], v[182:185], v[200:203], v[96:99]
	s_setprio 2
	s_barrier
; #define PG8_STAGE_T(bufoff, gbase, voff, AUX) do { _Pragma("unroll") for (int _i = 0; _i < 2; ++_i) \
;         __builtin_amdgcn_global_load_lds((const unsigned*)((const char*)(gbase) + (voff)[_i]), (PG8_LAS unsigned*)(lds + (bufoff) + ldsw + _i * 8192), 16, 0, AUX); } while (0)
; #define PG8_LDA(dst, b, h) do { _Pragma("unroll") for (int m = 0; m < 4; ++m) _Pragma("unroll") for (int k = 0; k < 2; ++k) dst[m][k] = *(const PG8_LAS bf16x8*)(lds + PG8_SA(b, h) + aoff + m * 2048 + k * 1024); } while (0)
; #define PG8_MMA(ai, bj, At, Bt) do { __builtin_amdgcn_s_setprio(1); _Pragma("unroll") for (int m = 0; m < 4; ++m) _Pragma("unroll") for (int n = 0; n < 2; ++n) _Pragma("unroll") for (int k = 0; k < 2; ++k) \
;         acc[ai][bj][m][n] = __builtin_amdgcn_mfma_f32_16x16x32_bf16(Bt[n][k], At[m][k], acc[ai][bj][m][n], 0, 0, 0); __builtin_amdgcn_s_setprio(0); } while (0)
; #define PG8_WAIT_V(n) asm volatile("s_waitcnt vmcnt(" #n ")" ::: "memory")
; #define PG8_WAIT_L(n) asm volatile("s_waitcnt lgkmcnt(" #n ")" ::: "memory")
; #define PG8_BAR __builtin_amdgcn_s_barrier()
; #define PG8_SCHED __builtin_amdgcn_sched_barrier(0)
;     ...
;             if (!pe) { PG8_WAIT_V(8); } PG8_WAIT_L(0); PG8_BAR; PG8_MMA(0, 0, At, B0); PG8_MMA(0, 1, At, B1); PG8_BAR; PG8_SCHED;
;             PG8_LDA(At, 1, 1); PG8_STAGE_T(PG8_SB(1, 0), b3, voffB, AUX_B); PG8_STAGE_T(PG8_SB(1, 1), b3 + hstep, voffB, AUX_B); PG8_STAGE_T(PG8_SA(1, 0), a3, voffA, AUX_A);
;             PG8_WAIT_V(8); PG8_WAIT_L(0); PG8_BAR; PG8_MMA(1, 0, At, B0); PG8_MMA(1, 1, At, B1); PG8_BAR; PG8_SCHED;
;     ...
;         if constexpr (ALIGN_EPI) { if (wr == 0) PG8_BAR; }
	v_mfma_f32_16x16x32_bf16 v[84:87], v[174:177], v[208:211], v[84:87]
	v_mfma_f32_16x16x32_bf16 v[80:83], v[182:185], v[208:211], v[80:83]
	v_mfma_f32_16x16x32_bf16 v[68:71], v[174:177], v[216:219], v[68:71]
	v_mfma_f32_16x16x32_bf16 v[64:67], v[182:185], v[216:219], v[64:67]
	s_setprio 0
	s_add_i32 s46, s64, s48
	v_lshl_add_u64 v[144:145], v[144:145], 0, s[10:11]
	s_mov_b32 m0, s46
	ds_read_b128 v[186:189], v151 offset:49152
	ds_read_b128 v[190:193], v151 offset:50176
	ds_read_b128 v[196:199], v151 offset:51200
	ds_read_b128 v[200:203], v151 offset:52224
	ds_read_b128 v[204:207], v151 offset:53248
	ds_read_b128 v[208:211], v151 offset:54272
	ds_read_b128 v[212:215], v151 offset:55296
	ds_read_b128 v[216:219], v151 offset:56320
	global_load_lds_dwordx4 v[144:145], off
	s_add_i32 m0, s46, 0x2000
	s_add_u32 s44, s44, 0x40080
	v_lshl_add_u64 v[144:145], v[220:221], 0, s[10:11]
	s_addc_u32 s45, s45, 0
	s_add_i32 s46, s65, s48
	global_load_lds_dwordx4 v[144:145], off
	v_lshl_add_u64 v[144:145], s[44:45], 0, v[130:131]
	s_mov_b32 m0, s46
	s_nop 0
	global_load_lds_dwordx4 v[144:145], off
	v_lshl_add_u64 v[144:145], s[44:45], 0, v[134:135]
	s_add_i32 m0, s46, 0x2000
	s_nop 0
	global_load_lds_dwordx4 v[144:145], off
	v_lshl_add_u64 v[144:145], v[222:223], 0, s[10:11]
	s_mov_b32 m0, s53
	s_nop 0
	global_load_lds_dwordx4 v[144:145], off
	v_lshl_add_u64 v[144:145], v[224:225], 0, s[10:11]
	s_mov_b32 m0, s54
	s_nop 0
	global_load_lds_dwordx4 v[144:145], off
	s_waitcnt vmcnt(8)
	s_waitcnt lgkmcnt(0)
	s_barrier
	s_waitcnt lgkmcnt(0)
	v_mfma_f32_16x16x32_bf16 v[60:63], v[154:157], v[186:189], v[60:63]
	v_mfma_f32_16x16x32_bf16 v[56:59], v[162:165], v[186:189], v[56:59]
	v_mfma_f32_16x16x32_bf16 v[44:47], v[154:157], v[196:199], v[44:47]
	v_mfma_f32_16x16x32_bf16 v[40:43], v[162:165], v[196:199], v[40:43]
	v_mfma_f32_16x16x32_bf16 v[28:31], v[154:157], v[204:207], v[28:31]
	v_mfma_f32_16x16x32_bf16 v[24:27], v[162:165], v[204:207], v[24:27]
	v_mfma_f32_16x16x32_bf16 v[12:15], v[154:157], v[212:215], v[12:15]
	v_mfma_f32_16x16x32_bf16 v[8:11], v[162:165], v[212:215], v[8:11]
	v_mfma_f32_16x16x32_bf16 v[60:63], v[158:161], v[190:193], v[60:63]
	v_mfma_f32_16x16x32_bf16 v[56:59], v[166:169], v[190:193], v[56:59]
	v_mfma_f32_16x16x32_bf16 v[44:47], v[158:161], v[200:203], v[44:47]
	v_mfma_f32_16x16x32_bf16 v[40:43], v[166:169], v[200:203], v[40:43]
	v_mfma_f32_16x16x32_bf16 v[28:31], v[158:161], v[208:211], v[28:31]
	v_mfma_f32_16x16x32_bf16 v[24:27], v[166:169], v[208:211], v[24:27]
	v_mfma_f32_16x16x32_bf16 v[12:15], v[158:161], v[216:219], v[12:15]
	v_mfma_f32_16x16x32_bf16 v[8:11], v[166:169], v[216:219], v[8:11]
	v_mfma_f32_16x16x32_bf16 v[52:55], v[170:173], v[186:189], v[52:55]
	v_mfma_f32_16x16x32_bf16 v[48:51], v[178:181], v[186:189], v[48:51]
	v_mfma_f32_16x16x32_bf16 v[36:39], v[170:173], v[196:199], v[36:39]
	v_mfma_f32_16x16x32_bf16 v[32:35], v[178:181], v[196:199], v[32:35]
	v_mfma_f32_16x16x32_bf16 v[20:23], v[170:173], v[204:207], v[20:23]
	v_mfma_f32_16x16x32_bf16 v[16:19], v[178:181], v[204:207], v[16:19]
	v_mfma_f32_16x16x32_bf16 v[4:7], v[170:173], v[212:215], v[4:7]
	v_mfma_f32_16x16x32_bf16 v[0:3], v[178:181], v[212:215], v[0:3]
	v_mfma_f32_16x16x32_bf16 v[52:55], v[174:177], v[190:193], v[52:55]
	v_mfma_f32_16x16x32_bf16 v[48:51], v[182:185], v[190:193], v[48:51]
	v_mfma_f32_16x16x32_bf16 v[36:39], v[174:177], v[200:203], v[36:39]
	v_mfma_f32_16x16x32_bf16 v[32:35], v[182:185], v[200:203], v[32:35]
	s_setprio 2
	s_barrier
	v_mfma_f32_16x16x32_bf16 v[20:23], v[174:177], v[208:211], v[20:23]
	v_mfma_f32_16x16x32_bf16 v[16:19], v[182:185], v[208:211], v[16:19]
	v_mfma_f32_16x16x32_bf16 v[4:7], v[174:177], v[216:219], v[4:7]
	v_mfma_f32_16x16x32_bf16 v[0:3], v[182:185], v[216:219], v[0:3]
	s_setprio 0
	s_add_i32 s63, s63, 2
	s_add_u32 s42, s42, 0x100
	s_addc_u32 s43, s43, 0
	s_add_u32 s61, s61, 0x100
	s_addc_u32 s62, s62, 0
	s_cmp_gt_u32 s63, 13
	s_cbranch_scc0 .LBB0_886
	s_and_b64 vcc, exec, s[12:13]
	s_cbranch_vccz .LBB0_889
	s_barrier

; #define PG8_STAGE_T(bufoff, gbase, voff, AUX) do { _Pragma("unroll") for (int _i = 0; _i < 2; ++_i) \
;         __builtin_amdgcn_global_load_lds((const unsigned*)((const char*)(gbase) + (voff)[_i]), (PG8_LAS unsigned*)(lds + (bufoff) + ldsw + _i * 8192), 16, 0, AUX); } while (0)
; #define PG8_LDA(dst, b, h) do { _Pragma("unroll") for (int m = 0; m < 4; ++m) _Pragma("unroll") for (int k = 0; k < 2; ++k) dst[m][k] = *(const PG8_LAS bf16x8*)(lds + PG8_SA(b, h) + aoff + m * 2048 + k * 1024); } while (0)
; #define PG8_LDB(dst, b, h) do { _Pragma("unroll") for (int n = 0; n < 2; ++n) _Pragma("unroll") for (int k = 0; k < 2; ++k) dst[n][k] = *(const PG8_LAS bf16x8*)(lds + PG8_SB(b, h) + boff + n * 2048 + k * 1024); } while (0)
; #define PG8_MMA(ai, bj, At, Bt) do { __builtin_amdgcn_s_setprio(1); _Pragma("unroll") for (int m = 0; m < 4; ++m) _Pragma("unroll") for (int n = 0; n < 2; ++n) _Pragma("unroll") for (int k = 0; k < 2; ++k) \
;         acc[ai][bj][m][n] = __builtin_amdgcn_mfma_f32_16x16x32_bf16(Bt[n][k], At[m][k], acc[ai][bj][m][n], 0, 0, 0); __builtin_amdgcn_s_setprio(0); } while (0)
; #define PG8_WAIT_V(n) asm volatile("s_waitcnt vmcnt(" #n ")" ::: "memory")
; #define PG8_WAIT_L(n) asm volatile("s_waitcnt lgkmcnt(" #n ")" ::: "memory")
; #define PG8_BAR __builtin_amdgcn_s_barrier()
;     ...
;             const bool last = (t == nt - 2);
;             const char* a1 = cA + (ptrdiff_t)(t + 1) * ck;
;             const char* a2 = last ? nA : cA + (ptrdiff_t)(t + 2) * ck; const char* b2 = last ? nB : cB + (ptrdiff_t)(t + 2) * ck;
;             const ptrdiff_t k3 = last ? nk : ck;
;             const char* a3 = a2 + k3; const char* b3 = b2 + k3;
;             if (last && has_next) S.a_ready(nxt);
;             if constexpr (SP2) {
;             int pei = 0; if constexpr (PEEL) { pei = __builtin_amdgcn_readfirstlane((t == 0 && ui > 0) ? 1 : 0); asm volatile("" : "+s"(pei)); }
;             const bool pe = pei != 0;
;             PG8_LDB(B0, 0, 0); PG8_LDB(B1, 0, 1); PG8_SCHED; PG8_LDA(At, 0, 0); if (!pe) { PG8_STAGE_T(PG8_SA(1, 1), a1 + hstep, voffA, AUX_A); }
;             if (!pe) { PG8_WAIT_V(8); } PG8_WAIT_L(0); PG8_BAR; PG8_MMA(0, 0, At, B0); PG8_MMA(0, 1, At, B1); PG8_BAR; PG8_SCHED;
;             PG8_LDA(At, 0, 1); PG8_STAGE_T(PG8_SB(0, 0), b2, voffB, AUX_B); PG8_STAGE_T(PG8_SB(0, 1), b2 + hstep, voffB, AUX_B); PG8_STAGE_T(PG8_SA(0, 0), a2, voffA, AUX_A);
.LBB0_1071:
	ds_read_b128 v[146:149], v166
	ds_read_b128 v[162:165], v166 offset:1024
	ds_read_b128 v[170:173], v166 offset:2048
	ds_read_b128 v[174:177], v166 offset:3072
	ds_read_b128 v[178:181], v167
	ds_read_b128 v[182:185], v167 offset:1024
	ds_read_b128 v[186:189], v167 offset:2048
	ds_read_b128 v[190:193], v167 offset:3072
	s_add_u32 s38, s36, 0xfffc0080
	s_addc_u32 s39, s37, -1
	s_cmp_eq_u32 s62, 12
	s_cselect_b32 s41, s13, s39
	s_cselect_b32 s40, s27, s38
	s_cselect_b32 s39, s15, s61
	s_cselect_b32 s38, s59, s60
	v_lshl_add_u64 v[150:151], s[36:37], 0, v[136:137]
	s_add_i32 m0, s45, 0xc000
	ds_read_b128 v[196:199], v168
	ds_read_b128 v[200:203], v168 offset:1024
	ds_read_b128 v[204:207], v168 offset:2048
	ds_read_b128 v[208:211], v168 offset:3072
	ds_read_b128 v[212:215], v168 offset:4096
	ds_read_b128 v[216:219], v168 offset:5120
	ds_read_b128 v[220:223], v168 offset:6144
	ds_read_b128 v[224:227], v168 offset:7168
	global_load_lds_dwordx4 v[150:151], off
	v_lshl_add_u64 v[150:151], s[36:37], 0, v[138:139]
	s_add_i32 m0, s45, 0xe000
	s_nop 0
	global_load_lds_dwordx4 v[150:151], off
	s_waitcnt vmcnt(8)
	s_waitcnt lgkmcnt(0)
	s_barrier
	s_waitcnt lgkmcnt(0)
	v_mfma_f32_16x16x32_bf16 v[124:127], v[146:149], v[196:199], v[124:127]
	v_mfma_f32_16x16x32_bf16 v[120:123], v[170:173], v[196:199], v[120:123]
	v_mfma_f32_16x16x32_bf16 v[108:111], v[146:149], v[204:207], v[108:111]
	v_mfma_f32_16x16x32_bf16 v[104:107], v[170:173], v[204:207], v[104:107]
	v_mfma_f32_16x16x32_bf16 v[92:95], v[146:149], v[212:215], v[92:95]
	v_mfma_f32_16x16x32_bf16 v[88:91], v[170:173], v[212:215], v[88:91]
	v_mfma_f32_16x16x32_bf16 v[76:79], v[146:149], v[220:223], v[76:79]
	v_mfma_f32_16x16x32_bf16 v[72:75], v[170:173], v[220:223], v[72:75]
	v_mfma_f32_16x16x32_bf16 v[124:127], v[162:165], v[200:203], v[124:127]
	v_mfma_f32_16x16x32_bf16 v[120:123], v[174:177], v[200:203], v[120:123]
	v_mfma_f32_16x16x32_bf16 v[108:111], v[162:165], v[208:211], v[108:111]
	v_mfma_f32_16x16x32_bf16 v[104:107], v[174:177], v[208:211], v[104:107]
	v_mfma_f32_16x16x32_bf16 v[92:95], v[162:165], v[216:219], v[92:95]
	v_mfma_f32_16x16x32_bf16 v[88:91], v[174:177], v[216:219], v[88:91]
	v_mfma_f32_16x16x32_bf16 v[76:79], v[162:165], v[224:227], v[76:79]
	v_mfma_f32_16x16x32_bf16 v[72:75], v[174:177], v[224:227], v[72:75]
	v_mfma_f32_16x16x32_bf16 v[116:119], v[178:181], v[196:199], v[116:119]
	v_mfma_f32_16x16x32_bf16 v[112:115], v[186:189], v[196:199], v[112:115]
	v_mfma_f32_16x16x32_bf16 v[100:103], v[178:181], v[204:207], v[100:103]
	v_mfma_f32_16x16x32_bf16 v[96:99], v[186:189], v[204:207], v[96:99]
	v_mfma_f32_16x16x32_bf16 v[84:87], v[178:181], v[212:215], v[84:87]
	v_mfma_f32_16x16x32_bf16 v[80:83], v[186:189], v[212:215], v[80:83]
	v_mfma_f32_16x16x32_bf16 v[68:71], v[178:181], v[220:223], v[68:71]
	v_mfma_f32_16x16x32_bf16 v[64:67], v[186:189], v[220:223], v[64:67]
	v_mfma_f32_16x16x32_bf16 v[116:119], v[182:185], v[200:203], v[116:119]
	v_mfma_f32_16x16x32_bf16 v[112:115], v[190:193], v[200:203], v[112:115]
	v_mfma_f32_16x16x32_bf16 v[100:103], v[182:185], v[208:211], v[100:103]
	v_mfma_f32_16x16x32_bf16 v[96:99], v[190:193], v[208:211], v[96:99]
	s_setprio 2
	s_barrier
	v_mfma_f32_16x16x32_bf16 v[84:87], v[182:185], v[216:219], v[84:87]
	v_mfma_f32_16x16x32_bf16 v[80:83], v[190:193], v[216:219], v[80:83]
	v_mfma_f32_16x16x32_bf16 v[68:71], v[182:185], v[224:227], v[68:71]
	v_mfma_f32_16x16x32_bf16 v[64:67], v[190:193], v[224:227], v[64:67]
	s_setprio 0
	s_add_i32 s63, s52, s43
	v_lshl_add_u64 v[150:151], s[38:39], 0, v[132:133]
	s_mov_b32 m0, s63
	ds_read_b128 v[196:199], v168 offset:16384
	ds_read_b128 v[200:203], v168 offset:17408
	ds_read_b128 v[204:207], v168 offset:18432
	ds_read_b128 v[208:211], v168 offset:19456
	ds_read_b128 v[212:215], v168 offset:20480
	ds_read_b128 v[216:219], v168 offset:21504
	ds_read_b128 v[220:223], v168 offset:22528
	ds_read_b128 v[224:227], v168 offset:23552
	global_load_lds_dwordx4 v[150:151], off
	s_add_i32 m0, s63, 0x2000
	s_add_u32 s64, s38, 0x40000
	v_lshl_add_u64 v[154:155], s[38:39], 0, v[128:129]
	s_addc_u32 s65, s39, 0
	s_add_i32 s63, s53, s43
	global_load_lds_dwordx4 v[154:155], off
	v_lshl_add_u64 v[158:159], s[64:65], 0, v[132:133]
	s_mov_b32 m0, s63
	v_lshl_add_u64 v[228:229], s[40:41], 0, v[130:131]
	global_load_lds_dwordx4 v[158:159], off
	v_lshl_add_u64 v[158:159], s[64:65], 0, v[128:129]
	s_add_i32 m0, s63, 0x2000
	s_nop 0
	global_load_lds_dwordx4 v[158:159], off
	v_lshl_add_u64 v[158:159], s[40:41], 0, v[134:135]
	s_mov_b32 m0, s45
	s_nop 0
	global_load_lds_dwordx4 v[158:159], off
	s_mov_b32 m0, s46
	s_nop 0
	global_load_lds_dwordx4 v[228:229], off
	s_waitcnt vmcnt(8)
	s_waitcnt lgkmcnt(0)
	s_barrier
; #define PG8_STAGE_T(bufoff, gbase, voff, AUX) do { _Pragma("unroll") for (int _i = 0; _i < 2; ++_i) \
;         __builtin_amdgcn_global_load_lds((const unsigned*)((const char*)(gbase) + (voff)[_i]), (PG8_LAS unsigned*)(lds + (bufoff) + ldsw + _i * 8192), 16, 0, AUX); } while (0)
; #define PG8_LDA(dst, b, h) do { _Pragma("unroll") for (int m = 0; m < 4; ++m) _Pragma("unroll") for (int k = 0; k < 2; ++k) dst[m][k] = *(const PG8_LAS bf16x8*)(lds + PG8_SA(b, h) + aoff + m * 2048 + k * 1024); } while (0)
; #define PG8_LDB(dst, b, h) do { _Pragma("unroll") for (int n = 0; n < 2; ++n) _Pragma("unroll") for (int k = 0; k < 2; ++k) dst[n][k] = *(const PG8_LAS bf16x8*)(lds + PG8_SB(b, h) + boff + n * 2048 + k * 1024); } while (0)
; #define PG8_MMA(ai, bj, At, Bt) do { __builtin_amdgcn_s_setprio(1); _Pragma("unroll") for (int m = 0; m < 4; ++m) _Pragma("unroll") for (int n = 0; n < 2; ++n) _Pragma("unroll") for (int k = 0; k < 2; ++k) \
;         acc[ai][bj][m][n] = __builtin_amdgcn_mfma_f32_16x16x32_bf16(Bt[n][k], At[m][k], acc[ai][bj][m][n], 0, 0, 0); __builtin_amdgcn_s_setprio(0); } while (0)
; #define PG8_WAIT_V(n) asm volatile("s_waitcnt vmcnt(" #n ")" ::: "memory")
; #define PG8_WAIT_L(n) asm volatile("s_waitcnt lgkmcnt(" #n ")" ::: "memory")
; #define PG8_BAR __builtin_amdgcn_s_barrier()
; #define PG8_SCHED __builtin_amdgcn_sched_barrier(0)
;     ...
;             if (!pe) { PG8_WAIT_V(8); } PG8_WAIT_L(0); PG8_BAR; PG8_MMA(1, 0, At, B0); PG8_MMA(1, 1, At, B1); PG8_BAR; PG8_SCHED;
;             PG8_LDB(B0, 1, 0); PG8_LDB(B1, 1, 1); PG8_SCHED; PG8_LDA(At, 1, 0); PG8_STAGE_T(PG8_SA(0, 1), a2 + hstep, voffA, AUX_A);
;             if (!pe) { PG8_WAIT_V(8); } PG8_WAIT_L(0); PG8_BAR; PG8_MMA(0, 0, At, B0); PG8_MMA(0, 1, At, B1); PG8_BAR; PG8_SCHED;
	s_waitcnt lgkmcnt(0)
	v_mfma_f32_16x16x32_bf16 v[60:63], v[146:149], v[196:199], v[60:63]
	v_mfma_f32_16x16x32_bf16 v[56:59], v[170:173], v[196:199], v[56:59]
	v_mfma_f32_16x16x32_bf16 v[44:47], v[146:149], v[204:207], v[44:47]
	v_mfma_f32_16x16x32_bf16 v[40:43], v[170:173], v[204:207], v[40:43]
	v_mfma_f32_16x16x32_bf16 v[28:31], v[146:149], v[212:215], v[28:31]
	v_mfma_f32_16x16x32_bf16 v[24:27], v[170:173], v[212:215], v[24:27]
	v_mfma_f32_16x16x32_bf16 v[12:15], v[146:149], v[220:223], v[12:15]
	v_mfma_f32_16x16x32_bf16 v[8:11], v[170:173], v[220:223], v[8:11]
	v_mfma_f32_16x16x32_bf16 v[60:63], v[162:165], v[200:203], v[60:63]
	v_mfma_f32_16x16x32_bf16 v[56:59], v[174:177], v[200:203], v[56:59]
	v_mfma_f32_16x16x32_bf16 v[44:47], v[162:165], v[208:211], v[44:47]
	v_mfma_f32_16x16x32_bf16 v[40:43], v[174:177], v[208:211], v[40:43]
	v_mfma_f32_16x16x32_bf16 v[28:31], v[162:165], v[216:219], v[28:31]
	v_mfma_f32_16x16x32_bf16 v[24:27], v[174:177], v[216:219], v[24:27]
	v_mfma_f32_16x16x32_bf16 v[12:15], v[162:165], v[224:227], v[12:15]
	v_mfma_f32_16x16x32_bf16 v[8:11], v[174:177], v[224:227], v[8:11]
	v_mfma_f32_16x16x32_bf16 v[52:55], v[178:181], v[196:199], v[52:55]
	v_mfma_f32_16x16x32_bf16 v[48:51], v[186:189], v[196:199], v[48:51]
	v_mfma_f32_16x16x32_bf16 v[36:39], v[178:181], v[204:207], v[36:39]
	v_mfma_f32_16x16x32_bf16 v[32:35], v[186:189], v[204:207], v[32:35]
	v_mfma_f32_16x16x32_bf16 v[20:23], v[178:181], v[212:215], v[20:23]
	v_mfma_f32_16x16x32_bf16 v[16:19], v[186:189], v[212:215], v[16:19]
	v_mfma_f32_16x16x32_bf16 v[4:7], v[178:181], v[220:223], v[4:7]
	v_mfma_f32_16x16x32_bf16 v[0:3], v[186:189], v[220:223], v[0:3]
	v_mfma_f32_16x16x32_bf16 v[52:55], v[182:185], v[200:203], v[52:55]
	v_mfma_f32_16x16x32_bf16 v[48:51], v[190:193], v[200:203], v[48:51]
	v_mfma_f32_16x16x32_bf16 v[36:39], v[182:185], v[208:211], v[36:39]
	v_mfma_f32_16x16x32_bf16 v[32:35], v[190:193], v[208:211], v[32:35]
	s_setprio 2
	s_barrier
	v_mfma_f32_16x16x32_bf16 v[20:23], v[182:185], v[216:219], v[20:23]
	v_mfma_f32_16x16x32_bf16 v[16:19], v[190:193], v[216:219], v[16:19]
	v_mfma_f32_16x16x32_bf16 v[4:7], v[182:185], v[224:227], v[4:7]
	v_mfma_f32_16x16x32_bf16 v[0:3], v[190:193], v[224:227], v[0:3]
	s_setprio 0
	s_add_i32 s63, 0, 0x18000
	v_add_u32_e32 v144, s63, v153
	s_add_i32 s64, 0, 0x1c000
	ds_read_b128 v[146:149], v144
	ds_read_b128 v[162:165], v144 offset:1024
	ds_read_b128 v[170:173], v144 offset:2048
	ds_read_b128 v[174:177], v144 offset:3072
	v_add_u32_e32 v144, s64, v153
	ds_read_b128 v[178:181], v144
	ds_read_b128 v[182:185], v144 offset:1024
	ds_read_b128 v[186:189], v144 offset:2048
	ds_read_b128 v[190:193], v144 offset:3072
	s_add_u32 s40, s40, 0x40000
	s_addc_u32 s41, s41, 0
	s_mov_b32 m0, s47
	v_lshl_add_u64 v[230:231], s[40:41], 0, v[134:135]
	ds_read_b128 v[196:199], v168 offset:32768
	ds_read_b128 v[200:203], v168 offset:33792
	ds_read_b128 v[204:207], v168 offset:34816
	ds_read_b128 v[208:211], v168 offset:35840
	ds_read_b128 v[212:215], v168 offset:36864
	ds_read_b128 v[216:219], v168 offset:37888
	ds_read_b128 v[220:223], v168 offset:38912
	ds_read_b128 v[224:227], v168 offset:39936
	global_load_lds_dwordx4 v[230:231], off
	v_lshl_add_u64 v[230:231], s[40:41], 0, v[130:131]
	s_mov_b32 m0, s48
	s_nop 0
	global_load_lds_dwordx4 v[230:231], off
	s_waitcnt vmcnt(8)
	s_waitcnt lgkmcnt(0)
	s_barrier
	s_waitcnt lgkmcnt(0)
	v_mfma_f32_16x16x32_bf16 v[124:127], v[146:149], v[196:199], v[124:127]
	v_mfma_f32_16x16x32_bf16 v[120:123], v[170:173], v[196:199], v[120:123]
	v_mfma_f32_16x16x32_bf16 v[108:111], v[146:149], v[204:207], v[108:111]
	v_mfma_f32_16x16x32_bf16 v[104:107], v[170:173], v[204:207], v[104:107]
	v_mfma_f32_16x16x32_bf16 v[92:95], v[146:149], v[212:215], v[92:95]
	v_mfma_f32_16x16x32_bf16 v[88:91], v[170:173], v[212:215], v[88:91]
	v_mfma_f32_16x16x32_bf16 v[76:79], v[146:149], v[220:223], v[76:79]
	v_mfma_f32_16x16x32_bf16 v[72:75], v[170:173], v[220:223], v[72:75]
	v_mfma_f32_16x16x32_bf16 v[124:127], v[162:165], v[200:203], v[124:127]
	v_mfma_f32_16x16x32_bf16 v[120:123], v[174:177], v[200:203], v[120:123]
	v_mfma_f32_16x16x32_bf16 v[108:111], v[162:165], v[208:211], v[108:111]
	v_mfma_f32_16x16x32_bf16 v[104:107], v[174:177], v[208:211], v[104:107]
	v_mfma_f32_16x16x32_bf16 v[92:95], v[162:165], v[216:219], v[92:95]
	v_mfma_f32_16x16x32_bf16 v[88:91], v[174:177], v[216:219], v[88:91]
	v_mfma_f32_16x16x32_bf16 v[76:79], v[162:165], v[224:227], v[76:79]
	v_mfma_f32_16x16x32_bf16 v[72:75], v[174:177], v[224:227], v[72:75]
	v_mfma_f32_16x16x32_bf16 v[116:119], v[178:181], v[196:199], v[116:119]
	v_mfma_f32_16x16x32_bf16 v[112:115], v[186:189], v[196:199], v[112:115]
	v_mfma_f32_16x16x32_bf16 v[100:103], v[178:181], v[204:207], v[100:103]
	v_mfma_f32_16x16x32_bf16 v[96:99], v[186:189], v[204:207], v[96:99]
	v_mfma_f32_16x16x32_bf16 v[84:87], v[178:181], v[212:215], v[84:87]
	v_mfma_f32_16x16x32_bf16 v[80:83], v[186:189], v[212:215], v[80:83]
	v_mfma_f32_16x16x32_bf16 v[68:71], v[178:181], v[220:223], v[68:71]
	v_mfma_f32_16x16x32_bf16 v[64:67], v[186:189], v[220:223], v[64:67]
	v_mfma_f32_16x16x32_bf16 v[116:119], v[182:185], v[200:203], v[116:119]
	v_mfma_f32_16x16x32_bf16 v[112:115], v[190:193], v[200:203], v[112:115]
	v_mfma_f32_16x16x32_bf16 v[100:103], v[182:185], v[208:211], v[100:103]
	v_mfma_f32_16x16x32_bf16 v[96:99], v[190:193], v[208:211], v[96:99]
	s_setprio 2
	s_barrier
; #define PG8_STAGE_T(bufoff, gbase, voff, AUX) do { _Pragma("unroll") for (int _i = 0; _i < 2; ++_i) \
;         __builtin_amdgcn_global_load_lds((const unsigned*)((const char*)(gbase) + (voff)[_i]), (PG8_LAS unsigned*)(lds + (bufoff) + ldsw + _i * 8192), 16, 0, AUX); } while (0)
; #define PG8_LDA(dst, b, h) do { _Pragma("unroll") for (int m = 0; m < 4; ++m) _Pragma("unroll") for (int k = 0; k < 2; ++k) dst[m][k] = *(const PG8_LAS bf16x8*)(lds + PG8_SA(b, h) + aoff + m * 2048 + k * 1024); } while (0)
; #define PG8_MMA(ai, bj, At, Bt) do { __builtin_amdgcn_s_setprio(1); _Pragma("unroll") for (int m = 0; m < 4; ++m) _Pragma("unroll") for (int n = 0; n < 2; ++n) _Pragma("unroll") for (int k = 0; k < 2; ++k) \
;         acc[ai][bj][m][n] = __builtin_amdgcn_mfma_f32_16x16x32_bf16(Bt[n][k], At[m][k], acc[ai][bj][m][n], 0, 0, 0); __builtin_amdgcn_s_setprio(0); } while (0)
; #define PG8_WAIT_V(n) asm volatile("s_waitcnt vmcnt(" #n ")" ::: "memory")
; #define PG8_WAIT_L(n) asm volatile("s_waitcnt lgkmcnt(" #n ")" ::: "memory")
; #define PG8_BAR __builtin_amdgcn_s_barrier()
; #define PG8_SCHED __builtin_amdgcn_sched_barrier(0)
;     ...
;             if (!pe) { PG8_WAIT_V(8); } PG8_WAIT_L(0); PG8_BAR; PG8_MMA(0, 0, At, B0); PG8_MMA(0, 1, At, B1); PG8_BAR; PG8_SCHED;
;             PG8_LDA(At, 1, 1); PG8_STAGE_T(PG8_SB(1, 0), b3, voffB, AUX_B); PG8_STAGE_T(PG8_SB(1, 1), b3 + hstep, voffB, AUX_B); PG8_STAGE_T(PG8_SA(1, 0), a3, voffA, AUX_A);
;             PG8_WAIT_V(8); PG8_WAIT_L(0); PG8_BAR; PG8_MMA(1, 0, At, B0); PG8_MMA(1, 1, At, B1); PG8_BAR; PG8_SCHED;
;     ...
;         if constexpr (ALIGN_EPI) { if (wr == 0) PG8_BAR; }
	v_mfma_f32_16x16x32_bf16 v[84:87], v[182:185], v[216:219], v[84:87]
	v_mfma_f32_16x16x32_bf16 v[80:83], v[190:193], v[216:219], v[80:83]
	v_mfma_f32_16x16x32_bf16 v[68:71], v[182:185], v[224:227], v[68:71]
	v_mfma_f32_16x16x32_bf16 v[64:67], v[190:193], v[224:227], v[64:67]
	s_setprio 0
	s_add_i32 s40, s63, s43
	v_lshl_add_u64 v[150:151], v[150:151], 0, s[8:9]
	s_mov_b32 m0, s40
	ds_read_b128 v[196:199], v168 offset:49152
	ds_read_b128 v[200:203], v168 offset:50176
	ds_read_b128 v[204:207], v168 offset:51200
	ds_read_b128 v[208:211], v168 offset:52224
	ds_read_b128 v[212:215], v168 offset:53248
	ds_read_b128 v[216:219], v168 offset:54272
	ds_read_b128 v[220:223], v168 offset:55296
	ds_read_b128 v[224:227], v168 offset:56320
	global_load_lds_dwordx4 v[150:151], off
	s_add_i32 m0, s40, 0x2000
	s_add_u32 s38, s38, 0x40080
	v_lshl_add_u64 v[150:151], v[154:155], 0, s[8:9]
	s_addc_u32 s39, s39, 0
	s_add_i32 s40, s64, s43
	global_load_lds_dwordx4 v[150:151], off
	v_lshl_add_u64 v[150:151], s[38:39], 0, v[132:133]
	s_mov_b32 m0, s40
	s_nop 0
	global_load_lds_dwordx4 v[150:151], off
	v_lshl_add_u64 v[150:151], s[38:39], 0, v[128:129]
	s_add_i32 m0, s40, 0x2000
	s_nop 0
	global_load_lds_dwordx4 v[150:151], off
	v_lshl_add_u64 v[150:151], v[158:159], 0, s[8:9]
	s_mov_b32 m0, s50
	s_nop 0
	global_load_lds_dwordx4 v[150:151], off
	v_lshl_add_u64 v[150:151], v[228:229], 0, s[8:9]
	s_mov_b32 m0, s51
	s_nop 0
	global_load_lds_dwordx4 v[150:151], off
	s_waitcnt vmcnt(8)
	s_waitcnt lgkmcnt(0)
	s_barrier
	s_waitcnt lgkmcnt(0)
	v_mfma_f32_16x16x32_bf16 v[60:63], v[146:149], v[196:199], v[60:63]
	v_mfma_f32_16x16x32_bf16 v[56:59], v[170:173], v[196:199], v[56:59]
	v_mfma_f32_16x16x32_bf16 v[44:47], v[146:149], v[204:207], v[44:47]
	v_mfma_f32_16x16x32_bf16 v[40:43], v[170:173], v[204:207], v[40:43]
	v_mfma_f32_16x16x32_bf16 v[28:31], v[146:149], v[212:215], v[28:31]
	v_mfma_f32_16x16x32_bf16 v[24:27], v[170:173], v[212:215], v[24:27]
	v_mfma_f32_16x16x32_bf16 v[12:15], v[146:149], v[220:223], v[12:15]
	v_mfma_f32_16x16x32_bf16 v[8:11], v[170:173], v[220:223], v[8:11]
	v_mfma_f32_16x16x32_bf16 v[60:63], v[162:165], v[200:203], v[60:63]
	v_mfma_f32_16x16x32_bf16 v[56:59], v[174:177], v[200:203], v[56:59]
	v_mfma_f32_16x16x32_bf16 v[44:47], v[162:165], v[208:211], v[44:47]
	v_mfma_f32_16x16x32_bf16 v[40:43], v[174:177], v[208:211], v[40:43]
	v_mfma_f32_16x16x32_bf16 v[28:31], v[162:165], v[216:219], v[28:31]
	v_mfma_f32_16x16x32_bf16 v[24:27], v[174:177], v[216:219], v[24:27]
	v_mfma_f32_16x16x32_bf16 v[12:15], v[162:165], v[224:227], v[12:15]
	v_mfma_f32_16x16x32_bf16 v[8:11], v[174:177], v[224:227], v[8:11]
	v_mfma_f32_16x16x32_bf16 v[52:55], v[178:181], v[196:199], v[52:55]
	v_mfma_f32_16x16x32_bf16 v[48:51], v[186:189], v[196:199], v[48:51]
	v_mfma_f32_16x16x32_bf16 v[36:39], v[178:181], v[204:207], v[36:39]
	v_mfma_f32_16x16x32_bf16 v[32:35], v[186:189], v[204:207], v[32:35]
	v_mfma_f32_16x16x32_bf16 v[20:23], v[178:181], v[212:215], v[20:23]
	v_mfma_f32_16x16x32_bf16 v[16:19], v[186:189], v[212:215], v[16:19]
	v_mfma_f32_16x16x32_bf16 v[4:7], v[178:181], v[220:223], v[4:7]
	v_mfma_f32_16x16x32_bf16 v[0:3], v[186:189], v[220:223], v[0:3]
	v_mfma_f32_16x16x32_bf16 v[52:55], v[182:185], v[200:203], v[52:55]
	v_mfma_f32_16x16x32_bf16 v[48:51], v[190:193], v[200:203], v[48:51]
	v_mfma_f32_16x16x32_bf16 v[36:39], v[182:185], v[208:211], v[36:39]
	v_mfma_f32_16x16x32_bf16 v[32:35], v[190:193], v[208:211], v[32:35]
	s_setprio 2
	s_barrier
	v_mfma_f32_16x16x32_bf16 v[20:23], v[182:185], v[216:219], v[20:23]
	v_mfma_f32_16x16x32_bf16 v[16:19], v[190:193], v[216:219], v[16:19]
	v_mfma_f32_16x16x32_bf16 v[4:7], v[182:185], v[224:227], v[4:7]
	v_mfma_f32_16x16x32_bf16 v[0:3], v[190:193], v[224:227], v[0:3]
	s_setprio 0
	s_add_i32 s62, s62, 2
	s_add_u32 s36, s36, 0x100
	s_addc_u32 s37, s37, 0
	s_add_u32 s60, s60, 0x100
	s_addc_u32 s61, s61, 0
	s_cmp_gt_u32 s62, 13
	s_cbranch_scc0 .LBB0_1071
	s_and_b64 vcc, exec, s[10:11]
	s_cbranch_vccz .LBB0_1074
	s_barrier

; #define PG8_STAGE_T(bufoff, gbase, voff, AUX) do { _Pragma("unroll") for (int _i = 0; _i < 2; ++_i) \
;         __builtin_amdgcn_global_load_lds((const unsigned*)((const char*)(gbase) + (voff)[_i]), (PG8_LAS unsigned*)(lds + (bufoff) + ldsw + _i * 8192), 16, 0, AUX); } while (0)
; #define PG8_LDA(dst, b, h) do { _Pragma("unroll") for (int m = 0; m < 4; ++m) _Pragma("unroll") for (int k = 0; k < 2; ++k) dst[m][k] = *(const PG8_LAS bf16x8*)(lds + PG8_SA(b, h) + aoff + m * 2048 + k * 1024); } while (0)
; #define PG8_LDB(dst, b, h) do { _Pragma("unroll") for (int n = 0; n < 2; ++n) _Pragma("unroll") for (int k = 0; k < 2; ++k) dst[n][k] = *(const PG8_LAS bf16x8*)(lds + PG8_SB(b, h) + boff + n * 2048 + k * 1024); } while (0)
; #define PG8_MMA(ai, bj, At, Bt) do { __builtin_amdgcn_s_setprio(1); _Pragma("unroll") for (int m = 0; m < 4; ++m) _Pragma("unroll") for (int n = 0; n < 2; ++n) _Pragma("unroll") for (int k = 0; k < 2; ++k) \
;         acc[ai][bj][m][n] = __builtin_amdgcn_mfma_f32_16x16x32_bf16(Bt[n][k], At[m][k], acc[ai][bj][m][n], 0, 0, 0); __builtin_amdgcn_s_setprio(0); } while (0)
; #define PG8_WAIT_V(n) asm volatile("s_waitcnt vmcnt(" #n ")" ::: "memory")
; #define PG8_WAIT_L(n) asm volatile("s_waitcnt lgkmcnt(" #n ")" ::: "memory")
; #define PG8_BAR __builtin_amdgcn_s_barrier()
;     ...
;             const bool last = (t == nt - 2);
;             const char* a1 = cA + (ptrdiff_t)(t + 1) * ck;
;             const char* a2 = last ? nA : cA + (ptrdiff_t)(t + 2) * ck; const char* b2 = last ? nB : cB + (ptrdiff_t)(t + 2) * ck;
;             const ptrdiff_t k3 = last ? nk : ck;
;             const char* a3 = a2 + k3; const char* b3 = b2 + k3;
;             if (last && has_next) S.a_ready(nxt);
;             if constexpr (SP2) {
;             int pei = 0; if constexpr (PEEL) { pei = __builtin_amdgcn_readfirstlane((t == 0 && ui > 0) ? 1 : 0); asm volatile("" : "+s"(pei)); }
;             const bool pe = pei != 0;
;             PG8_LDB(B0, 0, 0); PG8_LDB(B1, 0, 1); PG8_SCHED; PG8_LDA(At, 0, 0); if (!pe) { PG8_STAGE_T(PG8_SA(1, 1), a1 + hstep, voffA, AUX_A); }
;             if (!pe) { PG8_WAIT_V(8); } PG8_WAIT_L(0); PG8_BAR; PG8_MMA(0, 0, At, B0); PG8_MMA(0, 1, At, B1); PG8_BAR; PG8_SCHED;
;             PG8_LDA(At, 0, 1); PG8_STAGE_T(PG8_SB(0, 0), b2, voffB, AUX_B); PG8_STAGE_T(PG8_SB(0, 1), b2 + hstep, voffB, AUX_B); PG8_STAGE_T(PG8_SA(0, 0), a2, voffA, AUX_A);
.LBB0_1156:
	ds_read_b128 v[154:157], v149
	s_waitcnt lgkmcnt(0)
	ds_read_b128 v[158:161], v149 offset:1024
	ds_read_b128 v[162:165], v149 offset:2048
	ds_read_b128 v[166:169], v149 offset:3072
	ds_read_b128 v[170:173], v150
	ds_read_b128 v[174:177], v150 offset:1024
	ds_read_b128 v[178:181], v150 offset:2048
	ds_read_b128 v[182:185], v150 offset:3072
	s_add_u32 s26, s24, 0xfff50080
	s_addc_u32 s27, s25, -1
	s_cmp_eq_u32 s55, 40
	s_cselect_b32 s37, s5, s27
	s_cselect_b32 s36, s4, s26
	s_cselect_b32 s27, s23, s54
	s_cselect_b32 s26, s22, s53
	v_lshl_add_u64 v[144:145], s[24:25], 0, v[136:137]
	s_add_i32 m0, s39, 0xc000
	ds_read_b128 v[186:189], v151
	ds_read_b128 v[190:193], v151 offset:1024
	ds_read_b128 v[196:199], v151 offset:2048
	ds_read_b128 v[200:203], v151 offset:3072
	ds_read_b128 v[204:207], v151 offset:4096
	ds_read_b128 v[208:211], v151 offset:5120
	ds_read_b128 v[212:215], v151 offset:6144
	ds_read_b128 v[216:219], v151 offset:7168
	global_load_lds_dwordx4 v[144:145], off
	v_lshl_add_u64 v[144:145], s[24:25], 0, v[138:139]
	s_add_i32 m0, s39, 0xe000
	s_nop 0
	global_load_lds_dwordx4 v[144:145], off
	s_waitcnt vmcnt(8)
	s_waitcnt lgkmcnt(0)
	s_barrier
	s_waitcnt lgkmcnt(0)
	v_mfma_f32_16x16x32_bf16 v[124:127], v[154:157], v[186:189], v[124:127]
	v_mfma_f32_16x16x32_bf16 v[120:123], v[162:165], v[186:189], v[120:123]
	v_mfma_f32_16x16x32_bf16 v[108:111], v[154:157], v[196:199], v[108:111]
	v_mfma_f32_16x16x32_bf16 v[104:107], v[162:165], v[196:199], v[104:107]
	v_mfma_f32_16x16x32_bf16 v[92:95], v[154:157], v[204:207], v[92:95]
	v_mfma_f32_16x16x32_bf16 v[88:91], v[162:165], v[204:207], v[88:91]
	v_mfma_f32_16x16x32_bf16 v[76:79], v[154:157], v[212:215], v[76:79]
	v_mfma_f32_16x16x32_bf16 v[72:75], v[162:165], v[212:215], v[72:75]
	v_mfma_f32_16x16x32_bf16 v[124:127], v[158:161], v[190:193], v[124:127]
	v_mfma_f32_16x16x32_bf16 v[120:123], v[166:169], v[190:193], v[120:123]
	v_mfma_f32_16x16x32_bf16 v[108:111], v[158:161], v[200:203], v[108:111]
	v_mfma_f32_16x16x32_bf16 v[104:107], v[166:169], v[200:203], v[104:107]
	v_mfma_f32_16x16x32_bf16 v[92:95], v[158:161], v[208:211], v[92:95]
	v_mfma_f32_16x16x32_bf16 v[88:91], v[166:169], v[208:211], v[88:91]
	v_mfma_f32_16x16x32_bf16 v[76:79], v[158:161], v[216:219], v[76:79]
	v_mfma_f32_16x16x32_bf16 v[72:75], v[166:169], v[216:219], v[72:75]
	v_mfma_f32_16x16x32_bf16 v[116:119], v[170:173], v[186:189], v[116:119]
	v_mfma_f32_16x16x32_bf16 v[112:115], v[178:181], v[186:189], v[112:115]
	v_mfma_f32_16x16x32_bf16 v[100:103], v[170:173], v[196:199], v[100:103]
	v_mfma_f32_16x16x32_bf16 v[96:99], v[178:181], v[196:199], v[96:99]
	v_mfma_f32_16x16x32_bf16 v[84:87], v[170:173], v[204:207], v[84:87]
	v_mfma_f32_16x16x32_bf16 v[80:83], v[178:181], v[204:207], v[80:83]
	v_mfma_f32_16x16x32_bf16 v[68:71], v[170:173], v[212:215], v[68:71]
	v_mfma_f32_16x16x32_bf16 v[64:67], v[178:181], v[212:215], v[64:67]
	v_mfma_f32_16x16x32_bf16 v[116:119], v[174:177], v[190:193], v[116:119]
	v_mfma_f32_16x16x32_bf16 v[112:115], v[182:185], v[190:193], v[112:115]
	v_mfma_f32_16x16x32_bf16 v[100:103], v[174:177], v[200:203], v[100:103]
	v_mfma_f32_16x16x32_bf16 v[96:99], v[182:185], v[200:203], v[96:99]
	s_setprio 2
	s_barrier
	v_mfma_f32_16x16x32_bf16 v[84:87], v[174:177], v[208:211], v[84:87]
	v_mfma_f32_16x16x32_bf16 v[80:83], v[182:185], v[208:211], v[80:83]
	v_mfma_f32_16x16x32_bf16 v[68:71], v[174:177], v[216:219], v[68:71]
	v_mfma_f32_16x16x32_bf16 v[64:67], v[182:185], v[216:219], v[64:67]
	s_setprio 0
	s_add_i32 s56, s46, s38
	v_lshl_add_u64 v[144:145], s[26:27], 0, v[130:131]
	s_mov_b32 m0, s56
	ds_read_b128 v[186:189], v151 offset:16384
	ds_read_b128 v[190:193], v151 offset:17408
	ds_read_b128 v[196:199], v151 offset:18432
	ds_read_b128 v[200:203], v151 offset:19456
	ds_read_b128 v[204:207], v151 offset:20480
	ds_read_b128 v[208:211], v151 offset:21504
	ds_read_b128 v[212:215], v151 offset:22528
	ds_read_b128 v[216:219], v151 offset:23552
	global_load_lds_dwordx4 v[144:145], off
	s_add_i32 m0, s56, 0x2000
	s_add_u32 s56, s26, 0xb0000
	v_lshl_add_u64 v[220:221], s[26:27], 0, v[134:135]
	s_addc_u32 s57, s27, 0
	s_add_i32 s58, s47, s38
	global_load_lds_dwordx4 v[220:221], off
	v_lshl_add_u64 v[222:223], s[56:57], 0, v[130:131]
	s_mov_b32 m0, s58
	v_lshl_add_u64 v[224:225], s[36:37], 0, v[132:133]
	global_load_lds_dwordx4 v[222:223], off
	v_lshl_add_u64 v[222:223], s[56:57], 0, v[134:135]
	s_add_i32 m0, s58, 0x2000
	s_nop 0
	global_load_lds_dwordx4 v[222:223], off
	v_lshl_add_u64 v[222:223], s[36:37], 0, v[128:129]
	s_mov_b32 m0, s39
	s_nop 0
	global_load_lds_dwordx4 v[222:223], off
	s_mov_b32 m0, s40
	s_nop 0
	global_load_lds_dwordx4 v[224:225], off
	s_waitcnt vmcnt(8)
	s_waitcnt lgkmcnt(0)
	s_barrier
; #define PG8_STAGE_T(bufoff, gbase, voff, AUX) do { _Pragma("unroll") for (int _i = 0; _i < 2; ++_i) \
;         __builtin_amdgcn_global_load_lds((const unsigned*)((const char*)(gbase) + (voff)[_i]), (PG8_LAS unsigned*)(lds + (bufoff) + ldsw + _i * 8192), 16, 0, AUX); } while (0)
; #define PG8_LDA(dst, b, h) do { _Pragma("unroll") for (int m = 0; m < 4; ++m) _Pragma("unroll") for (int k = 0; k < 2; ++k) dst[m][k] = *(const PG8_LAS bf16x8*)(lds + PG8_SA(b, h) + aoff + m * 2048 + k * 1024); } while (0)
; #define PG8_LDB(dst, b, h) do { _Pragma("unroll") for (int n = 0; n < 2; ++n) _Pragma("unroll") for (int k = 0; k < 2; ++k) dst[n][k] = *(const PG8_LAS bf16x8*)(lds + PG8_SB(b, h) + boff + n * 2048 + k * 1024); } while (0)
; #define PG8_MMA(ai, bj, At, Bt) do { __builtin_amdgcn_s_setprio(1); _Pragma("unroll") for (int m = 0; m < 4; ++m) _Pragma("unroll") for (int n = 0; n < 2; ++n) _Pragma("unroll") for (int k = 0; k < 2; ++k) \
;         acc[ai][bj][m][n] = __builtin_amdgcn_mfma_f32_16x16x32_bf16(Bt[n][k], At[m][k], acc[ai][bj][m][n], 0, 0, 0); __builtin_amdgcn_s_setprio(0); } while (0)
; #define PG8_WAIT_V(n) asm volatile("s_waitcnt vmcnt(" #n ")" ::: "memory")
; #define PG8_WAIT_L(n) asm volatile("s_waitcnt lgkmcnt(" #n ")" ::: "memory")
; #define PG8_BAR __builtin_amdgcn_s_barrier()
; #define PG8_SCHED __builtin_amdgcn_sched_barrier(0)
;     ...
;             if (!pe) { PG8_WAIT_V(8); } PG8_WAIT_L(0); PG8_BAR; PG8_MMA(1, 0, At, B0); PG8_MMA(1, 1, At, B1); PG8_BAR; PG8_SCHED;
;             PG8_LDB(B0, 1, 0); PG8_LDB(B1, 1, 1); PG8_SCHED; PG8_LDA(At, 1, 0); PG8_STAGE_T(PG8_SA(0, 1), a2 + hstep, voffA, AUX_A);
;             if (!pe) { PG8_WAIT_V(8); } PG8_WAIT_L(0); PG8_BAR; PG8_MMA(0, 0, At, B0); PG8_MMA(0, 1, At, B1); PG8_BAR; PG8_SCHED;
	s_waitcnt lgkmcnt(0)
	v_mfma_f32_16x16x32_bf16 v[60:63], v[154:157], v[186:189], v[60:63]
	v_mfma_f32_16x16x32_bf16 v[56:59], v[162:165], v[186:189], v[56:59]
	v_mfma_f32_16x16x32_bf16 v[44:47], v[154:157], v[196:199], v[44:47]
	v_mfma_f32_16x16x32_bf16 v[40:43], v[162:165], v[196:199], v[40:43]
	v_mfma_f32_16x16x32_bf16 v[28:31], v[154:157], v[204:207], v[28:31]
	v_mfma_f32_16x16x32_bf16 v[24:27], v[162:165], v[204:207], v[24:27]
	v_mfma_f32_16x16x32_bf16 v[12:15], v[154:157], v[212:215], v[12:15]
	v_mfma_f32_16x16x32_bf16 v[8:11], v[162:165], v[212:215], v[8:11]
	v_mfma_f32_16x16x32_bf16 v[60:63], v[158:161], v[190:193], v[60:63]
	v_mfma_f32_16x16x32_bf16 v[56:59], v[166:169], v[190:193], v[56:59]
	v_mfma_f32_16x16x32_bf16 v[44:47], v[158:161], v[200:203], v[44:47]
	v_mfma_f32_16x16x32_bf16 v[40:43], v[166:169], v[200:203], v[40:43]
	v_mfma_f32_16x16x32_bf16 v[28:31], v[158:161], v[208:211], v[28:31]
	v_mfma_f32_16x16x32_bf16 v[24:27], v[166:169], v[208:211], v[24:27]
	v_mfma_f32_16x16x32_bf16 v[12:15], v[158:161], v[216:219], v[12:15]
	v_mfma_f32_16x16x32_bf16 v[8:11], v[166:169], v[216:219], v[8:11]
	v_mfma_f32_16x16x32_bf16 v[52:55], v[170:173], v[186:189], v[52:55]
	v_mfma_f32_16x16x32_bf16 v[48:51], v[178:181], v[186:189], v[48:51]
	v_mfma_f32_16x16x32_bf16 v[36:39], v[170:173], v[196:199], v[36:39]
	v_mfma_f32_16x16x32_bf16 v[32:35], v[178:181], v[196:199], v[32:35]
	v_mfma_f32_16x16x32_bf16 v[20:23], v[170:173], v[204:207], v[20:23]
	v_mfma_f32_16x16x32_bf16 v[16:19], v[178:181], v[204:207], v[16:19]
	v_mfma_f32_16x16x32_bf16 v[4:7], v[170:173], v[212:215], v[4:7]
	v_mfma_f32_16x16x32_bf16 v[0:3], v[178:181], v[212:215], v[0:3]
	v_mfma_f32_16x16x32_bf16 v[52:55], v[174:177], v[190:193], v[52:55]
	v_mfma_f32_16x16x32_bf16 v[48:51], v[182:185], v[190:193], v[48:51]
	v_mfma_f32_16x16x32_bf16 v[36:39], v[174:177], v[200:203], v[36:39]
	v_mfma_f32_16x16x32_bf16 v[32:35], v[182:185], v[200:203], v[32:35]
	s_setprio 2
	s_barrier
	v_mfma_f32_16x16x32_bf16 v[20:23], v[174:177], v[208:211], v[20:23]
	v_mfma_f32_16x16x32_bf16 v[16:19], v[182:185], v[208:211], v[16:19]
	v_mfma_f32_16x16x32_bf16 v[4:7], v[174:177], v[216:219], v[4:7]
	v_mfma_f32_16x16x32_bf16 v[0:3], v[182:185], v[216:219], v[0:3]
	s_setprio 0
	s_add_i32 s56, 0, 0x18000
	v_add_u32_e32 v153, s56, v147
	s_add_i32 s57, 0, 0x1c000
	ds_read_b128 v[154:157], v153
	ds_read_b128 v[158:161], v153 offset:1024
	ds_read_b128 v[162:165], v153 offset:2048
	ds_read_b128 v[166:169], v153 offset:3072
	v_add_u32_e32 v153, s57, v147
	ds_read_b128 v[170:173], v153
	ds_read_b128 v[174:177], v153 offset:1024
	ds_read_b128 v[178:181], v153 offset:2048
	ds_read_b128 v[182:185], v153 offset:3072
	s_add_u32 s36, s36, 0xb0000
	s_addc_u32 s37, s37, 0
	s_mov_b32 m0, s41
	v_lshl_add_u64 v[226:227], s[36:37], 0, v[128:129]
	ds_read_b128 v[186:189], v151 offset:32768
	ds_read_b128 v[190:193], v151 offset:33792
	ds_read_b128 v[196:199], v151 offset:34816
	ds_read_b128 v[200:203], v151 offset:35840
	ds_read_b128 v[204:207], v151 offset:36864
	ds_read_b128 v[208:211], v151 offset:37888
	ds_read_b128 v[212:215], v151 offset:38912
	ds_read_b128 v[216:219], v151 offset:39936
	global_load_lds_dwordx4 v[226:227], off
	v_lshl_add_u64 v[226:227], s[36:37], 0, v[132:133]
	s_mov_b32 m0, s42
	s_nop 0
	global_load_lds_dwordx4 v[226:227], off
	s_waitcnt vmcnt(8)
	s_waitcnt lgkmcnt(0)
	s_barrier
	s_waitcnt lgkmcnt(0)
	v_mfma_f32_16x16x32_bf16 v[124:127], v[154:157], v[186:189], v[124:127]
	v_mfma_f32_16x16x32_bf16 v[120:123], v[162:165], v[186:189], v[120:123]
	v_mfma_f32_16x16x32_bf16 v[108:111], v[154:157], v[196:199], v[108:111]
	v_mfma_f32_16x16x32_bf16 v[104:107], v[162:165], v[196:199], v[104:107]
	v_mfma_f32_16x16x32_bf16 v[92:95], v[154:157], v[204:207], v[92:95]
	v_mfma_f32_16x16x32_bf16 v[88:91], v[162:165], v[204:207], v[88:91]
	v_mfma_f32_16x16x32_bf16 v[76:79], v[154:157], v[212:215], v[76:79]
	v_mfma_f32_16x16x32_bf16 v[72:75], v[162:165], v[212:215], v[72:75]
	v_mfma_f32_16x16x32_bf16 v[124:127], v[158:161], v[190:193], v[124:127]
	v_mfma_f32_16x16x32_bf16 v[120:123], v[166:169], v[190:193], v[120:123]
	v_mfma_f32_16x16x32_bf16 v[108:111], v[158:161], v[200:203], v[108:111]
	v_mfma_f32_16x16x32_bf16 v[104:107], v[166:169], v[200:203], v[104:107]
	v_mfma_f32_16x16x32_bf16 v[92:95], v[158:161], v[208:211], v[92:95]
	v_mfma_f32_16x16x32_bf16 v[88:91], v[166:169], v[208:211], v[88:91]
	v_mfma_f32_16x16x32_bf16 v[76:79], v[158:161], v[216:219], v[76:79]
	v_mfma_f32_16x16x32_bf16 v[72:75], v[166:169], v[216:219], v[72:75]
	v_mfma_f32_16x16x32_bf16 v[116:119], v[170:173], v[186:189], v[116:119]
	v_mfma_f32_16x16x32_bf16 v[112:115], v[178:181], v[186:189], v[112:115]
	v_mfma_f32_16x16x32_bf16 v[100:103], v[170:173], v[196:199], v[100:103]
	v_mfma_f32_16x16x32_bf16 v[96:99], v[178:181], v[196:199], v[96:99]
	v_mfma_f32_16x16x32_bf16 v[84:87], v[170:173], v[204:207], v[84:87]
	v_mfma_f32_16x16x32_bf16 v[80:83], v[178:181], v[204:207], v[80:83]
	v_mfma_f32_16x16x32_bf16 v[68:71], v[170:173], v[212:215], v[68:71]
	v_mfma_f32_16x16x32_bf16 v[64:67], v[178:181], v[212:215], v[64:67]
	v_mfma_f32_16x16x32_bf16 v[116:119], v[174:177], v[190:193], v[116:119]
	v_mfma_f32_16x16x32_bf16 v[112:115], v[182:185], v[190:193], v[112:115]
	v_mfma_f32_16x16x32_bf16 v[100:103], v[174:177], v[200:203], v[100:103]
	v_mfma_f32_16x16x32_bf16 v[96:99], v[182:185], v[200:203], v[96:99]
	s_setprio 2
	s_barrier
; #define PG8_STAGE_T(bufoff, gbase, voff, AUX) do { _Pragma("unroll") for (int _i = 0; _i < 2; ++_i) \
;         __builtin_amdgcn_global_load_lds((const unsigned*)((const char*)(gbase) + (voff)[_i]), (PG8_LAS unsigned*)(lds + (bufoff) + ldsw + _i * 8192), 16, 0, AUX); } while (0)
; #define PG8_LDA(dst, b, h) do { _Pragma("unroll") for (int m = 0; m < 4; ++m) _Pragma("unroll") for (int k = 0; k < 2; ++k) dst[m][k] = *(const PG8_LAS bf16x8*)(lds + PG8_SA(b, h) + aoff + m * 2048 + k * 1024); } while (0)
; #define PG8_MMA(ai, bj, At, Bt) do { __builtin_amdgcn_s_setprio(1); _Pragma("unroll") for (int m = 0; m < 4; ++m) _Pragma("unroll") for (int n = 0; n < 2; ++n) _Pragma("unroll") for (int k = 0; k < 2; ++k) \
;         acc[ai][bj][m][n] = __builtin_amdgcn_mfma_f32_16x16x32_bf16(Bt[n][k], At[m][k], acc[ai][bj][m][n], 0, 0, 0); __builtin_amdgcn_s_setprio(0); } while (0)
; #define PG8_WAIT_V(n) asm volatile("s_waitcnt vmcnt(" #n ")" ::: "memory")
; #define PG8_WAIT_L(n) asm volatile("s_waitcnt lgkmcnt(" #n ")" ::: "memory")
; #define PG8_BAR __builtin_amdgcn_s_barrier()
; #define PG8_SCHED __builtin_amdgcn_sched_barrier(0)
;     ...
;             if (!pe) { PG8_WAIT_V(8); } PG8_WAIT_L(0); PG8_BAR; PG8_MMA(0, 0, At, B0); PG8_MMA(0, 1, At, B1); PG8_BAR; PG8_SCHED;
;             PG8_LDA(At, 1, 1); PG8_STAGE_T(PG8_SB(1, 0), b3, voffB, AUX_B); PG8_STAGE_T(PG8_SB(1, 1), b3 + hstep, voffB, AUX_B); PG8_STAGE_T(PG8_SA(1, 0), a3, voffA, AUX_A);
;             PG8_WAIT_V(8); PG8_WAIT_L(0); PG8_BAR; PG8_MMA(1, 0, At, B0); PG8_MMA(1, 1, At, B1); PG8_BAR; PG8_SCHED;
;     ...
;         if constexpr (ALIGN_EPI) { if (wr == 0) PG8_BAR; }
	v_mfma_f32_16x16x32_bf16 v[84:87], v[174:177], v[208:211], v[84:87]
	v_mfma_f32_16x16x32_bf16 v[80:83], v[182:185], v[208:211], v[80:83]
	v_mfma_f32_16x16x32_bf16 v[68:71], v[174:177], v[216:219], v[68:71]
	v_mfma_f32_16x16x32_bf16 v[64:67], v[182:185], v[216:219], v[64:67]
	s_setprio 0
	s_add_i32 s36, s56, s38
	v_lshl_add_u64 v[144:145], v[144:145], 0, s[12:13]
	s_mov_b32 m0, s36
	ds_read_b128 v[186:189], v151 offset:49152
	ds_read_b128 v[190:193], v151 offset:50176
	ds_read_b128 v[196:199], v151 offset:51200
	ds_read_b128 v[200:203], v151 offset:52224
	ds_read_b128 v[204:207], v151 offset:53248
	ds_read_b128 v[208:211], v151 offset:54272
	ds_read_b128 v[212:215], v151 offset:55296
	ds_read_b128 v[216:219], v151 offset:56320
	global_load_lds_dwordx4 v[144:145], off
	s_add_i32 m0, s36, 0x2000
	s_add_u32 s26, s26, 0xb0080
	v_lshl_add_u64 v[144:145], v[220:221], 0, s[12:13]
	s_addc_u32 s27, s27, 0
	s_add_i32 s36, s57, s38
	global_load_lds_dwordx4 v[144:145], off
	v_lshl_add_u64 v[144:145], s[26:27], 0, v[130:131]
	s_mov_b32 m0, s36
	s_nop 0
	global_load_lds_dwordx4 v[144:145], off
	v_lshl_add_u64 v[144:145], s[26:27], 0, v[134:135]
	s_add_i32 m0, s36, 0x2000
	s_nop 0
	global_load_lds_dwordx4 v[144:145], off
	v_lshl_add_u64 v[144:145], v[222:223], 0, s[12:13]
	s_mov_b32 m0, s43
	s_nop 0
	global_load_lds_dwordx4 v[144:145], off
	v_lshl_add_u64 v[144:145], v[224:225], 0, s[12:13]
	s_mov_b32 m0, s44
	s_nop 0
	global_load_lds_dwordx4 v[144:145], off
	s_waitcnt vmcnt(8)
	s_waitcnt lgkmcnt(0)
	s_barrier
	s_waitcnt lgkmcnt(0)
	v_mfma_f32_16x16x32_bf16 v[60:63], v[154:157], v[186:189], v[60:63]
	v_mfma_f32_16x16x32_bf16 v[56:59], v[162:165], v[186:189], v[56:59]
	v_mfma_f32_16x16x32_bf16 v[44:47], v[154:157], v[196:199], v[44:47]
	v_mfma_f32_16x16x32_bf16 v[40:43], v[162:165], v[196:199], v[40:43]
	v_mfma_f32_16x16x32_bf16 v[28:31], v[154:157], v[204:207], v[28:31]
	v_mfma_f32_16x16x32_bf16 v[24:27], v[162:165], v[204:207], v[24:27]
	v_mfma_f32_16x16x32_bf16 v[12:15], v[154:157], v[212:215], v[12:15]
	v_mfma_f32_16x16x32_bf16 v[8:11], v[162:165], v[212:215], v[8:11]
	v_mfma_f32_16x16x32_bf16 v[60:63], v[158:161], v[190:193], v[60:63]
	v_mfma_f32_16x16x32_bf16 v[56:59], v[166:169], v[190:193], v[56:59]
	v_mfma_f32_16x16x32_bf16 v[44:47], v[158:161], v[200:203], v[44:47]
	v_mfma_f32_16x16x32_bf16 v[40:43], v[166:169], v[200:203], v[40:43]
	v_mfma_f32_16x16x32_bf16 v[28:31], v[158:161], v[208:211], v[28:31]
	v_mfma_f32_16x16x32_bf16 v[24:27], v[166:169], v[208:211], v[24:27]
	v_mfma_f32_16x16x32_bf16 v[12:15], v[158:161], v[216:219], v[12:15]
	v_mfma_f32_16x16x32_bf16 v[8:11], v[166:169], v[216:219], v[8:11]
	v_mfma_f32_16x16x32_bf16 v[52:55], v[170:173], v[186:189], v[52:55]
	v_mfma_f32_16x16x32_bf16 v[48:51], v[178:181], v[186:189], v[48:51]
	v_mfma_f32_16x16x32_bf16 v[36:39], v[170:173], v[196:199], v[36:39]
	v_mfma_f32_16x16x32_bf16 v[32:35], v[178:181], v[196:199], v[32:35]
	v_mfma_f32_16x16x32_bf16 v[20:23], v[170:173], v[204:207], v[20:23]
	v_mfma_f32_16x16x32_bf16 v[16:19], v[178:181], v[204:207], v[16:19]
	v_mfma_f32_16x16x32_bf16 v[4:7], v[170:173], v[212:215], v[4:7]
	v_mfma_f32_16x16x32_bf16 v[0:3], v[178:181], v[212:215], v[0:3]
	v_mfma_f32_16x16x32_bf16 v[52:55], v[174:177], v[190:193], v[52:55]
	v_mfma_f32_16x16x32_bf16 v[48:51], v[182:185], v[190:193], v[48:51]
	v_mfma_f32_16x16x32_bf16 v[36:39], v[174:177], v[200:203], v[36:39]
	v_mfma_f32_16x16x32_bf16 v[32:35], v[182:185], v[200:203], v[32:35]
	s_setprio 2
	s_barrier
	v_mfma_f32_16x16x32_bf16 v[20:23], v[174:177], v[208:211], v[20:23]
	v_mfma_f32_16x16x32_bf16 v[16:19], v[182:185], v[208:211], v[16:19]
	v_mfma_f32_16x16x32_bf16 v[4:7], v[174:177], v[216:219], v[4:7]
	v_mfma_f32_16x16x32_bf16 v[0:3], v[182:185], v[216:219], v[0:3]
	s_setprio 0
	s_add_i32 s55, s55, 2
	s_add_u32 s24, s24, 0x100
	s_addc_u32 s25, s25, 0
	s_add_u32 s53, s53, 0x100
	s_addc_u32 s54, s54, 0
	s_cmp_gt_u32 s55, 41
	s_cbranch_scc0 .LBB0_1156
	s_and_b64 vcc, exec, s[14:15]
	s_cbranch_vccz .LBB0_1159
	s_barrier

; #define PG8_STAGE_T(bufoff, gbase, voff, AUX) do { _Pragma("unroll") for (int _i = 0; _i < 2; ++_i) \
;         __builtin_amdgcn_global_load_lds((const unsigned*)((const char*)(gbase) + (voff)[_i]), (PG8_LAS unsigned*)(lds + (bufoff) + ldsw + _i * 8192), 16, 0, AUX); } while (0)
; #define PG8_LDA(dst, b, h) do { _Pragma("unroll") for (int m = 0; m < 4; ++m) _Pragma("unroll") for (int k = 0; k < 2; ++k) dst[m][k] = *(const PG8_LAS bf16x8*)(lds + PG8_SA(b, h) + aoff + m * 2048 + k * 1024); } while (0)
; #define PG8_LDB(dst, b, h) do { _Pragma("unroll") for (int n = 0; n < 2; ++n) _Pragma("unroll") for (int k = 0; k < 2; ++k) dst[n][k] = *(const PG8_LAS bf16x8*)(lds + PG8_SB(b, h) + boff + n * 2048 + k * 1024); } while (0)
; #define PG8_MMA(ai, bj, At, Bt) do { __builtin_amdgcn_s_setprio(1); _Pragma("unroll") for (int m = 0; m < 4; ++m) _Pragma("unroll") for (int n = 0; n < 2; ++n) _Pragma("unroll") for (int k = 0; k < 2; ++k) \
;         acc[ai][bj][m][n] = __builtin_amdgcn_mfma_f32_16x16x32_bf16(Bt[n][k], At[m][k], acc[ai][bj][m][n], 0, 0, 0); __builtin_amdgcn_s_setprio(0); } while (0)
; #define PG8_WAIT_V(n) asm volatile("s_waitcnt vmcnt(" #n ")" ::: "memory")
; #define PG8_WAIT_L(n) asm volatile("s_waitcnt lgkmcnt(" #n ")" ::: "memory")
; #define PG8_BAR __builtin_amdgcn_s_barrier()
;     ...
;             const bool last = (t == nt - 2);
;             const char* a1 = cA + (ptrdiff_t)(t + 1) * ck;
;             const char* a2 = last ? nA : cA + (ptrdiff_t)(t + 2) * ck; const char* b2 = last ? nB : cB + (ptrdiff_t)(t + 2) * ck;
;             const ptrdiff_t k3 = last ? nk : ck;
;             const char* a3 = a2 + k3; const char* b3 = b2 + k3;
;             if (last && has_next) S.a_ready(nxt);
;             if constexpr (SP2) {
;             int pei = 0; if constexpr (PEEL) { pei = __builtin_amdgcn_readfirstlane((t == 0 && ui > 0) ? 1 : 0); asm volatile("" : "+s"(pei)); }
;             const bool pe = pei != 0;
;             PG8_LDB(B0, 0, 0); PG8_LDB(B1, 0, 1); PG8_SCHED; PG8_LDA(At, 0, 0); if (!pe) { PG8_STAGE_T(PG8_SA(1, 1), a1 + hstep, voffA, AUX_A); }
;             if (!pe) { PG8_WAIT_V(8); } PG8_WAIT_L(0); PG8_BAR; PG8_MMA(0, 0, At, B0); PG8_MMA(0, 1, At, B1); PG8_BAR; PG8_SCHED;
;             PG8_LDA(At, 0, 1); PG8_STAGE_T(PG8_SB(0, 0), b2, voffB, AUX_B); PG8_STAGE_T(PG8_SB(0, 1), b2 + hstep, voffB, AUX_B); PG8_STAGE_T(PG8_SA(0, 0), a2, voffA, AUX_A);
.LBB0_1353:
	ds_read_b128 v[144:147], v162
	ds_read_b128 v[148:151], v162 offset:1024
	ds_read_b128 v[152:155], v162 offset:2048
	ds_read_b128 v[166:169], v162 offset:3072
	ds_read_b128 v[170:173], v163
	ds_read_b128 v[174:177], v163 offset:1024
	ds_read_b128 v[178:181], v163 offset:2048
	ds_read_b128 v[182:185], v163 offset:3072
	s_add_u32 s44, s42, 0xfffc0080
	s_addc_u32 s45, s43, -1
	s_cmp_eq_u32 s70, 12
	s_cselect_b32 s47, s25, s45
	s_cselect_b32 s46, s41, s44
	s_cselect_b32 s45, s27, s69
	s_cselect_b32 s44, s67, s68
	v_lshl_add_u64 v[156:157], s[42:43], 0, v[136:137]
	s_add_i32 m0, s50, 0xc000
	ds_read_b128 v[186:189], v164
	ds_read_b128 v[190:193], v164 offset:1024
	ds_read_b128 v[196:199], v164 offset:2048
	ds_read_b128 v[200:203], v164 offset:3072
	ds_read_b128 v[204:207], v164 offset:4096
	ds_read_b128 v[208:211], v164 offset:5120
	ds_read_b128 v[212:215], v164 offset:6144
	ds_read_b128 v[216:219], v164 offset:7168
	global_load_lds_dwordx4 v[156:157], off
	v_lshl_add_u64 v[156:157], s[42:43], 0, v[138:139]
	s_add_i32 m0, s50, 0xe000
	s_nop 0
	global_load_lds_dwordx4 v[156:157], off
	s_waitcnt vmcnt(8)
	s_waitcnt lgkmcnt(0)
	s_barrier
	s_waitcnt lgkmcnt(0)
	v_mfma_f32_16x16x32_bf16 v[124:127], v[144:147], v[186:189], v[124:127]
	v_mfma_f32_16x16x32_bf16 v[120:123], v[152:155], v[186:189], v[120:123]
	v_mfma_f32_16x16x32_bf16 v[108:111], v[144:147], v[196:199], v[108:111]
	v_mfma_f32_16x16x32_bf16 v[104:107], v[152:155], v[196:199], v[104:107]
	v_mfma_f32_16x16x32_bf16 v[92:95], v[144:147], v[204:207], v[92:95]
	v_mfma_f32_16x16x32_bf16 v[88:91], v[152:155], v[204:207], v[88:91]
	v_mfma_f32_16x16x32_bf16 v[76:79], v[144:147], v[212:215], v[76:79]
	v_mfma_f32_16x16x32_bf16 v[72:75], v[152:155], v[212:215], v[72:75]
	v_mfma_f32_16x16x32_bf16 v[124:127], v[148:151], v[190:193], v[124:127]
	v_mfma_f32_16x16x32_bf16 v[120:123], v[166:169], v[190:193], v[120:123]
	v_mfma_f32_16x16x32_bf16 v[108:111], v[148:151], v[200:203], v[108:111]
	v_mfma_f32_16x16x32_bf16 v[104:107], v[166:169], v[200:203], v[104:107]
	v_mfma_f32_16x16x32_bf16 v[92:95], v[148:151], v[208:211], v[92:95]
	v_mfma_f32_16x16x32_bf16 v[88:91], v[166:169], v[208:211], v[88:91]
	v_mfma_f32_16x16x32_bf16 v[76:79], v[148:151], v[216:219], v[76:79]
	v_mfma_f32_16x16x32_bf16 v[72:75], v[166:169], v[216:219], v[72:75]
	v_mfma_f32_16x16x32_bf16 v[116:119], v[170:173], v[186:189], v[116:119]
	v_mfma_f32_16x16x32_bf16 v[112:115], v[178:181], v[186:189], v[112:115]
	v_mfma_f32_16x16x32_bf16 v[100:103], v[170:173], v[196:199], v[100:103]
	v_mfma_f32_16x16x32_bf16 v[96:99], v[178:181], v[196:199], v[96:99]
	v_mfma_f32_16x16x32_bf16 v[84:87], v[170:173], v[204:207], v[84:87]
	v_mfma_f32_16x16x32_bf16 v[80:83], v[178:181], v[204:207], v[80:83]
	v_mfma_f32_16x16x32_bf16 v[68:71], v[170:173], v[212:215], v[68:71]
	v_mfma_f32_16x16x32_bf16 v[64:67], v[178:181], v[212:215], v[64:67]
	v_mfma_f32_16x16x32_bf16 v[116:119], v[174:177], v[190:193], v[116:119]
	v_mfma_f32_16x16x32_bf16 v[112:115], v[182:185], v[190:193], v[112:115]
	v_mfma_f32_16x16x32_bf16 v[100:103], v[174:177], v[200:203], v[100:103]
	v_mfma_f32_16x16x32_bf16 v[96:99], v[182:185], v[200:203], v[96:99]
	s_setprio 2
	s_barrier
	v_mfma_f32_16x16x32_bf16 v[84:87], v[174:177], v[208:211], v[84:87]
	v_mfma_f32_16x16x32_bf16 v[80:83], v[182:185], v[208:211], v[80:83]
	v_mfma_f32_16x16x32_bf16 v[68:71], v[174:177], v[216:219], v[68:71]
	v_mfma_f32_16x16x32_bf16 v[64:67], v[182:185], v[216:219], v[64:67]
	s_setprio 0
	s_add_i32 s71, s57, s49
	v_lshl_add_u64 v[156:157], s[44:45], 0, v[130:131]
	s_mov_b32 m0, s71
	ds_read_b128 v[186:189], v164 offset:16384
	ds_read_b128 v[190:193], v164 offset:17408
	ds_read_b128 v[196:199], v164 offset:18432
	ds_read_b128 v[200:203], v164 offset:19456
	ds_read_b128 v[204:207], v164 offset:20480
	ds_read_b128 v[208:211], v164 offset:21504
	ds_read_b128 v[212:215], v164 offset:22528
	ds_read_b128 v[216:219], v164 offset:23552
	global_load_lds_dwordx4 v[156:157], off
	s_add_i32 m0, s71, 0x2000
	s_add_u32 s76, s44, 0x40000
	v_lshl_add_u64 v[220:221], s[44:45], 0, v[134:135]
	s_addc_u32 s77, s45, 0
	s_add_i32 s71, s58, s49
	global_load_lds_dwordx4 v[220:221], off
	v_lshl_add_u64 v[222:223], s[76:77], 0, v[130:131]
	s_mov_b32 m0, s71
	v_lshl_add_u64 v[224:225], s[46:47], 0, v[132:133]
	global_load_lds_dwordx4 v[222:223], off
	v_lshl_add_u64 v[222:223], s[76:77], 0, v[134:135]
	s_add_i32 m0, s71, 0x2000
	s_nop 0
	global_load_lds_dwordx4 v[222:223], off
	v_lshl_add_u64 v[222:223], s[46:47], 0, v[128:129]
	s_mov_b32 m0, s50
	s_nop 0
	global_load_lds_dwordx4 v[222:223], off
	s_mov_b32 m0, s51
	s_nop 0
	global_load_lds_dwordx4 v[224:225], off
	s_waitcnt vmcnt(8)
	s_waitcnt lgkmcnt(0)
	s_barrier
; #define PG8_STAGE_T(bufoff, gbase, voff, AUX) do { _Pragma("unroll") for (int _i = 0; _i < 2; ++_i) \
;         __builtin_amdgcn_global_load_lds((const unsigned*)((const char*)(gbase) + (voff)[_i]), (PG8_LAS unsigned*)(lds + (bufoff) + ldsw + _i * 8192), 16, 0, AUX); } while (0)
; #define PG8_LDA(dst, b, h) do { _Pragma("unroll") for (int m = 0; m < 4; ++m) _Pragma("unroll") for (int k = 0; k < 2; ++k) dst[m][k] = *(const PG8_LAS bf16x8*)(lds + PG8_SA(b, h) + aoff + m * 2048 + k * 1024); } while (0)
; #define PG8_LDB(dst, b, h) do { _Pragma("unroll") for (int n = 0; n < 2; ++n) _Pragma("unroll") for (int k = 0; k < 2; ++k) dst[n][k] = *(const PG8_LAS bf16x8*)(lds + PG8_SB(b, h) + boff + n * 2048 + k * 1024); } while (0)
; #define PG8_MMA(ai, bj, At, Bt) do { __builtin_amdgcn_s_setprio(1); _Pragma("unroll") for (int m = 0; m < 4; ++m) _Pragma("unroll") for (int n = 0; n < 2; ++n) _Pragma("unroll") for (int k = 0; k < 2; ++k) \
;         acc[ai][bj][m][n] = __builtin_amdgcn_mfma_f32_16x16x32_bf16(Bt[n][k], At[m][k], acc[ai][bj][m][n], 0, 0, 0); __builtin_amdgcn_s_setprio(0); } while (0)
; #define PG8_WAIT_V(n) asm volatile("s_waitcnt vmcnt(" #n ")" ::: "memory")
; #define PG8_WAIT_L(n) asm volatile("s_waitcnt lgkmcnt(" #n ")" ::: "memory")
; #define PG8_BAR __builtin_amdgcn_s_barrier()
; #define PG8_SCHED __builtin_amdgcn_sched_barrier(0)
;     ...
;             if (!pe) { PG8_WAIT_V(8); } PG8_WAIT_L(0); PG8_BAR; PG8_MMA(1, 0, At, B0); PG8_MMA(1, 1, At, B1); PG8_BAR; PG8_SCHED;
;             PG8_LDB(B0, 1, 0); PG8_LDB(B1, 1, 1); PG8_SCHED; PG8_LDA(At, 1, 0); PG8_STAGE_T(PG8_SA(0, 1), a2 + hstep, voffA, AUX_A);
;             if (!pe) { PG8_WAIT_V(8); } PG8_WAIT_L(0); PG8_BAR; PG8_MMA(0, 0, At, B0); PG8_MMA(0, 1, At, B1); PG8_BAR; PG8_SCHED;
	s_waitcnt lgkmcnt(0)
	v_mfma_f32_16x16x32_bf16 v[60:63], v[144:147], v[186:189], v[60:63]
	v_mfma_f32_16x16x32_bf16 v[56:59], v[152:155], v[186:189], v[56:59]
	v_mfma_f32_16x16x32_bf16 v[44:47], v[144:147], v[196:199], v[44:47]
	v_mfma_f32_16x16x32_bf16 v[40:43], v[152:155], v[196:199], v[40:43]
	v_mfma_f32_16x16x32_bf16 v[28:31], v[144:147], v[204:207], v[28:31]
	v_mfma_f32_16x16x32_bf16 v[24:27], v[152:155], v[204:207], v[24:27]
	v_mfma_f32_16x16x32_bf16 v[12:15], v[144:147], v[212:215], v[12:15]
	v_mfma_f32_16x16x32_bf16 v[8:11], v[152:155], v[212:215], v[8:11]
	v_mfma_f32_16x16x32_bf16 v[60:63], v[148:151], v[190:193], v[60:63]
	v_mfma_f32_16x16x32_bf16 v[56:59], v[166:169], v[190:193], v[56:59]
	v_mfma_f32_16x16x32_bf16 v[44:47], v[148:151], v[200:203], v[44:47]
	v_mfma_f32_16x16x32_bf16 v[40:43], v[166:169], v[200:203], v[40:43]
	v_mfma_f32_16x16x32_bf16 v[28:31], v[148:151], v[208:211], v[28:31]
	v_mfma_f32_16x16x32_bf16 v[24:27], v[166:169], v[208:211], v[24:27]
	v_mfma_f32_16x16x32_bf16 v[12:15], v[148:151], v[216:219], v[12:15]
	v_mfma_f32_16x16x32_bf16 v[8:11], v[166:169], v[216:219], v[8:11]
	v_mfma_f32_16x16x32_bf16 v[52:55], v[170:173], v[186:189], v[52:55]
	v_mfma_f32_16x16x32_bf16 v[48:51], v[178:181], v[186:189], v[48:51]
	v_mfma_f32_16x16x32_bf16 v[36:39], v[170:173], v[196:199], v[36:39]
	v_mfma_f32_16x16x32_bf16 v[32:35], v[178:181], v[196:199], v[32:35]
	v_mfma_f32_16x16x32_bf16 v[20:23], v[170:173], v[204:207], v[20:23]
	v_mfma_f32_16x16x32_bf16 v[16:19], v[178:181], v[204:207], v[16:19]
	v_mfma_f32_16x16x32_bf16 v[4:7], v[170:173], v[212:215], v[4:7]
	v_mfma_f32_16x16x32_bf16 v[0:3], v[178:181], v[212:215], v[0:3]
	v_mfma_f32_16x16x32_bf16 v[52:55], v[174:177], v[190:193], v[52:55]
	v_mfma_f32_16x16x32_bf16 v[48:51], v[182:185], v[190:193], v[48:51]
	v_mfma_f32_16x16x32_bf16 v[36:39], v[174:177], v[200:203], v[36:39]
	v_mfma_f32_16x16x32_bf16 v[32:35], v[182:185], v[200:203], v[32:35]
	s_setprio 2
	s_barrier
	v_mfma_f32_16x16x32_bf16 v[20:23], v[174:177], v[208:211], v[20:23]
	v_mfma_f32_16x16x32_bf16 v[16:19], v[182:185], v[208:211], v[16:19]
	v_mfma_f32_16x16x32_bf16 v[4:7], v[174:177], v[216:219], v[4:7]
	v_mfma_f32_16x16x32_bf16 v[0:3], v[182:185], v[216:219], v[0:3]
	s_setprio 0
	s_add_i32 s71, 0, 0x18000
	v_add_u32_e32 v165, s71, v159
	s_add_i32 s76, 0, 0x1c000
	ds_read_b128 v[144:147], v165
	ds_read_b128 v[148:151], v165 offset:1024
	ds_read_b128 v[152:155], v165 offset:2048
	ds_read_b128 v[166:169], v165 offset:3072
	v_add_u32_e32 v165, s76, v159
	ds_read_b128 v[170:173], v165
	ds_read_b128 v[174:177], v165 offset:1024
	ds_read_b128 v[178:181], v165 offset:2048
	ds_read_b128 v[182:185], v165 offset:3072
	s_add_u32 s46, s46, 0x40000
	s_addc_u32 s47, s47, 0
	s_mov_b32 m0, s52
	v_lshl_add_u64 v[226:227], s[46:47], 0, v[128:129]
	ds_read_b128 v[186:189], v164 offset:32768
	ds_read_b128 v[190:193], v164 offset:33792
	ds_read_b128 v[196:199], v164 offset:34816
	ds_read_b128 v[200:203], v164 offset:35840
	ds_read_b128 v[204:207], v164 offset:36864
	ds_read_b128 v[208:211], v164 offset:37888
	ds_read_b128 v[212:215], v164 offset:38912
	ds_read_b128 v[216:219], v164 offset:39936
	global_load_lds_dwordx4 v[226:227], off
	v_lshl_add_u64 v[226:227], s[46:47], 0, v[132:133]
	s_mov_b32 m0, s53
	s_nop 0
	global_load_lds_dwordx4 v[226:227], off
	s_waitcnt vmcnt(8)
	s_waitcnt lgkmcnt(0)
	s_barrier
	s_waitcnt lgkmcnt(0)
	v_mfma_f32_16x16x32_bf16 v[124:127], v[144:147], v[186:189], v[124:127]
	v_mfma_f32_16x16x32_bf16 v[120:123], v[152:155], v[186:189], v[120:123]
	v_mfma_f32_16x16x32_bf16 v[108:111], v[144:147], v[196:199], v[108:111]
	v_mfma_f32_16x16x32_bf16 v[104:107], v[152:155], v[196:199], v[104:107]
	v_mfma_f32_16x16x32_bf16 v[92:95], v[144:147], v[204:207], v[92:95]
	v_mfma_f32_16x16x32_bf16 v[88:91], v[152:155], v[204:207], v[88:91]
	v_mfma_f32_16x16x32_bf16 v[76:79], v[144:147], v[212:215], v[76:79]
	v_mfma_f32_16x16x32_bf16 v[72:75], v[152:155], v[212:215], v[72:75]
	v_mfma_f32_16x16x32_bf16 v[124:127], v[148:151], v[190:193], v[124:127]
	v_mfma_f32_16x16x32_bf16 v[120:123], v[166:169], v[190:193], v[120:123]
	v_mfma_f32_16x16x32_bf16 v[108:111], v[148:151], v[200:203], v[108:111]
	v_mfma_f32_16x16x32_bf16 v[104:107], v[166:169], v[200:203], v[104:107]
	v_mfma_f32_16x16x32_bf16 v[92:95], v[148:151], v[208:211], v[92:95]
	v_mfma_f32_16x16x32_bf16 v[88:91], v[166:169], v[208:211], v[88:91]
	v_mfma_f32_16x16x32_bf16 v[76:79], v[148:151], v[216:219], v[76:79]
	v_mfma_f32_16x16x32_bf16 v[72:75], v[166:169], v[216:219], v[72:75]
	v_mfma_f32_16x16x32_bf16 v[116:119], v[170:173], v[186:189], v[116:119]
	v_mfma_f32_16x16x32_bf16 v[112:115], v[178:181], v[186:189], v[112:115]
	v_mfma_f32_16x16x32_bf16 v[100:103], v[170:173], v[196:199], v[100:103]
	v_mfma_f32_16x16x32_bf16 v[96:99], v[178:181], v[196:199], v[96:99]
	v_mfma_f32_16x16x32_bf16 v[84:87], v[170:173], v[204:207], v[84:87]
	v_mfma_f32_16x16x32_bf16 v[80:83], v[178:181], v[204:207], v[80:83]
	v_mfma_f32_16x16x32_bf16 v[68:71], v[170:173], v[212:215], v[68:71]
	v_mfma_f32_16x16x32_bf16 v[64:67], v[178:181], v[212:215], v[64:67]
	v_mfma_f32_16x16x32_bf16 v[116:119], v[174:177], v[190:193], v[116:119]
	v_mfma_f32_16x16x32_bf16 v[112:115], v[182:185], v[190:193], v[112:115]
	v_mfma_f32_16x16x32_bf16 v[100:103], v[174:177], v[200:203], v[100:103]
	v_mfma_f32_16x16x32_bf16 v[96:99], v[182:185], v[200:203], v[96:99]
	s_setprio 2
	s_barrier
; #define PG8_STAGE_T(bufoff, gbase, voff, AUX) do { _Pragma("unroll") for (int _i = 0; _i < 2; ++_i) \
;         __builtin_amdgcn_global_load_lds((const unsigned*)((const char*)(gbase) + (voff)[_i]), (PG8_LAS unsigned*)(lds + (bufoff) + ldsw + _i * 8192), 16, 0, AUX); } while (0)
; #define PG8_LDA(dst, b, h) do { _Pragma("unroll") for (int m = 0; m < 4; ++m) _Pragma("unroll") for (int k = 0; k < 2; ++k) dst[m][k] = *(const PG8_LAS bf16x8*)(lds + PG8_SA(b, h) + aoff + m * 2048 + k * 1024); } while (0)
; #define PG8_MMA(ai, bj, At, Bt) do { __builtin_amdgcn_s_setprio(1); _Pragma("unroll") for (int m = 0; m < 4; ++m) _Pragma("unroll") for (int n = 0; n < 2; ++n) _Pragma("unroll") for (int k = 0; k < 2; ++k) \
;         acc[ai][bj][m][n] = __builtin_amdgcn_mfma_f32_16x16x32_bf16(Bt[n][k], At[m][k], acc[ai][bj][m][n], 0, 0, 0); __builtin_amdgcn_s_setprio(0); } while (0)
; #define PG8_WAIT_V(n) asm volatile("s_waitcnt vmcnt(" #n ")" ::: "memory")
; #define PG8_WAIT_L(n) asm volatile("s_waitcnt lgkmcnt(" #n ")" ::: "memory")
; #define PG8_BAR __builtin_amdgcn_s_barrier()
; #define PG8_SCHED __builtin_amdgcn_sched_barrier(0)
;     ...
;             if (!pe) { PG8_WAIT_V(8); } PG8_WAIT_L(0); PG8_BAR; PG8_MMA(0, 0, At, B0); PG8_MMA(0, 1, At, B1); PG8_BAR; PG8_SCHED;
;             PG8_LDA(At, 1, 1); PG8_STAGE_T(PG8_SB(1, 0), b3, voffB, AUX_B); PG8_STAGE_T(PG8_SB(1, 1), b3 + hstep, voffB, AUX_B); PG8_STAGE_T(PG8_SA(1, 0), a3, voffA, AUX_A);
;             PG8_WAIT_V(8); PG8_WAIT_L(0); PG8_BAR; PG8_MMA(1, 0, At, B0); PG8_MMA(1, 1, At, B1); PG8_BAR; PG8_SCHED;
;     ...
;         if constexpr (ALIGN_EPI) { if (wr == 0) PG8_BAR; }
	v_mfma_f32_16x16x32_bf16 v[84:87], v[174:177], v[208:211], v[84:87]
	v_mfma_f32_16x16x32_bf16 v[80:83], v[182:185], v[208:211], v[80:83]
	v_mfma_f32_16x16x32_bf16 v[68:71], v[174:177], v[216:219], v[68:71]
	v_mfma_f32_16x16x32_bf16 v[64:67], v[182:185], v[216:219], v[64:67]
	s_setprio 0
	s_add_i32 s46, s71, s49
	v_lshl_add_u64 v[156:157], v[156:157], 0, s[8:9]
	s_mov_b32 m0, s46
	ds_read_b128 v[186:189], v164 offset:49152
	ds_read_b128 v[190:193], v164 offset:50176
	ds_read_b128 v[196:199], v164 offset:51200
	ds_read_b128 v[200:203], v164 offset:52224
	ds_read_b128 v[204:207], v164 offset:53248
	ds_read_b128 v[208:211], v164 offset:54272
	ds_read_b128 v[212:215], v164 offset:55296
	ds_read_b128 v[216:219], v164 offset:56320
	global_load_lds_dwordx4 v[156:157], off
	s_add_i32 m0, s46, 0x2000
	s_add_u32 s44, s44, 0x40080
	v_lshl_add_u64 v[156:157], v[220:221], 0, s[8:9]
	s_addc_u32 s45, s45, 0
	s_add_i32 s46, s76, s49
	global_load_lds_dwordx4 v[156:157], off
	v_lshl_add_u64 v[156:157], s[44:45], 0, v[130:131]
	s_mov_b32 m0, s46
	s_nop 0
	global_load_lds_dwordx4 v[156:157], off
	v_lshl_add_u64 v[156:157], s[44:45], 0, v[134:135]
	s_add_i32 m0, s46, 0x2000
	s_nop 0
	global_load_lds_dwordx4 v[156:157], off
	v_lshl_add_u64 v[156:157], v[222:223], 0, s[8:9]
	s_mov_b32 m0, s55
	s_nop 0
	global_load_lds_dwordx4 v[156:157], off
	v_lshl_add_u64 v[156:157], v[224:225], 0, s[8:9]
	s_mov_b32 m0, s56
	s_nop 0
	global_load_lds_dwordx4 v[156:157], off
	s_waitcnt vmcnt(8)
	s_waitcnt lgkmcnt(0)
	s_barrier
	s_waitcnt lgkmcnt(0)
	v_mfma_f32_16x16x32_bf16 v[60:63], v[144:147], v[186:189], v[60:63]
	v_mfma_f32_16x16x32_bf16 v[56:59], v[152:155], v[186:189], v[56:59]
	v_mfma_f32_16x16x32_bf16 v[44:47], v[144:147], v[196:199], v[44:47]
	v_mfma_f32_16x16x32_bf16 v[40:43], v[152:155], v[196:199], v[40:43]
	v_mfma_f32_16x16x32_bf16 v[28:31], v[144:147], v[204:207], v[28:31]
	v_mfma_f32_16x16x32_bf16 v[24:27], v[152:155], v[204:207], v[24:27]
	v_mfma_f32_16x16x32_bf16 v[12:15], v[144:147], v[212:215], v[12:15]
	v_mfma_f32_16x16x32_bf16 v[8:11], v[152:155], v[212:215], v[8:11]
	v_mfma_f32_16x16x32_bf16 v[60:63], v[148:151], v[190:193], v[60:63]
	v_mfma_f32_16x16x32_bf16 v[56:59], v[166:169], v[190:193], v[56:59]
	v_mfma_f32_16x16x32_bf16 v[44:47], v[148:151], v[200:203], v[44:47]
	v_mfma_f32_16x16x32_bf16 v[40:43], v[166:169], v[200:203], v[40:43]
	v_mfma_f32_16x16x32_bf16 v[28:31], v[148:151], v[208:211], v[28:31]
	v_mfma_f32_16x16x32_bf16 v[24:27], v[166:169], v[208:211], v[24:27]
	v_mfma_f32_16x16x32_bf16 v[12:15], v[148:151], v[216:219], v[12:15]
	v_mfma_f32_16x16x32_bf16 v[8:11], v[166:169], v[216:219], v[8:11]
	v_mfma_f32_16x16x32_bf16 v[52:55], v[170:173], v[186:189], v[52:55]
	v_mfma_f32_16x16x32_bf16 v[48:51], v[178:181], v[186:189], v[48:51]
	v_mfma_f32_16x16x32_bf16 v[36:39], v[170:173], v[196:199], v[36:39]
	v_mfma_f32_16x16x32_bf16 v[32:35], v[178:181], v[196:199], v[32:35]
	v_mfma_f32_16x16x32_bf16 v[20:23], v[170:173], v[204:207], v[20:23]
	v_mfma_f32_16x16x32_bf16 v[16:19], v[178:181], v[204:207], v[16:19]
	v_mfma_f32_16x16x32_bf16 v[4:7], v[170:173], v[212:215], v[4:7]
	v_mfma_f32_16x16x32_bf16 v[0:3], v[178:181], v[212:215], v[0:3]
	v_mfma_f32_16x16x32_bf16 v[52:55], v[174:177], v[190:193], v[52:55]
	v_mfma_f32_16x16x32_bf16 v[48:51], v[182:185], v[190:193], v[48:51]
	v_mfma_f32_16x16x32_bf16 v[36:39], v[174:177], v[200:203], v[36:39]
	v_mfma_f32_16x16x32_bf16 v[32:35], v[182:185], v[200:203], v[32:35]
	s_setprio 2
	s_barrier
	v_mfma_f32_16x16x32_bf16 v[20:23], v[174:177], v[208:211], v[20:23]
	v_mfma_f32_16x16x32_bf16 v[16:19], v[182:185], v[208:211], v[16:19]
	v_mfma_f32_16x16x32_bf16 v[4:7], v[174:177], v[216:219], v[4:7]
	v_mfma_f32_16x16x32_bf16 v[0:3], v[182:185], v[216:219], v[0:3]
	s_setprio 0
	s_add_i32 s70, s70, 2
	s_add_u32 s42, s42, 0x100
	s_addc_u32 s43, s43, 0
	s_add_u32 s68, s68, 0x100
	s_addc_u32 s69, s69, 0
	s_cmp_gt_u32 s70, 13
	s_cbranch_scc0 .LBB0_1353
	s_and_b64 vcc, exec, s[10:11]
	s_cbranch_vccz .LBB0_1356
	s_barrier

; #define PG8_STAGE_T(bufoff, gbase, voff, AUX) do { _Pragma("unroll") for (int _i = 0; _i < 2; ++_i) \
;         __builtin_amdgcn_global_load_lds((const unsigned*)((const char*)(gbase) + (voff)[_i]), (PG8_LAS unsigned*)(lds + (bufoff) + ldsw + _i * 8192), 16, 0, AUX); } while (0)
; #define PG8_LDA(dst, b, h) do { _Pragma("unroll") for (int m = 0; m < 4; ++m) _Pragma("unroll") for (int k = 0; k < 2; ++k) dst[m][k] = *(const PG8_LAS bf16x8*)(lds + PG8_SA(b, h) + aoff + m * 2048 + k * 1024); } while (0)
; #define PG8_LDB(dst, b, h) do { _Pragma("unroll") for (int n = 0; n < 2; ++n) _Pragma("unroll") for (int k = 0; k < 2; ++k) dst[n][k] = *(const PG8_LAS bf16x8*)(lds + PG8_SB(b, h) + boff + n * 2048 + k * 1024); } while (0)
; #define PG8_MMA(ai, bj, At, Bt) do { __builtin_amdgcn_s_setprio(1); _Pragma("unroll") for (int m = 0; m < 4; ++m) _Pragma("unroll") for (int n = 0; n < 2; ++n) _Pragma("unroll") for (int k = 0; k < 2; ++k) \
;         acc[ai][bj][m][n] = __builtin_amdgcn_mfma_f32_16x16x32_bf16(Bt[n][k], At[m][k], acc[ai][bj][m][n], 0, 0, 0); __builtin_amdgcn_s_setprio(0); } while (0)
; #define PG8_WAIT_V(n) asm volatile("s_waitcnt vmcnt(" #n ")" ::: "memory")
; #define PG8_WAIT_L(n) asm volatile("s_waitcnt lgkmcnt(" #n ")" ::: "memory")
; #define PG8_BAR __builtin_amdgcn_s_barrier()
;     ...
;             const bool last = (t == nt - 2);
;             const char* a1 = cA + (ptrdiff_t)(t + 1) * ck;
;             const char* a2 = last ? nA : cA + (ptrdiff_t)(t + 2) * ck; const char* b2 = last ? nB : cB + (ptrdiff_t)(t + 2) * ck;
;             const ptrdiff_t k3 = last ? nk : ck;
;             const char* a3 = a2 + k3; const char* b3 = b2 + k3;
;             if (last && has_next) S.a_ready(nxt);
;             if constexpr (SP2) {
;             int pei = 0; if constexpr (PEEL) { pei = __builtin_amdgcn_readfirstlane((t == 0 && ui > 0) ? 1 : 0); asm volatile("" : "+s"(pei)); }
;             const bool pe = pei != 0;
;             PG8_LDB(B0, 0, 0); PG8_LDB(B1, 0, 1); PG8_SCHED; PG8_LDA(At, 0, 0); if (!pe) { PG8_STAGE_T(PG8_SA(1, 1), a1 + hstep, voffA, AUX_A); }
;             if (!pe) { PG8_WAIT_V(8); } PG8_WAIT_L(0); PG8_BAR; PG8_MMA(0, 0, At, B0); PG8_MMA(0, 1, At, B1); PG8_BAR; PG8_SCHED;
;             PG8_LDA(At, 0, 1); PG8_STAGE_T(PG8_SB(0, 0), b2, voffB, AUX_B); PG8_STAGE_T(PG8_SB(0, 1), b2 + hstep, voffB, AUX_B); PG8_STAGE_T(PG8_SA(0, 0), a2, voffA, AUX_A);
.LBB0_1389:
	ds_read_b128 v[128:131], v173
	ds_read_b128 v[132:135], v173 offset:1024
	ds_read_b128 v[152:155], v173 offset:2048
	ds_read_b128 v[156:159], v173 offset:3072
	s_waitcnt lgkmcnt(0)
	ds_read_b128 v[160:163], v174
	ds_read_b128 v[164:167], v174 offset:1024
	ds_read_b128 v[178:181], v174 offset:2048
	ds_read_b128 v[182:185], v174 offset:3072
	s_add_i32 s61, s40, 2
	s_add_u32 s62, s38, 0x80
	s_addc_u32 s41, s39, 0
	s_cmp_eq_u32 s50, s40
	s_cselect_b32 s40, s6, s62
	s_cselect_b32 s41, s7, s41
	s_cselect_b32 s63, s37, s60
	s_cselect_b32 s62, s36, s59
	v_lshl_add_u64 v[168:169], s[38:39], 0, v[144:145]
	s_add_i32 m0, s43, 0xc000
	ds_read_b128 v[186:189], v175
	ds_read_b128 v[190:193], v175 offset:1024
	ds_read_b128 v[196:199], v175 offset:2048
	ds_read_b128 v[200:203], v175 offset:3072
	ds_read_b128 v[204:207], v175 offset:4096
	ds_read_b128 v[208:211], v175 offset:5120
	ds_read_b128 v[212:215], v175 offset:6144
	ds_read_b128 v[216:219], v175 offset:7168
	global_load_lds_dwordx4 v[168:169], off
	v_lshl_add_u64 v[168:169], s[38:39], 0, v[146:147]
	s_add_i32 m0, s43, 0xe000
	s_nop 0
	global_load_lds_dwordx4 v[168:169], off
	s_waitcnt vmcnt(8)
	s_waitcnt lgkmcnt(0)
	s_barrier
	s_waitcnt lgkmcnt(0)
	v_mfma_f32_16x16x32_bf16 v[124:127], v[128:131], v[186:189], v[124:127]
	v_mfma_f32_16x16x32_bf16 v[120:123], v[152:155], v[186:189], v[120:123]
	v_mfma_f32_16x16x32_bf16 v[108:111], v[128:131], v[196:199], v[108:111]
	v_mfma_f32_16x16x32_bf16 v[104:107], v[152:155], v[196:199], v[104:107]
	v_mfma_f32_16x16x32_bf16 v[92:95], v[128:131], v[204:207], v[92:95]
	v_mfma_f32_16x16x32_bf16 v[88:91], v[152:155], v[204:207], v[88:91]
	v_mfma_f32_16x16x32_bf16 v[76:79], v[128:131], v[212:215], v[76:79]
	v_mfma_f32_16x16x32_bf16 v[72:75], v[152:155], v[212:215], v[72:75]
	v_mfma_f32_16x16x32_bf16 v[124:127], v[132:135], v[190:193], v[124:127]
	v_mfma_f32_16x16x32_bf16 v[120:123], v[156:159], v[190:193], v[120:123]
	v_mfma_f32_16x16x32_bf16 v[108:111], v[132:135], v[200:203], v[108:111]
	v_mfma_f32_16x16x32_bf16 v[104:107], v[156:159], v[200:203], v[104:107]
	v_mfma_f32_16x16x32_bf16 v[92:95], v[132:135], v[208:211], v[92:95]
	v_mfma_f32_16x16x32_bf16 v[88:91], v[156:159], v[208:211], v[88:91]
	v_mfma_f32_16x16x32_bf16 v[76:79], v[132:135], v[216:219], v[76:79]
	v_mfma_f32_16x16x32_bf16 v[72:75], v[156:159], v[216:219], v[72:75]
	v_mfma_f32_16x16x32_bf16 v[116:119], v[160:163], v[186:189], v[116:119]
	v_mfma_f32_16x16x32_bf16 v[112:115], v[178:181], v[186:189], v[112:115]
	v_mfma_f32_16x16x32_bf16 v[100:103], v[160:163], v[196:199], v[100:103]
	v_mfma_f32_16x16x32_bf16 v[96:99], v[178:181], v[196:199], v[96:99]
	v_mfma_f32_16x16x32_bf16 v[84:87], v[160:163], v[204:207], v[84:87]
	v_mfma_f32_16x16x32_bf16 v[80:83], v[178:181], v[204:207], v[80:83]
	v_mfma_f32_16x16x32_bf16 v[68:71], v[160:163], v[212:215], v[68:71]
	v_mfma_f32_16x16x32_bf16 v[64:67], v[178:181], v[212:215], v[64:67]
	v_mfma_f32_16x16x32_bf16 v[116:119], v[164:167], v[190:193], v[116:119]
	v_mfma_f32_16x16x32_bf16 v[112:115], v[182:185], v[190:193], v[112:115]
	v_mfma_f32_16x16x32_bf16 v[100:103], v[164:167], v[200:203], v[100:103]
	v_mfma_f32_16x16x32_bf16 v[96:99], v[182:185], v[200:203], v[96:99]
	s_setprio 2
	s_barrier
	v_mfma_f32_16x16x32_bf16 v[84:87], v[164:167], v[208:211], v[84:87]
	v_mfma_f32_16x16x32_bf16 v[80:83], v[182:185], v[208:211], v[80:83]
	v_mfma_f32_16x16x32_bf16 v[68:71], v[164:167], v[216:219], v[68:71]
	v_mfma_f32_16x16x32_bf16 v[64:67], v[182:185], v[216:219], v[64:67]
	s_setprio 0
	s_add_i32 s64, s52, s42
	v_lshl_add_u64 v[168:169], s[62:63], 0, v[138:139]
	s_mov_b32 m0, s64
	ds_read_b128 v[186:189], v175 offset:16384
	ds_read_b128 v[190:193], v175 offset:17408
	ds_read_b128 v[196:199], v175 offset:18432
	ds_read_b128 v[200:203], v175 offset:19456
	ds_read_b128 v[204:207], v175 offset:20480
	ds_read_b128 v[208:211], v175 offset:21504
	ds_read_b128 v[212:215], v175 offset:22528
	ds_read_b128 v[216:219], v175 offset:23552
	global_load_lds_dwordx4 v[168:169], off
	s_add_i32 m0, s64, 0x2000
	v_lshl_add_u64 v[220:221], s[62:63], 0, v[142:143]
	s_add_u32 s62, s62, s10
	s_addc_u32 s63, s63, s11
	s_add_i32 s64, s53, s42
	global_load_lds_dwordx4 v[220:221], off
	v_lshl_add_u64 v[222:223], s[62:63], 0, v[138:139]
	s_mov_b32 m0, s64
	v_lshl_add_u64 v[224:225], s[62:63], 0, v[142:143]
	global_load_lds_dwordx4 v[222:223], off
	s_add_i32 m0, s64, 0x2000
	v_lshl_add_u64 v[226:227], s[40:41], 0, v[136:137]
	global_load_lds_dwordx4 v[224:225], off
	s_mov_b32 m0, s43
	v_lshl_add_u64 v[228:229], s[40:41], 0, v[140:141]
	global_load_lds_dwordx4 v[226:227], off
	s_mov_b32 m0, s44
	s_nop 0
	global_load_lds_dwordx4 v[228:229], off
	s_waitcnt vmcnt(8)
	s_waitcnt lgkmcnt(0)
	s_barrier
; #define PG8_STAGE_T(bufoff, gbase, voff, AUX) do { _Pragma("unroll") for (int _i = 0; _i < 2; ++_i) \
;         __builtin_amdgcn_global_load_lds((const unsigned*)((const char*)(gbase) + (voff)[_i]), (PG8_LAS unsigned*)(lds + (bufoff) + ldsw + _i * 8192), 16, 0, AUX); } while (0)
; #define PG8_LDA(dst, b, h) do { _Pragma("unroll") for (int m = 0; m < 4; ++m) _Pragma("unroll") for (int k = 0; k < 2; ++k) dst[m][k] = *(const PG8_LAS bf16x8*)(lds + PG8_SA(b, h) + aoff + m * 2048 + k * 1024); } while (0)
; #define PG8_LDB(dst, b, h) do { _Pragma("unroll") for (int n = 0; n < 2; ++n) _Pragma("unroll") for (int k = 0; k < 2; ++k) dst[n][k] = *(const PG8_LAS bf16x8*)(lds + PG8_SB(b, h) + boff + n * 2048 + k * 1024); } while (0)
; #define PG8_MMA(ai, bj, At, Bt) do { __builtin_amdgcn_s_setprio(1); _Pragma("unroll") for (int m = 0; m < 4; ++m) _Pragma("unroll") for (int n = 0; n < 2; ++n) _Pragma("unroll") for (int k = 0; k < 2; ++k) \
;         acc[ai][bj][m][n] = __builtin_amdgcn_mfma_f32_16x16x32_bf16(Bt[n][k], At[m][k], acc[ai][bj][m][n], 0, 0, 0); __builtin_amdgcn_s_setprio(0); } while (0)
; #define PG8_WAIT_V(n) asm volatile("s_waitcnt vmcnt(" #n ")" ::: "memory")
; #define PG8_WAIT_L(n) asm volatile("s_waitcnt lgkmcnt(" #n ")" ::: "memory")
; #define PG8_BAR __builtin_amdgcn_s_barrier()
; #define PG8_SCHED __builtin_amdgcn_sched_barrier(0)
;     ...
;             if (!pe) { PG8_WAIT_V(8); } PG8_WAIT_L(0); PG8_BAR; PG8_MMA(1, 0, At, B0); PG8_MMA(1, 1, At, B1); PG8_BAR; PG8_SCHED;
;             PG8_LDB(B0, 1, 0); PG8_LDB(B1, 1, 1); PG8_SCHED; PG8_LDA(At, 1, 0); PG8_STAGE_T(PG8_SA(0, 1), a2 + hstep, voffA, AUX_A);
;             if (!pe) { PG8_WAIT_V(8); } PG8_WAIT_L(0); PG8_BAR; PG8_MMA(0, 0, At, B0); PG8_MMA(0, 1, At, B1); PG8_BAR; PG8_SCHED;
	s_waitcnt lgkmcnt(0)
	v_mfma_f32_16x16x32_bf16 v[60:63], v[128:131], v[186:189], v[60:63]
	v_mfma_f32_16x16x32_bf16 v[56:59], v[152:155], v[186:189], v[56:59]
	v_mfma_f32_16x16x32_bf16 v[44:47], v[128:131], v[196:199], v[44:47]
	v_mfma_f32_16x16x32_bf16 v[40:43], v[152:155], v[196:199], v[40:43]
	v_mfma_f32_16x16x32_bf16 v[28:31], v[128:131], v[204:207], v[28:31]
	v_mfma_f32_16x16x32_bf16 v[24:27], v[152:155], v[204:207], v[24:27]
	v_mfma_f32_16x16x32_bf16 v[12:15], v[128:131], v[212:215], v[12:15]
	v_mfma_f32_16x16x32_bf16 v[8:11], v[152:155], v[212:215], v[8:11]
	v_mfma_f32_16x16x32_bf16 v[60:63], v[132:135], v[190:193], v[60:63]
	v_mfma_f32_16x16x32_bf16 v[56:59], v[156:159], v[190:193], v[56:59]
	v_mfma_f32_16x16x32_bf16 v[44:47], v[132:135], v[200:203], v[44:47]
	v_mfma_f32_16x16x32_bf16 v[40:43], v[156:159], v[200:203], v[40:43]
	v_mfma_f32_16x16x32_bf16 v[28:31], v[132:135], v[208:211], v[28:31]
	v_mfma_f32_16x16x32_bf16 v[24:27], v[156:159], v[208:211], v[24:27]
	v_mfma_f32_16x16x32_bf16 v[12:15], v[132:135], v[216:219], v[12:15]
	v_mfma_f32_16x16x32_bf16 v[8:11], v[156:159], v[216:219], v[8:11]
	v_mfma_f32_16x16x32_bf16 v[52:55], v[160:163], v[186:189], v[52:55]
	v_mfma_f32_16x16x32_bf16 v[48:51], v[178:181], v[186:189], v[48:51]
	v_mfma_f32_16x16x32_bf16 v[36:39], v[160:163], v[196:199], v[36:39]
	v_mfma_f32_16x16x32_bf16 v[32:35], v[178:181], v[196:199], v[32:35]
	v_mfma_f32_16x16x32_bf16 v[20:23], v[160:163], v[204:207], v[20:23]
	v_mfma_f32_16x16x32_bf16 v[16:19], v[178:181], v[204:207], v[16:19]
	v_mfma_f32_16x16x32_bf16 v[4:7], v[160:163], v[212:215], v[4:7]
	v_mfma_f32_16x16x32_bf16 v[0:3], v[178:181], v[212:215], v[0:3]
	v_mfma_f32_16x16x32_bf16 v[52:55], v[164:167], v[190:193], v[52:55]
	v_mfma_f32_16x16x32_bf16 v[48:51], v[182:185], v[190:193], v[48:51]
	v_mfma_f32_16x16x32_bf16 v[36:39], v[164:167], v[200:203], v[36:39]
	v_mfma_f32_16x16x32_bf16 v[32:35], v[182:185], v[200:203], v[32:35]
	s_setprio 2
	s_barrier
	v_mfma_f32_16x16x32_bf16 v[20:23], v[164:167], v[208:211], v[20:23]
	v_mfma_f32_16x16x32_bf16 v[16:19], v[182:185], v[208:211], v[16:19]
	v_mfma_f32_16x16x32_bf16 v[4:7], v[164:167], v[216:219], v[4:7]
	v_mfma_f32_16x16x32_bf16 v[0:3], v[182:185], v[216:219], v[0:3]
	s_setprio 0
	s_add_i32 s62, 0, 0x18000
	s_add_i32 s63, 0, 0x1c000
	v_add_u32_e32 v156, s62, v171
	v_add_u32_e32 v177, s63, v171
	ds_read_b128 v[128:131], v156
	ds_read_b128 v[132:135], v156 offset:1024
	ds_read_b128 v[152:155], v156 offset:2048
	ds_read_b128 v[156:159], v156 offset:3072
	ds_read_b128 v[160:163], v177
	ds_read_b128 v[164:167], v177 offset:1024
	ds_read_b128 v[178:181], v177 offset:2048
	ds_read_b128 v[182:185], v177 offset:3072
	s_add_u32 s40, s40, s10
	s_addc_u32 s41, s41, s11
	s_mov_b32 m0, s45
	v_lshl_add_u64 v[230:231], s[40:41], 0, v[136:137]
	ds_read_b128 v[186:189], v175 offset:32768
	ds_read_b128 v[190:193], v175 offset:33792
	ds_read_b128 v[196:199], v175 offset:34816
	ds_read_b128 v[200:203], v175 offset:35840
	ds_read_b128 v[204:207], v175 offset:36864
	ds_read_b128 v[208:211], v175 offset:37888
	ds_read_b128 v[212:215], v175 offset:38912
	ds_read_b128 v[216:219], v175 offset:39936
	global_load_lds_dwordx4 v[230:231], off
	v_lshl_add_u64 v[230:231], s[40:41], 0, v[140:141]
	s_mov_b32 m0, s46
	s_nop 0
	global_load_lds_dwordx4 v[230:231], off
	s_waitcnt vmcnt(8)
	s_waitcnt lgkmcnt(0)
	s_barrier
	s_waitcnt lgkmcnt(0)
	v_mfma_f32_16x16x32_bf16 v[124:127], v[128:131], v[186:189], v[124:127]
	v_mfma_f32_16x16x32_bf16 v[120:123], v[152:155], v[186:189], v[120:123]
	v_mfma_f32_16x16x32_bf16 v[108:111], v[128:131], v[196:199], v[108:111]
	v_mfma_f32_16x16x32_bf16 v[104:107], v[152:155], v[196:199], v[104:107]
	v_mfma_f32_16x16x32_bf16 v[92:95], v[128:131], v[204:207], v[92:95]
	v_mfma_f32_16x16x32_bf16 v[88:91], v[152:155], v[204:207], v[88:91]
	v_mfma_f32_16x16x32_bf16 v[76:79], v[128:131], v[212:215], v[76:79]
	v_mfma_f32_16x16x32_bf16 v[72:75], v[152:155], v[212:215], v[72:75]
	v_mfma_f32_16x16x32_bf16 v[124:127], v[132:135], v[190:193], v[124:127]
	v_mfma_f32_16x16x32_bf16 v[120:123], v[156:159], v[190:193], v[120:123]
	v_mfma_f32_16x16x32_bf16 v[108:111], v[132:135], v[200:203], v[108:111]
	v_mfma_f32_16x16x32_bf16 v[104:107], v[156:159], v[200:203], v[104:107]
	v_mfma_f32_16x16x32_bf16 v[92:95], v[132:135], v[208:211], v[92:95]
	v_mfma_f32_16x16x32_bf16 v[88:91], v[156:159], v[208:211], v[88:91]
	v_mfma_f32_16x16x32_bf16 v[76:79], v[132:135], v[216:219], v[76:79]
	v_mfma_f32_16x16x32_bf16 v[72:75], v[156:159], v[216:219], v[72:75]
	v_mfma_f32_16x16x32_bf16 v[116:119], v[160:163], v[186:189], v[116:119]
	v_mfma_f32_16x16x32_bf16 v[112:115], v[178:181], v[186:189], v[112:115]
	v_mfma_f32_16x16x32_bf16 v[100:103], v[160:163], v[196:199], v[100:103]
	v_mfma_f32_16x16x32_bf16 v[96:99], v[178:181], v[196:199], v[96:99]
	v_mfma_f32_16x16x32_bf16 v[84:87], v[160:163], v[204:207], v[84:87]
	v_mfma_f32_16x16x32_bf16 v[80:83], v[178:181], v[204:207], v[80:83]
	v_mfma_f32_16x16x32_bf16 v[68:71], v[160:163], v[212:215], v[68:71]
	v_mfma_f32_16x16x32_bf16 v[64:67], v[178:181], v[212:215], v[64:67]
	v_mfma_f32_16x16x32_bf16 v[116:119], v[164:167], v[190:193], v[116:119]
	v_mfma_f32_16x16x32_bf16 v[112:115], v[182:185], v[190:193], v[112:115]
	v_mfma_f32_16x16x32_bf16 v[100:103], v[164:167], v[200:203], v[100:103]
	v_mfma_f32_16x16x32_bf16 v[96:99], v[182:185], v[200:203], v[96:99]
	s_setprio 2
	s_barrier
; #define PG8_STAGE_T(bufoff, gbase, voff, AUX) do { _Pragma("unroll") for (int _i = 0; _i < 2; ++_i) \
;         __builtin_amdgcn_global_load_lds((const unsigned*)((const char*)(gbase) + (voff)[_i]), (PG8_LAS unsigned*)(lds + (bufoff) + ldsw + _i * 8192), 16, 0, AUX); } while (0)
; #define PG8_LDA(dst, b, h) do { _Pragma("unroll") for (int m = 0; m < 4; ++m) _Pragma("unroll") for (int k = 0; k < 2; ++k) dst[m][k] = *(const PG8_LAS bf16x8*)(lds + PG8_SA(b, h) + aoff + m * 2048 + k * 1024); } while (0)
; #define PG8_MMA(ai, bj, At, Bt) do { __builtin_amdgcn_s_setprio(1); _Pragma("unroll") for (int m = 0; m < 4; ++m) _Pragma("unroll") for (int n = 0; n < 2; ++n) _Pragma("unroll") for (int k = 0; k < 2; ++k) \
;         acc[ai][bj][m][n] = __builtin_amdgcn_mfma_f32_16x16x32_bf16(Bt[n][k], At[m][k], acc[ai][bj][m][n], 0, 0, 0); __builtin_amdgcn_s_setprio(0); } while (0)
; #define PG8_WAIT_V(n) asm volatile("s_waitcnt vmcnt(" #n ")" ::: "memory")
; #define PG8_WAIT_L(n) asm volatile("s_waitcnt lgkmcnt(" #n ")" ::: "memory")
; #define PG8_BAR __builtin_amdgcn_s_barrier()
; #define PG8_SCHED __builtin_amdgcn_sched_barrier(0)
;     ...
;             if (!pe) { PG8_WAIT_V(8); } PG8_WAIT_L(0); PG8_BAR; PG8_MMA(0, 0, At, B0); PG8_MMA(0, 1, At, B1); PG8_BAR; PG8_SCHED;
;             PG8_LDA(At, 1, 1); PG8_STAGE_T(PG8_SB(1, 0), b3, voffB, AUX_B); PG8_STAGE_T(PG8_SB(1, 1), b3 + hstep, voffB, AUX_B); PG8_STAGE_T(PG8_SA(1, 0), a3, voffA, AUX_A);
;             PG8_WAIT_V(8); PG8_WAIT_L(0); PG8_BAR; PG8_MMA(1, 0, At, B0); PG8_MMA(1, 1, At, B1); PG8_BAR; PG8_SCHED;
	v_mfma_f32_16x16x32_bf16 v[84:87], v[164:167], v[208:211], v[84:87]
	v_mfma_f32_16x16x32_bf16 v[80:83], v[182:185], v[208:211], v[80:83]
	v_mfma_f32_16x16x32_bf16 v[68:71], v[164:167], v[216:219], v[68:71]
	v_mfma_f32_16x16x32_bf16 v[64:67], v[182:185], v[216:219], v[64:67]
	s_setprio 0
	s_add_i32 s40, s62, s42
	v_lshl_add_u64 v[168:169], v[168:169], 0, s[24:25]
	s_mov_b32 m0, s40
	ds_read_b128 v[186:189], v175 offset:49152
	ds_read_b128 v[190:193], v175 offset:50176
	ds_read_b128 v[196:199], v175 offset:51200
	ds_read_b128 v[200:203], v175 offset:52224
	ds_read_b128 v[204:207], v175 offset:53248
	ds_read_b128 v[208:211], v175 offset:54272
	ds_read_b128 v[212:215], v175 offset:55296
	ds_read_b128 v[216:219], v175 offset:56320
	global_load_lds_dwordx4 v[168:169], off
	v_lshl_add_u64 v[168:169], v[220:221], 0, s[24:25]
	s_add_i32 m0, s40, 0x2000
	s_add_i32 s40, s63, s42
	global_load_lds_dwordx4 v[168:169], off
	v_lshl_add_u64 v[168:169], v[222:223], 0, s[24:25]
	s_mov_b32 m0, s40
	s_nop 0
	global_load_lds_dwordx4 v[168:169], off
	v_lshl_add_u64 v[168:169], v[224:225], 0, s[24:25]
	s_add_i32 m0, s40, 0x2000
	s_nop 0
	global_load_lds_dwordx4 v[168:169], off
	v_lshl_add_u64 v[168:169], v[226:227], 0, s[24:25]
	s_mov_b32 m0, s47
	s_nop 0
	global_load_lds_dwordx4 v[168:169], off
	v_lshl_add_u64 v[168:169], v[228:229], 0, s[24:25]
	s_mov_b32 m0, s48
	s_nop 0
	global_load_lds_dwordx4 v[168:169], off
	s_waitcnt vmcnt(8)
	s_waitcnt lgkmcnt(0)
	s_barrier
	s_waitcnt lgkmcnt(0)
	v_mfma_f32_16x16x32_bf16 v[60:63], v[128:131], v[186:189], v[60:63]
	v_mfma_f32_16x16x32_bf16 v[56:59], v[152:155], v[186:189], v[56:59]
	v_mfma_f32_16x16x32_bf16 v[44:47], v[128:131], v[196:199], v[44:47]
	v_mfma_f32_16x16x32_bf16 v[40:43], v[152:155], v[196:199], v[40:43]
	v_mfma_f32_16x16x32_bf16 v[28:31], v[128:131], v[204:207], v[28:31]
	v_mfma_f32_16x16x32_bf16 v[24:27], v[152:155], v[204:207], v[24:27]
	v_mfma_f32_16x16x32_bf16 v[12:15], v[128:131], v[212:215], v[12:15]
	v_mfma_f32_16x16x32_bf16 v[8:11], v[152:155], v[212:215], v[8:11]
	v_mfma_f32_16x16x32_bf16 v[60:63], v[132:135], v[190:193], v[60:63]
	v_mfma_f32_16x16x32_bf16 v[56:59], v[156:159], v[190:193], v[56:59]
	v_mfma_f32_16x16x32_bf16 v[44:47], v[132:135], v[200:203], v[44:47]
	v_mfma_f32_16x16x32_bf16 v[40:43], v[156:159], v[200:203], v[40:43]
	v_mfma_f32_16x16x32_bf16 v[28:31], v[132:135], v[208:211], v[28:31]
	v_mfma_f32_16x16x32_bf16 v[24:27], v[156:159], v[208:211], v[24:27]
	v_mfma_f32_16x16x32_bf16 v[12:15], v[132:135], v[216:219], v[12:15]
	v_mfma_f32_16x16x32_bf16 v[8:11], v[156:159], v[216:219], v[8:11]
	v_mfma_f32_16x16x32_bf16 v[52:55], v[160:163], v[186:189], v[52:55]
	v_mfma_f32_16x16x32_bf16 v[48:51], v[178:181], v[186:189], v[48:51]
	v_mfma_f32_16x16x32_bf16 v[36:39], v[160:163], v[196:199], v[36:39]
	v_mfma_f32_16x16x32_bf16 v[32:35], v[178:181], v[196:199], v[32:35]
	v_mfma_f32_16x16x32_bf16 v[20:23], v[160:163], v[204:207], v[20:23]
	v_mfma_f32_16x16x32_bf16 v[16:19], v[178:181], v[204:207], v[16:19]
	v_mfma_f32_16x16x32_bf16 v[4:7], v[160:163], v[212:215], v[4:7]
	v_mfma_f32_16x16x32_bf16 v[0:3], v[178:181], v[212:215], v[0:3]
	v_mfma_f32_16x16x32_bf16 v[52:55], v[164:167], v[190:193], v[52:55]
	v_mfma_f32_16x16x32_bf16 v[48:51], v[182:185], v[190:193], v[48:51]
	v_mfma_f32_16x16x32_bf16 v[36:39], v[164:167], v[200:203], v[36:39]
	v_mfma_f32_16x16x32_bf16 v[32:35], v[182:185], v[200:203], v[32:35]
	s_setprio 2
	s_barrier
	v_mfma_f32_16x16x32_bf16 v[20:23], v[164:167], v[208:211], v[20:23]
	v_mfma_f32_16x16x32_bf16 v[16:19], v[182:185], v[208:211], v[16:19]
	v_mfma_f32_16x16x32_bf16 v[4:7], v[164:167], v[216:219], v[4:7]
	v_mfma_f32_16x16x32_bf16 v[0:3], v[182:185], v[216:219], v[0:3]
	s_setprio 0
	s_add_u32 s38, s38, 0x100
	s_addc_u32 s39, s39, 0
	s_add_u32 s59, s59, 0x100
	s_addc_u32 s60, s60, 0
	s_cmp_ge_i32 s61, s49
	s_mov_b32 s40, s61
	s_cbranch_scc0 .LBB0_1389
